# v1 + all 8 per-row ss loads hoisted above the epilogue barrier in the 4 SwiGLU epilogues and the AB-in epilogue; flat->global stores there
# speedup vs baseline: 1.0046x; 1.0046x over previous
.LBB0_56:
	s_add_u32 s12, s10, 0xfffc0080
	s_addc_u32 s13, s11, -1
	s_add_i32 s48, 0, 0x10000
	s_cmp_eq_u32 s22, 12
	s_cselect_b32 s15, s20, s13
	s_cselect_b32 s14, s37, s12
	s_cselect_b32 s13, s41, s21
	s_cselect_b32 s12, s91, s96
	s_add_i32 s50, 0, 0x14000
	v_add_u32_e32 v154, s48, v147
	v_add_u32_e32 v158, s50, v147
	ds_read_b128 v[138:141], v154
	ds_read_b128 v[142:145], v154 offset:1024
	ds_read_b128 v[150:153], v154 offset:2048
	ds_read_b128 v[154:157], v154 offset:3072
	ds_read_b128 v[162:165], v158
	ds_read_b128 v[166:169], v158 offset:1024
	ds_read_b128 v[170:173], v158 offset:2048
	ds_read_b128 v[174:177], v158 offset:3072
	v_lshl_add_u64 v[158:159], s[10:11], 0, v[136:137]
	s_add_i32 m0, s30, 0xc000
	ds_read_b128 v[178:181], v149
	ds_read_b128 v[182:185], v149 offset:1024
	ds_read_b128 v[186:189], v149 offset:2048
	ds_read_b128 v[190:193], v149 offset:3072
	ds_read_b128 v[194:197], v149 offset:4096
	ds_read_b128 v[198:201], v149 offset:5120
	ds_read_b128 v[202:205], v149 offset:6144
	ds_read_b128 v[206:209], v149 offset:7168
	global_load_lds_dwordx4 v[158:159], off
	v_lshl_add_u64 v[158:159], s[10:11], 0, v[134:135]
	s_add_i32 m0, s30, 0xe000
	s_nop 0
	global_load_lds_dwordx4 v[158:159], off
	s_waitcnt vmcnt(8)
	s_waitcnt lgkmcnt(0)
	s_barrier
	s_setprio 1
	s_waitcnt lgkmcnt(0)
	v_mfma_f32_16x16x32_bf16 v[124:127], v[138:141], v[178:181], v[124:127]
	v_mfma_f32_16x16x32_bf16 v[116:119], v[150:153], v[178:181], v[116:119]
	v_mfma_f32_16x16x32_bf16 v[108:111], v[138:141], v[186:189], v[108:111]
	v_mfma_f32_16x16x32_bf16 v[100:103], v[150:153], v[186:189], v[100:103]
	v_mfma_f32_16x16x32_bf16 v[92:95], v[138:141], v[194:197], v[92:95]
	v_mfma_f32_16x16x32_bf16 v[84:87], v[150:153], v[194:197], v[84:87]
	v_mfma_f32_16x16x32_bf16 v[76:79], v[138:141], v[202:205], v[76:79]
	v_mfma_f32_16x16x32_bf16 v[64:67], v[150:153], v[202:205], v[64:67]
	v_mfma_f32_16x16x32_bf16 v[124:127], v[142:145], v[182:185], v[124:127]
	v_mfma_f32_16x16x32_bf16 v[116:119], v[154:157], v[182:185], v[116:119]
	v_mfma_f32_16x16x32_bf16 v[108:111], v[142:145], v[190:193], v[108:111]
	v_mfma_f32_16x16x32_bf16 v[100:103], v[154:157], v[190:193], v[100:103]
	v_mfma_f32_16x16x32_bf16 v[92:95], v[142:145], v[198:201], v[92:95]
	v_mfma_f32_16x16x32_bf16 v[84:87], v[154:157], v[198:201], v[84:87]
	v_mfma_f32_16x16x32_bf16 v[76:79], v[142:145], v[206:209], v[76:79]
	v_mfma_f32_16x16x32_bf16 v[64:67], v[154:157], v[206:209], v[64:67]
	s_setprio 0
	s_setprio 1
	v_mfma_f32_16x16x32_bf16 v[120:123], v[162:165], v[178:181], v[120:123]
	v_mfma_f32_16x16x32_bf16 v[112:115], v[170:173], v[178:181], v[112:115]
	v_mfma_f32_16x16x32_bf16 v[104:107], v[162:165], v[186:189], v[104:107]
	v_mfma_f32_16x16x32_bf16 v[96:99], v[170:173], v[186:189], v[96:99]
	v_mfma_f32_16x16x32_bf16 v[88:91], v[162:165], v[194:197], v[88:91]
	v_mfma_f32_16x16x32_bf16 v[80:83], v[170:173], v[194:197], v[80:83]
	v_mfma_f32_16x16x32_bf16 v[72:75], v[162:165], v[202:205], v[72:75]
	v_mfma_f32_16x16x32_bf16 v[68:71], v[170:173], v[202:205], v[68:71]
	v_mfma_f32_16x16x32_bf16 v[120:123], v[166:169], v[182:185], v[120:123]
	v_mfma_f32_16x16x32_bf16 v[112:115], v[174:177], v[182:185], v[112:115]
	v_mfma_f32_16x16x32_bf16 v[104:107], v[166:169], v[190:193], v[104:107]
	v_mfma_f32_16x16x32_bf16 v[96:99], v[174:177], v[190:193], v[96:99]
	v_mfma_f32_16x16x32_bf16 v[88:91], v[166:169], v[198:201], v[88:91]
	v_mfma_f32_16x16x32_bf16 v[80:83], v[174:177], v[198:201], v[80:83]
	v_mfma_f32_16x16x32_bf16 v[72:75], v[166:169], v[206:209], v[72:75]
	v_mfma_f32_16x16x32_bf16 v[68:71], v[174:177], v[206:209], v[68:71]
	s_setprio 0
	s_barrier
	s_add_i32 s48, s48, s28
	v_lshl_add_u64 v[158:159], s[12:13], 0, v[160:161]
	s_mov_b32 m0, s48
	ds_read_b128 v[178:181], v149 offset:16384
	ds_read_b128 v[182:185], v149 offset:17408
	ds_read_b128 v[186:189], v149 offset:18432
	ds_read_b128 v[190:193], v149 offset:19456
	ds_read_b128 v[194:197], v149 offset:20480
	ds_read_b128 v[198:201], v149 offset:21504
	ds_read_b128 v[202:205], v149 offset:22528
	ds_read_b128 v[206:209], v149 offset:23552
	global_load_lds_dwordx4 v[158:159], off
	s_add_i32 m0, s48, 0x2000
	s_add_u32 s48, s12, 0x40000
	v_lshl_add_u64 v[210:211], s[12:13], 0, v[128:129]
	s_addc_u32 s49, s13, 0
	s_add_i32 s50, s50, s28
	global_load_lds_dwordx4 v[210:211], off
	v_lshl_add_u64 v[212:213], s[48:49], 0, v[160:161]
	s_mov_b32 m0, s50
	v_lshl_add_u64 v[214:215], s[14:15], 0, v[130:131]
	global_load_lds_dwordx4 v[212:213], off
	v_lshl_add_u64 v[212:213], s[48:49], 0, v[128:129]
	s_add_i32 m0, s50, 0x2000
	s_nop 0
	global_load_lds_dwordx4 v[212:213], off
	v_lshl_add_u64 v[212:213], s[14:15], 0, v[132:133]
	s_mov_b32 m0, s30
	s_nop 0
	global_load_lds_dwordx4 v[212:213], off
	s_mov_b32 m0, s31
	s_nop 0
	global_load_lds_dwordx4 v[214:215], off
	s_waitcnt vmcnt(8)
	s_waitcnt lgkmcnt(0)
	s_barrier
	s_setprio 1
	s_waitcnt lgkmcnt(0)
	v_mfma_f32_16x16x32_bf16 v[60:63], v[138:141], v[178:181], v[60:63]
	v_mfma_f32_16x16x32_bf16 v[48:51], v[150:153], v[178:181], v[48:51]
	v_mfma_f32_16x16x32_bf16 v[44:47], v[138:141], v[186:189], v[44:47]
	v_mfma_f32_16x16x32_bf16 v[32:35], v[150:153], v[186:189], v[32:35]
	v_mfma_f32_16x16x32_bf16 v[28:31], v[138:141], v[194:197], v[28:31]
	v_mfma_f32_16x16x32_bf16 v[16:19], v[150:153], v[194:197], v[16:19]
	v_mfma_f32_16x16x32_bf16 v[12:15], v[138:141], v[202:205], v[12:15]
	v_mfma_f32_16x16x32_bf16 v[0:3], v[150:153], v[202:205], v[0:3]
	v_mfma_f32_16x16x32_bf16 v[60:63], v[142:145], v[182:185], v[60:63]
	v_mfma_f32_16x16x32_bf16 v[48:51], v[154:157], v[182:185], v[48:51]
	v_mfma_f32_16x16x32_bf16 v[44:47], v[142:145], v[190:193], v[44:47]
	v_mfma_f32_16x16x32_bf16 v[32:35], v[154:157], v[190:193], v[32:35]
	v_mfma_f32_16x16x32_bf16 v[28:31], v[142:145], v[198:201], v[28:31]
	v_mfma_f32_16x16x32_bf16 v[16:19], v[154:157], v[198:201], v[16:19]
	v_mfma_f32_16x16x32_bf16 v[12:15], v[142:145], v[206:209], v[12:15]
	v_mfma_f32_16x16x32_bf16 v[0:3], v[154:157], v[206:209], v[0:3]
	s_setprio 0
	s_setprio 1
	v_mfma_f32_16x16x32_bf16 v[56:59], v[162:165], v[178:181], v[56:59]
	v_mfma_f32_16x16x32_bf16 v[52:55], v[170:173], v[178:181], v[52:55]
	v_mfma_f32_16x16x32_bf16 v[40:43], v[162:165], v[186:189], v[40:43]
	v_mfma_f32_16x16x32_bf16 v[36:39], v[170:173], v[186:189], v[36:39]
	v_mfma_f32_16x16x32_bf16 v[24:27], v[162:165], v[194:197], v[24:27]
	v_mfma_f32_16x16x32_bf16 v[20:23], v[170:173], v[194:197], v[20:23]
	v_mfma_f32_16x16x32_bf16 v[8:11], v[162:165], v[202:205], v[8:11]
	v_mfma_f32_16x16x32_bf16 v[4:7], v[170:173], v[202:205], v[4:7]
	v_mfma_f32_16x16x32_bf16 v[56:59], v[166:169], v[182:185], v[56:59]
	v_mfma_f32_16x16x32_bf16 v[52:55], v[174:177], v[182:185], v[52:55]
	v_mfma_f32_16x16x32_bf16 v[40:43], v[166:169], v[190:193], v[40:43]
	v_mfma_f32_16x16x32_bf16 v[36:39], v[174:177], v[190:193], v[36:39]
	v_mfma_f32_16x16x32_bf16 v[24:27], v[166:169], v[198:201], v[24:27]
	v_mfma_f32_16x16x32_bf16 v[20:23], v[174:177], v[198:201], v[20:23]
	v_mfma_f32_16x16x32_bf16 v[8:11], v[166:169], v[206:209], v[8:11]
	v_mfma_f32_16x16x32_bf16 v[4:7], v[174:177], v[206:209], v[4:7]
	s_setprio 0
	s_barrier
	s_add_i32 s48, 0, 0x18000
	s_add_i32 s49, 0, 0x1c000
	v_add_u32_e32 v154, s48, v147
	v_add_u32_e32 v174, s49, v147
	ds_read_b128 v[138:141], v154
	ds_read_b128 v[142:145], v154 offset:1024
	ds_read_b128 v[150:153], v154 offset:2048
	ds_read_b128 v[154:157], v154 offset:3072
	ds_read_b128 v[162:165], v174
	ds_read_b128 v[166:169], v174 offset:1024
	ds_read_b128 v[170:173], v174 offset:2048
	ds_read_b128 v[174:177], v174 offset:3072
	s_add_u32 s14, s14, 0x40000
	s_addc_u32 s15, s15, 0
	s_mov_b32 m0, s33
	v_lshl_add_u64 v[216:217], s[14:15], 0, v[132:133]
	ds_read_b128 v[178:181], v149 offset:32768
	ds_read_b128 v[182:185], v149 offset:33792
	ds_read_b128 v[186:189], v149 offset:34816
	ds_read_b128 v[190:193], v149 offset:35840
	ds_read_b128 v[194:197], v149 offset:36864
	ds_read_b128 v[198:201], v149 offset:37888
	ds_read_b128 v[202:205], v149 offset:38912
	ds_read_b128 v[206:209], v149 offset:39936
	global_load_lds_dwordx4 v[216:217], off
	v_lshl_add_u64 v[216:217], s[14:15], 0, v[130:131]
	s_mov_b32 m0, s34
	s_nop 0
	global_load_lds_dwordx4 v[216:217], off
	s_waitcnt vmcnt(8)
	s_waitcnt lgkmcnt(0)
	s_barrier
	s_setprio 1
	s_waitcnt lgkmcnt(0)
	v_mfma_f32_16x16x32_bf16 v[124:127], v[138:141], v[178:181], v[124:127]
	v_mfma_f32_16x16x32_bf16 v[116:119], v[150:153], v[178:181], v[116:119]
	v_mfma_f32_16x16x32_bf16 v[108:111], v[138:141], v[186:189], v[108:111]
	v_mfma_f32_16x16x32_bf16 v[100:103], v[150:153], v[186:189], v[100:103]
	v_mfma_f32_16x16x32_bf16 v[92:95], v[138:141], v[194:197], v[92:95]
	v_mfma_f32_16x16x32_bf16 v[84:87], v[150:153], v[194:197], v[84:87]
	v_mfma_f32_16x16x32_bf16 v[76:79], v[138:141], v[202:205], v[76:79]
	v_mfma_f32_16x16x32_bf16 v[64:67], v[150:153], v[202:205], v[64:67]
	v_mfma_f32_16x16x32_bf16 v[124:127], v[142:145], v[182:185], v[124:127]
	v_mfma_f32_16x16x32_bf16 v[116:119], v[154:157], v[182:185], v[116:119]
	v_mfma_f32_16x16x32_bf16 v[108:111], v[142:145], v[190:193], v[108:111]
	v_mfma_f32_16x16x32_bf16 v[100:103], v[154:157], v[190:193], v[100:103]
	v_mfma_f32_16x16x32_bf16 v[92:95], v[142:145], v[198:201], v[92:95]
	v_mfma_f32_16x16x32_bf16 v[84:87], v[154:157], v[198:201], v[84:87]
	v_mfma_f32_16x16x32_bf16 v[76:79], v[142:145], v[206:209], v[76:79]
	v_mfma_f32_16x16x32_bf16 v[64:67], v[154:157], v[206:209], v[64:67]
	s_setprio 0
	s_setprio 1
	v_mfma_f32_16x16x32_bf16 v[120:123], v[162:165], v[178:181], v[120:123]
	v_mfma_f32_16x16x32_bf16 v[112:115], v[170:173], v[178:181], v[112:115]
	v_mfma_f32_16x16x32_bf16 v[104:107], v[162:165], v[186:189], v[104:107]
	v_mfma_f32_16x16x32_bf16 v[96:99], v[170:173], v[186:189], v[96:99]
	v_mfma_f32_16x16x32_bf16 v[88:91], v[162:165], v[194:197], v[88:91]
	v_mfma_f32_16x16x32_bf16 v[80:83], v[170:173], v[194:197], v[80:83]
	v_mfma_f32_16x16x32_bf16 v[72:75], v[162:165], v[202:205], v[72:75]
	v_mfma_f32_16x16x32_bf16 v[68:71], v[170:173], v[202:205], v[68:71]
	v_mfma_f32_16x16x32_bf16 v[120:123], v[166:169], v[182:185], v[120:123]
	v_mfma_f32_16x16x32_bf16 v[112:115], v[174:177], v[182:185], v[112:115]
	v_mfma_f32_16x16x32_bf16 v[104:107], v[166:169], v[190:193], v[104:107]
	v_mfma_f32_16x16x32_bf16 v[96:99], v[174:177], v[190:193], v[96:99]
	v_mfma_f32_16x16x32_bf16 v[88:91], v[166:169], v[198:201], v[88:91]
	v_mfma_f32_16x16x32_bf16 v[80:83], v[174:177], v[198:201], v[80:83]
	v_mfma_f32_16x16x32_bf16 v[72:75], v[166:169], v[206:209], v[72:75]
	v_mfma_f32_16x16x32_bf16 v[68:71], v[174:177], v[206:209], v[68:71]
	s_setprio 0
	s_barrier
	s_add_i32 s14, s48, s28
	v_lshl_add_u64 v[158:159], v[158:159], 0, s[88:89]
	s_mov_b32 m0, s14
	ds_read_b128 v[178:181], v149 offset:49152
	ds_read_b128 v[182:185], v149 offset:50176
	ds_read_b128 v[186:189], v149 offset:51200
	ds_read_b128 v[190:193], v149 offset:52224
	ds_read_b128 v[194:197], v149 offset:53248
	ds_read_b128 v[198:201], v149 offset:54272
	ds_read_b128 v[202:205], v149 offset:55296
	ds_read_b128 v[206:209], v149 offset:56320
	global_load_lds_dwordx4 v[158:159], off
	s_add_i32 m0, s14, 0x2000
	s_add_u32 s12, s12, 0x40080
	v_lshl_add_u64 v[158:159], v[210:211], 0, s[88:89]
	s_addc_u32 s13, s13, 0
	s_add_i32 s14, s49, s28
	global_load_lds_dwordx4 v[158:159], off
	v_lshl_add_u64 v[158:159], s[12:13], 0, v[160:161]
	s_mov_b32 m0, s14
	s_nop 0
	global_load_lds_dwordx4 v[158:159], off
	v_lshl_add_u64 v[158:159], s[12:13], 0, v[128:129]
	s_add_i32 m0, s14, 0x2000
	s_nop 0
	global_load_lds_dwordx4 v[158:159], off
	v_lshl_add_u64 v[158:159], v[212:213], 0, s[88:89]
	s_mov_b32 m0, s35
	s_nop 0
	global_load_lds_dwordx4 v[158:159], off
	v_lshl_add_u64 v[158:159], v[214:215], 0, s[88:89]
	s_mov_b32 m0, s90
	s_nop 0
	global_load_lds_dwordx4 v[158:159], off
	s_waitcnt vmcnt(8)
	s_waitcnt lgkmcnt(0)
	s_barrier
	s_setprio 1
	s_waitcnt lgkmcnt(0)
	v_mfma_f32_16x16x32_bf16 v[60:63], v[138:141], v[178:181], v[60:63]
	v_mfma_f32_16x16x32_bf16 v[48:51], v[150:153], v[178:181], v[48:51]
	v_mfma_f32_16x16x32_bf16 v[44:47], v[138:141], v[186:189], v[44:47]
	v_mfma_f32_16x16x32_bf16 v[32:35], v[150:153], v[186:189], v[32:35]
	v_mfma_f32_16x16x32_bf16 v[28:31], v[138:141], v[194:197], v[28:31]
	v_mfma_f32_16x16x32_bf16 v[16:19], v[150:153], v[194:197], v[16:19]
	v_mfma_f32_16x16x32_bf16 v[12:15], v[138:141], v[202:205], v[12:15]
	v_mfma_f32_16x16x32_bf16 v[0:3], v[150:153], v[202:205], v[0:3]
	v_mfma_f32_16x16x32_bf16 v[60:63], v[142:145], v[182:185], v[60:63]
	v_mfma_f32_16x16x32_bf16 v[48:51], v[154:157], v[182:185], v[48:51]
	v_mfma_f32_16x16x32_bf16 v[44:47], v[142:145], v[190:193], v[44:47]
	v_mfma_f32_16x16x32_bf16 v[32:35], v[154:157], v[190:193], v[32:35]
	v_mfma_f32_16x16x32_bf16 v[28:31], v[142:145], v[198:201], v[28:31]
	v_mfma_f32_16x16x32_bf16 v[16:19], v[154:157], v[198:201], v[16:19]
	v_mfma_f32_16x16x32_bf16 v[12:15], v[142:145], v[206:209], v[12:15]
	v_mfma_f32_16x16x32_bf16 v[0:3], v[154:157], v[206:209], v[0:3]
	s_setprio 0
	s_setprio 1
	v_mfma_f32_16x16x32_bf16 v[56:59], v[162:165], v[178:181], v[56:59]
	v_mfma_f32_16x16x32_bf16 v[52:55], v[170:173], v[178:181], v[52:55]
	v_mfma_f32_16x16x32_bf16 v[40:43], v[162:165], v[186:189], v[40:43]
	v_mfma_f32_16x16x32_bf16 v[36:39], v[170:173], v[186:189], v[36:39]
	v_mfma_f32_16x16x32_bf16 v[24:27], v[162:165], v[194:197], v[24:27]
	v_mfma_f32_16x16x32_bf16 v[20:23], v[170:173], v[194:197], v[20:23]
	v_mfma_f32_16x16x32_bf16 v[8:11], v[162:165], v[202:205], v[8:11]
	v_mfma_f32_16x16x32_bf16 v[4:7], v[170:173], v[202:205], v[4:7]
	v_mfma_f32_16x16x32_bf16 v[56:59], v[166:169], v[182:185], v[56:59]
	v_mfma_f32_16x16x32_bf16 v[52:55], v[174:177], v[182:185], v[52:55]
	v_mfma_f32_16x16x32_bf16 v[40:43], v[166:169], v[190:193], v[40:43]
	v_mfma_f32_16x16x32_bf16 v[36:39], v[174:177], v[190:193], v[36:39]
	v_mfma_f32_16x16x32_bf16 v[24:27], v[166:169], v[198:201], v[24:27]
	v_mfma_f32_16x16x32_bf16 v[20:23], v[174:177], v[198:201], v[20:23]
	v_mfma_f32_16x16x32_bf16 v[8:11], v[166:169], v[206:209], v[8:11]
	v_mfma_f32_16x16x32_bf16 v[4:7], v[174:177], v[206:209], v[4:7]
	s_setprio 0
	s_barrier
	s_add_i32 s22, s22, 2
	s_add_u32 s96, s96, 0x100
	s_addc_u32 s21, s21, 0
	s_add_u32 s10, s10, 0x100
	s_addc_u32 s11, s11, 0
	s_cmp_gt_u32 s22, 13
	s_cbranch_scc0 .LBB0_56
	v_lshl_add_u32 v192, s8, 8, v146
	v_lshlrev_b32_e32 v192, 3, v192
	global_load_dwordx2 v[176:177], v192, s[4:5]
	global_load_dwordx2 v[178:179], v192, s[4:5] offset:128
	global_load_dwordx2 v[180:181], v192, s[4:5] offset:256
	global_load_dwordx2 v[182:183], v192, s[4:5] offset:384
	global_load_dwordx2 v[184:185], v192, s[4:5] offset:1024
	global_load_dwordx2 v[186:187], v192, s[4:5] offset:1152
	global_load_dwordx2 v[188:189], v192, s[4:5] offset:1280
	global_load_dwordx2 v[190:191], v192, s[4:5] offset:1408
	s_and_b64 vcc, exec, s[6:7]
	s_cbranch_vccz .LBB0_59
	s_barrier
.LBB0_59:
	v_lshl_or_b32 v142, s9, 7, v148
	v_lshl_add_u32 v138, s8, 8, v146
	v_ashrrev_i32_e32 v143, 31, v142
	v_mov_b64_e32 v[140:141], s[2:3]
	v_ashrrev_i32_e32 v139, 31, v138
	v_mad_i64_i32 v[144:145], s[8:9], v138, s16, v[140:141]
	v_lshlrev_b64 v[142:143], 1, v[142:143]
	v_lshl_add_u64 v[150:151], v[144:145], 0, v[142:143]
	v_lshl_add_u64 v[144:145], v[138:139], 3, s[4:5]
	v_pk_mul_f32 v[120:121], v[124:125], v[120:121]
	v_pk_mul_f32 v[122:123], v[126:127], v[122:123]
	v_pk_mul_f32 v[112:113], v[116:117], v[112:113]
	v_pk_mul_f32 v[114:115], v[118:119], v[114:115]
	v_pk_mul_f32 v[104:105], v[108:109], v[104:105]
	v_pk_mul_f32 v[106:107], v[110:111], v[106:107]
	v_pk_mul_f32 v[96:97], v[100:101], v[96:97]
	v_pk_mul_f32 v[98:99], v[102:103], v[98:99]
	v_pk_mul_f32 v[88:89], v[92:93], v[88:89]
	v_pk_mul_f32 v[90:91], v[94:95], v[90:91]
	v_pk_mul_f32 v[80:81], v[84:85], v[80:81]
	v_pk_mul_f32 v[82:83], v[86:87], v[82:83]
	v_pk_mul_f32 v[72:73], v[76:77], v[72:73]
	v_pk_mul_f32 v[74:75], v[78:79], v[74:75]
	v_pk_mul_f32 v[70:71], v[66:67], v[70:71]
	v_pk_mul_f32 v[56:57], v[60:61], v[56:57]
	v_pk_mul_f32 v[58:59], v[62:63], v[58:59]
	v_pk_mul_f32 v[54:55], v[50:51], v[54:55]
	v_pk_mul_f32 v[40:41], v[44:45], v[40:41]
	v_pk_mul_f32 v[42:43], v[46:47], v[42:43]
	v_pk_mul_f32 v[38:39], v[34:35], v[38:39]
	v_pk_mul_f32 v[24:25], v[28:29], v[24:25]
	v_pk_mul_f32 v[26:27], v[30:31], v[26:27]
	v_pk_mul_f32 v[22:23], v[18:19], v[22:23]
	v_pk_mul_f32 v[8:9], v[12:13], v[8:9]
	v_pk_mul_f32 v[10:11], v[14:15], v[10:11]
	v_pk_mul_f32 v[6:7], v[2:3], v[6:7]
	s_andn2_b64 vcc, exec, s[38:39]
	v_mov_b64_e32 v[172:173], v[244:245]
	s_waitcnt vmcnt(0) lgkmcnt(0)
	v_mov_b64_e32 v[152:153], v[176:177]
	v_ffbh_u32_e32 v139, v153
	v_min_u32_e32 v139, 32, v139
	v_lshlrev_b64 v[152:153], v139, v[152:153]
	v_min_u32_e32 v152, 1, v152
	v_or_b32_e32 v152, v153, v152
	v_cvt_f32_u32_e32 v152, v152
	v_sub_u32_e32 v139, 32, v139
	v_ldexp_f32 v139, v152, v139
	v_mul_f32_e32 v139, 0x35800000, v139
	v_fmamk_f32 v139, v139, 0x3a800000, v219
	v_rsq_f32_e32 v139, v139
	s_nop 0
	v_mul_f32_e32 v152, 0xbfb8aa3b, v139
	v_pk_mul_f32 v[156:157], v[124:125], v[152:153] op_sel_hi:[1,0]
	v_mul_f32_e32 v154, v139, v139
	v_exp_f32_e32 v156, v156
	v_exp_f32_e32 v157, v157
	s_nop 0
	v_pk_add_f32 v[156:157], v[156:157], 1.0 op_sel_hi:[1,0]
	s_nop 0
	v_rcp_f32_e32 v156, v156
	v_rcp_f32_e32 v157, v157
	s_nop 0
	v_pk_mul_f32 v[124:125], v[154:155], v[156:157] op_sel_hi:[0,1]
	v_pk_mul_f32 v[120:121], v[120:121], v[124:125]
	v_pk_mul_f32 v[124:125], v[126:127], v[152:153] op_sel_hi:[1,0]
	s_nop 0
	v_exp_f32_e32 v124, v124
	v_exp_f32_e32 v125, v125
	s_nop 0
	v_pk_add_f32 v[124:125], v[124:125], 1.0 op_sel_hi:[1,0]
	s_nop 0
	v_rcp_f32_e32 v124, v124
	v_rcp_f32_e32 v125, v125
	s_nop 0
	v_pk_mul_f32 v[124:125], v[154:155], v[124:125] op_sel_hi:[0,1]
	v_pk_mul_f32 v[122:123], v[122:123], v[124:125]
	v_pk_mul_f32 v[124:125], v[116:117], v[152:153] op_sel_hi:[1,0]
	s_nop 0
	v_exp_f32_e32 v124, v124
	v_exp_f32_e32 v125, v125
	s_nop 0
	v_pk_add_f32 v[124:125], v[124:125], 1.0 op_sel_hi:[1,0]
	s_nop 0
	v_rcp_f32_e32 v124, v124
	v_rcp_f32_e32 v125, v125
	s_nop 0
	v_pk_mul_f32 v[116:117], v[154:155], v[124:125] op_sel_hi:[0,1]
	v_pk_mul_f32 v[116:117], v[112:113], v[116:117]
	v_pk_mul_f32 v[112:113], v[118:119], v[152:153] op_sel_hi:[1,0]
	s_nop 0
	v_exp_f32_e32 v112, v112
	v_exp_f32_e32 v113, v113
	s_nop 0
	v_pk_add_f32 v[112:113], v[112:113], 1.0 op_sel_hi:[1,0]
	s_nop 0
	v_rcp_f32_e32 v112, v112
	v_rcp_f32_e32 v113, v113
	s_nop 0
	v_pk_mul_f32 v[112:113], v[154:155], v[112:113] op_sel_hi:[0,1]
	v_pk_mul_f32 v[118:119], v[114:115], v[112:113]
	v_cvt_pk_bf16_f32 v112, v120, v121
	v_cvt_pk_bf16_f32 v113, v122, v123
	v_cvt_pk_bf16_f32 v114, v116, v117
	v_cvt_pk_bf16_f32 v115, v118, v119
	global_store_dwordx4 v[150:151], v[112:115], off
	s_nop 1
	v_or_b32_e32 v114, 16, v138
	v_ashrrev_i32_e32 v115, 31, v114
	v_mad_i64_i32 v[112:113], s[8:9], v114, s16, v[140:141]
	v_lshl_add_u64 v[114:115], v[114:115], 3, s[4:5]
	s_nop 1
	v_mov_b64_e32 v[114:115], v[178:179]
	v_lshl_add_u64 v[112:113], v[112:113], 0, v[142:143]
	v_ffbh_u32_e32 v116, v115
	v_min_u32_e32 v116, 32, v116
	v_lshlrev_b64 v[114:115], v116, v[114:115]
	v_min_u32_e32 v114, 1, v114
	v_or_b32_e32 v114, v115, v114
	v_cvt_f32_u32_e32 v114, v114
	v_sub_u32_e32 v115, 32, v116
	v_ldexp_f32 v114, v114, v115
	v_mul_f32_e32 v114, 0x35800000, v114
	v_fmamk_f32 v114, v114, 0x3a800000, v219
	v_rsq_f32_e32 v115, v114
	s_nop 0
	v_mul_f32_e32 v114, 0xbfb8aa3b, v115
	v_pk_mul_f32 v[118:119], v[108:109], v[114:115] op_sel_hi:[1,0]
	v_mul_f32_e32 v116, v115, v115
	v_exp_f32_e32 v118, v118
	v_exp_f32_e32 v119, v119
	s_nop 0
	v_pk_add_f32 v[118:119], v[118:119], 1.0 op_sel_hi:[1,0]
	s_nop 0
	v_rcp_f32_e32 v118, v118
	v_rcp_f32_e32 v119, v119
	s_nop 0
	v_pk_mul_f32 v[108:109], v[116:117], v[118:119] op_sel_hi:[0,1]
	v_pk_mul_f32 v[104:105], v[104:105], v[108:109]
	v_pk_mul_f32 v[108:109], v[110:111], v[114:115] op_sel_hi:[1,0]
	s_nop 0
	v_exp_f32_e32 v108, v108
	v_exp_f32_e32 v109, v109
	s_nop 0
	v_pk_add_f32 v[108:109], v[108:109], 1.0 op_sel_hi:[1,0]
	s_nop 0
	v_rcp_f32_e32 v108, v108
	v_rcp_f32_e32 v109, v109
	s_nop 0
	v_pk_mul_f32 v[108:109], v[116:117], v[108:109] op_sel_hi:[0,1]
	v_pk_mul_f32 v[106:107], v[106:107], v[108:109]
	v_pk_mul_f32 v[108:109], v[100:101], v[114:115] op_sel_hi:[1,0]
	s_nop 0
	v_exp_f32_e32 v108, v108
	v_exp_f32_e32 v109, v109
	s_nop 0
	v_pk_add_f32 v[108:109], v[108:109], 1.0 op_sel_hi:[1,0]
	s_nop 0
	v_rcp_f32_e32 v108, v108
	v_rcp_f32_e32 v109, v109
	s_nop 0
	v_pk_mul_f32 v[100:101], v[116:117], v[108:109] op_sel_hi:[0,1]
	v_pk_mul_f32 v[100:101], v[96:97], v[100:101]
	v_pk_mul_f32 v[96:97], v[102:103], v[114:115] op_sel_hi:[1,0]
	s_nop 0
	v_exp_f32_e32 v96, v96
	v_exp_f32_e32 v97, v97
	s_nop 0
	v_pk_add_f32 v[96:97], v[96:97], 1.0 op_sel_hi:[1,0]
	s_nop 0
	v_rcp_f32_e32 v96, v96
	v_rcp_f32_e32 v97, v97
	s_nop 0
	v_pk_mul_f32 v[96:97], v[116:117], v[96:97] op_sel_hi:[0,1]
	v_pk_mul_f32 v[102:103], v[98:99], v[96:97]
	v_cvt_pk_bf16_f32 v96, v104, v105
	v_cvt_pk_bf16_f32 v97, v106, v107
	v_cvt_pk_bf16_f32 v98, v100, v101
	v_cvt_pk_bf16_f32 v99, v102, v103
	global_store_dwordx4 v[112:113], v[96:99], off
	s_nop 1
	v_or_b32_e32 v98, 32, v138
	v_ashrrev_i32_e32 v99, 31, v98
	v_mad_i64_i32 v[96:97], s[8:9], v98, s16, v[140:141]
	v_lshl_add_u64 v[98:99], v[98:99], 3, s[4:5]
	s_nop 1
	v_mov_b64_e32 v[98:99], v[180:181]
	v_lshl_add_u64 v[96:97], v[96:97], 0, v[142:143]
	v_ffbh_u32_e32 v100, v99
	v_min_u32_e32 v100, 32, v100
	v_lshlrev_b64 v[98:99], v100, v[98:99]
	v_min_u32_e32 v98, 1, v98
	v_or_b32_e32 v98, v99, v98
	v_cvt_f32_u32_e32 v98, v98
	v_sub_u32_e32 v99, 32, v100
	v_ldexp_f32 v98, v98, v99
	v_mul_f32_e32 v98, 0x35800000, v98
	v_fmamk_f32 v98, v98, 0x3a800000, v219
	v_rsq_f32_e32 v99, v98
	s_nop 0
	v_mul_f32_e32 v98, 0xbfb8aa3b, v99
	v_pk_mul_f32 v[102:103], v[92:93], v[98:99] op_sel_hi:[1,0]
	v_mul_f32_e32 v100, v99, v99
	v_exp_f32_e32 v102, v102
	v_exp_f32_e32 v103, v103
	s_nop 0
	v_pk_add_f32 v[102:103], v[102:103], 1.0 op_sel_hi:[1,0]
	s_nop 0
	v_rcp_f32_e32 v102, v102
	v_rcp_f32_e32 v103, v103
	s_nop 0
	v_pk_mul_f32 v[92:93], v[100:101], v[102:103] op_sel_hi:[0,1]
	v_pk_mul_f32 v[88:89], v[88:89], v[92:93]
	v_pk_mul_f32 v[92:93], v[94:95], v[98:99] op_sel_hi:[1,0]
	s_nop 0
	v_exp_f32_e32 v92, v92
	v_exp_f32_e32 v93, v93
	s_nop 0
	v_pk_add_f32 v[92:93], v[92:93], 1.0 op_sel_hi:[1,0]
	s_nop 0
	v_rcp_f32_e32 v92, v92
	v_rcp_f32_e32 v93, v93
	s_nop 0
	v_pk_mul_f32 v[92:93], v[100:101], v[92:93] op_sel_hi:[0,1]
	v_pk_mul_f32 v[90:91], v[90:91], v[92:93]
	v_pk_mul_f32 v[92:93], v[84:85], v[98:99] op_sel_hi:[1,0]
	s_nop 0
	v_exp_f32_e32 v92, v92
	v_exp_f32_e32 v93, v93
	s_nop 0
	v_pk_add_f32 v[92:93], v[92:93], 1.0 op_sel_hi:[1,0]
	s_nop 0
	v_rcp_f32_e32 v92, v92
	v_rcp_f32_e32 v93, v93
	s_nop 0
	v_pk_mul_f32 v[84:85], v[100:101], v[92:93] op_sel_hi:[0,1]
	v_pk_mul_f32 v[84:85], v[80:81], v[84:85]
	v_pk_mul_f32 v[80:81], v[86:87], v[98:99] op_sel_hi:[1,0]
	s_nop 0
	v_exp_f32_e32 v80, v80
	v_exp_f32_e32 v81, v81
	s_nop 0
	v_pk_add_f32 v[80:81], v[80:81], 1.0 op_sel_hi:[1,0]
	s_nop 0
	v_rcp_f32_e32 v80, v80
	v_rcp_f32_e32 v81, v81
	s_nop 0
	v_pk_mul_f32 v[80:81], v[100:101], v[80:81] op_sel_hi:[0,1]
	v_pk_mul_f32 v[86:87], v[82:83], v[80:81]
	v_cvt_pk_bf16_f32 v80, v88, v89
	v_cvt_pk_bf16_f32 v81, v90, v91
	v_cvt_pk_bf16_f32 v82, v84, v85
	v_cvt_pk_bf16_f32 v83, v86, v87
	global_store_dwordx4 v[96:97], v[80:83], off
	s_nop 1
	v_or_b32_e32 v82, 48, v138
	v_ashrrev_i32_e32 v83, 31, v82
	v_mad_i64_i32 v[80:81], s[8:9], v82, s16, v[140:141]
	v_lshl_add_u64 v[82:83], v[82:83], 3, s[4:5]
	s_nop 1
	v_mov_b64_e32 v[82:83], v[182:183]
	v_lshl_add_u64 v[80:81], v[80:81], 0, v[142:143]
	v_ffbh_u32_e32 v84, v83
	v_min_u32_e32 v84, 32, v84
	v_lshlrev_b64 v[82:83], v84, v[82:83]
	v_min_u32_e32 v82, 1, v82
	v_or_b32_e32 v82, v83, v82
	v_cvt_f32_u32_e32 v82, v82
	v_sub_u32_e32 v83, 32, v84
	v_ldexp_f32 v82, v82, v83
	v_mul_f32_e32 v82, 0x35800000, v82
	v_fmamk_f32 v82, v82, 0x3a800000, v219
	v_rsq_f32_e32 v82, v82
	s_nop 0
	v_mul_f32_e32 v84, 0xbfb8aa3b, v82
	v_pk_mul_f32 v[86:87], v[76:77], v[84:85] op_sel_hi:[1,0]
	v_mul_f32_e32 v82, v82, v82
	v_exp_f32_e32 v86, v86
	v_exp_f32_e32 v87, v87
	s_nop 0
	v_pk_add_f32 v[86:87], v[86:87], 1.0 op_sel_hi:[1,0]
	s_nop 0
	v_rcp_f32_e32 v86, v86
	v_rcp_f32_e32 v87, v87
	s_nop 0
	v_pk_mul_f32 v[76:77], v[82:83], v[86:87] op_sel_hi:[0,1]
	v_pk_mul_f32 v[72:73], v[72:73], v[76:77]
	v_pk_mul_f32 v[76:77], v[78:79], v[84:85] op_sel_hi:[1,0]
	s_nop 0
	v_exp_f32_e32 v76, v76
	v_exp_f32_e32 v77, v77
	s_nop 0
	v_pk_add_f32 v[76:77], v[76:77], 1.0 op_sel_hi:[1,0]
	s_nop 0
	v_rcp_f32_e32 v76, v76
	v_rcp_f32_e32 v77, v77
	s_nop 0
	v_pk_mul_f32 v[76:77], v[82:83], v[76:77] op_sel_hi:[0,1]
	v_pk_mul_f32 v[74:75], v[74:75], v[76:77]
	v_pk_mul_f32 v[76:77], v[64:65], v[84:85] op_sel_hi:[1,0]
	v_pk_mul_f32 v[64:65], v[64:65], v[68:69]
	v_exp_f32_e32 v76, v76
	v_exp_f32_e32 v77, v77
	s_nop 0
	v_pk_add_f32 v[76:77], v[76:77], 1.0 op_sel_hi:[1,0]
	s_nop 0
	v_rcp_f32_e32 v76, v76
	v_rcp_f32_e32 v77, v77
	s_nop 0
	v_pk_mul_f32 v[68:69], v[82:83], v[76:77] op_sel_hi:[0,1]
	v_pk_mul_f32 v[68:69], v[64:65], v[68:69]
	v_pk_mul_f32 v[64:65], v[66:67], v[84:85] op_sel_hi:[1,0]
	v_cvt_pk_bf16_f32 v66, v68, v69
	v_exp_f32_e32 v64, v64
	v_exp_f32_e32 v65, v65
	s_nop 0
	v_pk_add_f32 v[64:65], v[64:65], 1.0 op_sel_hi:[1,0]
	s_nop 0
	v_rcp_f32_e32 v64, v64
	v_rcp_f32_e32 v65, v65
	s_nop 0
	v_pk_mul_f32 v[64:65], v[82:83], v[64:65] op_sel_hi:[0,1]
	v_pk_mul_f32 v[70:71], v[70:71], v[64:65]
	v_cvt_pk_bf16_f32 v64, v72, v73
	v_cvt_pk_bf16_f32 v65, v74, v75
	v_cvt_pk_bf16_f32 v67, v70, v71
	global_store_dwordx4 v[80:81], v[64:67], off
	s_nop 1
	v_mov_b64_e32 v[66:67], v[184:185]
	v_ffbh_u32_e32 v68, v67
	v_min_u32_e32 v68, 32, v68
	v_lshlrev_b64 v[66:67], v68, v[66:67]
	v_min_u32_e32 v66, 1, v66
	v_or_b32_e32 v66, v67, v66
	v_cvt_f32_u32_e32 v66, v66
	v_sub_u32_e32 v67, 32, v68
	v_add_u32_e32 v64, 0x80, v138
	v_mad_i64_i32 v[64:65], s[8:9], v64, s16, v[140:141]
	v_ldexp_f32 v66, v66, v67
	v_mul_f32_e32 v66, 0x35800000, v66
	v_fmamk_f32 v66, v66, 0x3a800000, v219
	v_rsq_f32_e32 v66, v66
	v_lshl_add_u64 v[64:65], v[64:65], 0, v[142:143]
	v_mul_f32_e32 v68, 0xbfb8aa3b, v66
	v_pk_mul_f32 v[70:71], v[60:61], v[68:69] op_sel_hi:[1,0]
	v_mul_f32_e32 v66, v66, v66
	v_exp_f32_e32 v70, v70
	v_exp_f32_e32 v71, v71
	s_nop 0
	v_pk_add_f32 v[70:71], v[70:71], 1.0 op_sel_hi:[1,0]
	s_nop 0
	v_rcp_f32_e32 v70, v70
	v_rcp_f32_e32 v71, v71
	s_nop 0
	v_pk_mul_f32 v[60:61], v[66:67], v[70:71] op_sel_hi:[0,1]
	v_pk_mul_f32 v[56:57], v[56:57], v[60:61]
	v_pk_mul_f32 v[60:61], v[62:63], v[68:69] op_sel_hi:[1,0]
	s_nop 0
	v_exp_f32_e32 v60, v60
	v_exp_f32_e32 v61, v61
	s_nop 0
	v_pk_add_f32 v[60:61], v[60:61], 1.0 op_sel_hi:[1,0]
	s_nop 0
	v_rcp_f32_e32 v60, v60
	v_rcp_f32_e32 v61, v61
	s_nop 0
	v_pk_mul_f32 v[60:61], v[66:67], v[60:61] op_sel_hi:[0,1]
	v_pk_mul_f32 v[58:59], v[58:59], v[60:61]
	v_pk_mul_f32 v[60:61], v[48:49], v[68:69] op_sel_hi:[1,0]
	v_pk_mul_f32 v[48:49], v[48:49], v[52:53]
	v_exp_f32_e32 v60, v60
	v_exp_f32_e32 v61, v61
	s_nop 0
	v_pk_add_f32 v[60:61], v[60:61], 1.0 op_sel_hi:[1,0]
	s_nop 0
	v_rcp_f32_e32 v60, v60
	v_rcp_f32_e32 v61, v61
	s_nop 0
	v_pk_mul_f32 v[52:53], v[66:67], v[60:61] op_sel_hi:[0,1]
	v_pk_mul_f32 v[52:53], v[48:49], v[52:53]
	v_pk_mul_f32 v[48:49], v[50:51], v[68:69] op_sel_hi:[1,0]
	v_cvt_pk_bf16_f32 v50, v52, v53
	v_exp_f32_e32 v48, v48
	v_exp_f32_e32 v49, v49
	s_nop 0
	v_pk_add_f32 v[48:49], v[48:49], 1.0 op_sel_hi:[1,0]
	s_nop 0
	v_rcp_f32_e32 v48, v48
	v_rcp_f32_e32 v49, v49
	s_nop 0
	v_pk_mul_f32 v[48:49], v[66:67], v[48:49] op_sel_hi:[0,1]
	v_pk_mul_f32 v[54:55], v[54:55], v[48:49]
	v_cvt_pk_bf16_f32 v48, v56, v57
	v_cvt_pk_bf16_f32 v49, v58, v59
	v_cvt_pk_bf16_f32 v51, v54, v55
	global_store_dwordx4 v[64:65], v[48:51], off
	s_nop 1
	v_mov_b64_e32 v[50:51], v[186:187]
	v_ffbh_u32_e32 v52, v51
	v_min_u32_e32 v52, 32, v52
	v_lshlrev_b64 v[50:51], v52, v[50:51]
	v_min_u32_e32 v50, 1, v50
	v_or_b32_e32 v50, v51, v50
	v_cvt_f32_u32_e32 v50, v50
	v_sub_u32_e32 v51, 32, v52
	v_add_u32_e32 v48, 0x90, v138
	v_mad_i64_i32 v[48:49], s[8:9], v48, s16, v[140:141]
	v_ldexp_f32 v50, v50, v51
	v_mul_f32_e32 v50, 0x35800000, v50
	v_fmamk_f32 v50, v50, 0x3a800000, v219
	v_rsq_f32_e32 v50, v50
	v_lshl_add_u64 v[48:49], v[48:49], 0, v[142:143]
	v_mul_f32_e32 v52, 0xbfb8aa3b, v50
	v_pk_mul_f32 v[54:55], v[44:45], v[52:53] op_sel_hi:[1,0]
	v_mul_f32_e32 v50, v50, v50
	v_exp_f32_e32 v54, v54
	v_exp_f32_e32 v55, v55
	s_nop 0
	v_pk_add_f32 v[54:55], v[54:55], 1.0 op_sel_hi:[1,0]
	s_nop 0
	v_rcp_f32_e32 v54, v54
	v_rcp_f32_e32 v55, v55
	s_nop 0
	v_pk_mul_f32 v[44:45], v[50:51], v[54:55] op_sel_hi:[0,1]
	v_pk_mul_f32 v[40:41], v[40:41], v[44:45]
	v_pk_mul_f32 v[44:45], v[46:47], v[52:53] op_sel_hi:[1,0]
	s_nop 0
	v_exp_f32_e32 v44, v44
	v_exp_f32_e32 v45, v45
	s_nop 0
	v_pk_add_f32 v[44:45], v[44:45], 1.0 op_sel_hi:[1,0]
	s_nop 0
	v_rcp_f32_e32 v44, v44
	v_rcp_f32_e32 v45, v45
	s_nop 0
	v_pk_mul_f32 v[44:45], v[50:51], v[44:45] op_sel_hi:[0,1]
	v_pk_mul_f32 v[42:43], v[42:43], v[44:45]
	v_pk_mul_f32 v[44:45], v[32:33], v[52:53] op_sel_hi:[1,0]
	v_pk_mul_f32 v[32:33], v[32:33], v[36:37]
	v_exp_f32_e32 v44, v44
	v_exp_f32_e32 v45, v45
	s_nop 0
	v_pk_add_f32 v[44:45], v[44:45], 1.0 op_sel_hi:[1,0]
	s_nop 0
	v_rcp_f32_e32 v44, v44
	v_rcp_f32_e32 v45, v45
	s_nop 0
	v_pk_mul_f32 v[36:37], v[50:51], v[44:45] op_sel_hi:[0,1]
	v_pk_mul_f32 v[36:37], v[32:33], v[36:37]
	v_pk_mul_f32 v[32:33], v[34:35], v[52:53] op_sel_hi:[1,0]
	v_cvt_pk_bf16_f32 v34, v36, v37
	v_exp_f32_e32 v32, v32
	v_exp_f32_e32 v33, v33
	s_nop 0
	v_pk_add_f32 v[32:33], v[32:33], 1.0 op_sel_hi:[1,0]
	s_nop 0
	v_rcp_f32_e32 v32, v32
	v_rcp_f32_e32 v33, v33
	s_nop 0
	v_pk_mul_f32 v[32:33], v[50:51], v[32:33] op_sel_hi:[0,1]
	v_pk_mul_f32 v[38:39], v[38:39], v[32:33]
	v_cvt_pk_bf16_f32 v32, v40, v41
	v_cvt_pk_bf16_f32 v33, v42, v43
	v_cvt_pk_bf16_f32 v35, v38, v39
	global_store_dwordx4 v[48:49], v[32:35], off
	s_nop 1
	v_mov_b64_e32 v[34:35], v[188:189]
	v_ffbh_u32_e32 v36, v35
	v_min_u32_e32 v36, 32, v36
	v_lshlrev_b64 v[34:35], v36, v[34:35]
	v_min_u32_e32 v34, 1, v34
	v_or_b32_e32 v34, v35, v34
	v_cvt_f32_u32_e32 v34, v34
	v_sub_u32_e32 v35, 32, v36
	v_add_u32_e32 v32, 0xa0, v138
	v_mad_i64_i32 v[32:33], s[8:9], v32, s16, v[140:141]
	v_ldexp_f32 v34, v34, v35
	v_mul_f32_e32 v34, 0x35800000, v34
	v_fmamk_f32 v34, v34, 0x3a800000, v219
	v_rsq_f32_e32 v34, v34
	v_lshl_add_u64 v[32:33], v[32:33], 0, v[142:143]
	v_mul_f32_e32 v36, 0xbfb8aa3b, v34
	v_pk_mul_f32 v[38:39], v[28:29], v[36:37] op_sel_hi:[1,0]
	v_mul_f32_e32 v34, v34, v34
	v_exp_f32_e32 v38, v38
	v_exp_f32_e32 v39, v39
	s_nop 0
	v_pk_add_f32 v[38:39], v[38:39], 1.0 op_sel_hi:[1,0]
	s_nop 0
	v_rcp_f32_e32 v38, v38
	v_rcp_f32_e32 v39, v39
	s_nop 0
	v_pk_mul_f32 v[28:29], v[34:35], v[38:39] op_sel_hi:[0,1]
	v_pk_mul_f32 v[24:25], v[24:25], v[28:29]
	v_pk_mul_f32 v[28:29], v[30:31], v[36:37] op_sel_hi:[1,0]
	s_nop 0
	v_exp_f32_e32 v28, v28
	v_exp_f32_e32 v29, v29
	s_nop 0
	v_pk_add_f32 v[28:29], v[28:29], 1.0 op_sel_hi:[1,0]
	s_nop 0
	v_rcp_f32_e32 v28, v28
	v_rcp_f32_e32 v29, v29
	s_nop 0
	v_pk_mul_f32 v[28:29], v[34:35], v[28:29] op_sel_hi:[0,1]
	v_pk_mul_f32 v[26:27], v[26:27], v[28:29]
	v_pk_mul_f32 v[28:29], v[16:17], v[36:37] op_sel_hi:[1,0]
	v_pk_mul_f32 v[16:17], v[16:17], v[20:21]
	v_exp_f32_e32 v28, v28
	v_exp_f32_e32 v29, v29
	s_nop 0
	v_pk_add_f32 v[28:29], v[28:29], 1.0 op_sel_hi:[1,0]
	s_nop 0
	v_rcp_f32_e32 v28, v28
	v_rcp_f32_e32 v29, v29
	s_nop 0
	v_pk_mul_f32 v[20:21], v[34:35], v[28:29] op_sel_hi:[0,1]
	v_pk_mul_f32 v[20:21], v[16:17], v[20:21]
	v_pk_mul_f32 v[16:17], v[18:19], v[36:37] op_sel_hi:[1,0]
	v_cvt_pk_bf16_f32 v18, v20, v21
	v_exp_f32_e32 v16, v16
	v_exp_f32_e32 v17, v17
	s_nop 0
	v_pk_add_f32 v[16:17], v[16:17], 1.0 op_sel_hi:[1,0]
	s_nop 0
	v_rcp_f32_e32 v16, v16
	v_rcp_f32_e32 v17, v17
	s_nop 0
	v_pk_mul_f32 v[16:17], v[34:35], v[16:17] op_sel_hi:[0,1]
	v_pk_mul_f32 v[22:23], v[22:23], v[16:17]
	v_cvt_pk_bf16_f32 v16, v24, v25
	v_cvt_pk_bf16_f32 v17, v26, v27
	v_cvt_pk_bf16_f32 v19, v22, v23
	global_store_dwordx4 v[32:33], v[16:19], off
	s_nop 1
	v_mov_b64_e32 v[18:19], v[190:191]
	v_ffbh_u32_e32 v20, v19
	v_min_u32_e32 v20, 32, v20
	v_lshlrev_b64 v[18:19], v20, v[18:19]
	v_min_u32_e32 v18, 1, v18
	v_or_b32_e32 v18, v19, v18
	v_cvt_f32_u32_e32 v18, v18
	v_sub_u32_e32 v19, 32, v20
	v_add_u32_e32 v16, 0xb0, v138
	v_mad_i64_i32 v[16:17], s[8:9], v16, s16, v[140:141]
	v_ldexp_f32 v18, v18, v19
	v_mul_f32_e32 v18, 0x35800000, v18
	v_fmamk_f32 v18, v18, 0x3a800000, v219
	v_rsq_f32_e32 v18, v18
	v_lshl_add_u64 v[16:17], v[16:17], 0, v[142:143]
	s_mov_b64 s[8:9], -1
	v_mul_f32_e32 v20, 0xbfb8aa3b, v18
	v_pk_mul_f32 v[22:23], v[12:13], v[20:21] op_sel_hi:[1,0]
	v_mul_f32_e32 v18, v18, v18
	v_exp_f32_e32 v22, v22
	v_exp_f32_e32 v23, v23
	s_nop 0
	v_pk_add_f32 v[22:23], v[22:23], 1.0 op_sel_hi:[1,0]
	s_nop 0
	v_rcp_f32_e32 v22, v22
	v_rcp_f32_e32 v23, v23
	s_nop 0
	v_pk_mul_f32 v[12:13], v[18:19], v[22:23] op_sel_hi:[0,1]
	v_pk_mul_f32 v[8:9], v[8:9], v[12:13]
	v_pk_mul_f32 v[12:13], v[14:15], v[20:21] op_sel_hi:[1,0]
	s_nop 0
	v_exp_f32_e32 v12, v12
	v_exp_f32_e32 v13, v13
	s_nop 0
	v_pk_add_f32 v[12:13], v[12:13], 1.0 op_sel_hi:[1,0]
	s_nop 0
	v_rcp_f32_e32 v12, v12
	v_rcp_f32_e32 v13, v13
	s_nop 0
	v_pk_mul_f32 v[12:13], v[18:19], v[12:13] op_sel_hi:[0,1]
	v_pk_mul_f32 v[10:11], v[10:11], v[12:13]
	v_pk_mul_f32 v[12:13], v[0:1], v[20:21] op_sel_hi:[1,0]
	v_pk_mul_f32 v[0:1], v[0:1], v[4:5]
	v_exp_f32_e32 v12, v12
	v_exp_f32_e32 v13, v13
	s_nop 0
	v_pk_add_f32 v[12:13], v[12:13], 1.0 op_sel_hi:[1,0]
	s_nop 0
	v_rcp_f32_e32 v12, v12
	v_rcp_f32_e32 v13, v13
	s_nop 0
	v_pk_mul_f32 v[4:5], v[18:19], v[12:13] op_sel_hi:[0,1]
	v_pk_mul_f32 v[4:5], v[0:1], v[4:5]
	v_pk_mul_f32 v[0:1], v[2:3], v[20:21] op_sel_hi:[1,0]
	v_cvt_pk_bf16_f32 v2, v4, v5
	v_exp_f32_e32 v0, v0
	v_exp_f32_e32 v1, v1
	s_nop 0
	v_pk_add_f32 v[0:1], v[0:1], 1.0 op_sel_hi:[1,0]
	s_nop 0
	v_rcp_f32_e32 v0, v0
	v_rcp_f32_e32 v1, v1
	s_nop 0
	v_pk_mul_f32 v[0:1], v[18:19], v[0:1] op_sel_hi:[0,1]
	v_pk_mul_f32 v[6:7], v[6:7], v[0:1]
	v_cvt_pk_bf16_f32 v0, v8, v9
	v_cvt_pk_bf16_f32 v1, v10, v11
	v_cvt_pk_bf16_f32 v3, v6, v7
	global_store_dwordx4 v[16:17], v[0:3], off
	s_cbranch_vccnz .LBB0_52
	s_andn2_b64 vcc, exec, s[0:1]
	s_cbranch_vccnz .LBB0_51
	s_barrier
	s_branch .LBB0_51

.LBB0_212:
	s_add_u32 s12, s10, 0xfffc0080
	s_addc_u32 s13, s11, -1
	s_add_i32 s22, 0, 0x10000
	s_cmp_eq_u32 s21, 12
	s_cselect_b32 s15, s20, s13
	s_cselect_b32 s14, s37, s12
	s_cselect_b32 s13, s41, s97
	s_cselect_b32 s12, s91, s96
	s_add_i32 s50, 0, 0x14000
	v_add_u32_e32 v154, s22, v147
	v_add_u32_e32 v158, s50, v147
	ds_read_b128 v[138:141], v154
	ds_read_b128 v[142:145], v154 offset:1024
	ds_read_b128 v[150:153], v154 offset:2048
	ds_read_b128 v[154:157], v154 offset:3072
	ds_read_b128 v[174:177], v158
	ds_read_b128 v[178:181], v158 offset:1024
	ds_read_b128 v[182:185], v158 offset:2048
	ds_read_b128 v[186:189], v158 offset:3072
	v_lshl_add_u64 v[158:159], s[10:11], 0, v[136:137]
	s_add_i32 m0, s30, 0xc000
	ds_read_b128 v[190:193], v149
	ds_read_b128 v[194:197], v149 offset:1024
	ds_read_b128 v[198:201], v149 offset:2048
	ds_read_b128 v[202:205], v149 offset:3072
	ds_read_b128 v[206:209], v149 offset:4096
	ds_read_b128 v[210:213], v149 offset:5120
	ds_read_b128 v[214:217], v149 offset:6144
	ds_read_b128 v[238:241], v149 offset:7168
	global_load_lds_dwordx4 v[158:159], off
	v_lshl_add_u64 v[158:159], s[10:11], 0, v[134:135]
	s_add_i32 m0, s30, 0xe000
	s_nop 0
	global_load_lds_dwordx4 v[158:159], off
	s_waitcnt vmcnt(8)
	s_waitcnt lgkmcnt(0)
	s_barrier
	s_setprio 1
	s_waitcnt lgkmcnt(0)
	v_mfma_f32_16x16x32_bf16 v[124:127], v[138:141], v[190:193], v[124:127]
	v_mfma_f32_16x16x32_bf16 v[116:119], v[150:153], v[190:193], v[116:119]
	v_mfma_f32_16x16x32_bf16 v[108:111], v[138:141], v[198:201], v[108:111]
	v_mfma_f32_16x16x32_bf16 v[100:103], v[150:153], v[198:201], v[100:103]
	v_mfma_f32_16x16x32_bf16 v[92:95], v[138:141], v[206:209], v[92:95]
	v_mfma_f32_16x16x32_bf16 v[84:87], v[150:153], v[206:209], v[84:87]
	v_mfma_f32_16x16x32_bf16 v[76:79], v[138:141], v[214:217], v[76:79]
	v_mfma_f32_16x16x32_bf16 v[64:67], v[150:153], v[214:217], v[64:67]
	v_mfma_f32_16x16x32_bf16 v[124:127], v[142:145], v[194:197], v[124:127]
	v_mfma_f32_16x16x32_bf16 v[116:119], v[154:157], v[194:197], v[116:119]
	v_mfma_f32_16x16x32_bf16 v[108:111], v[142:145], v[202:205], v[108:111]
	v_mfma_f32_16x16x32_bf16 v[100:103], v[154:157], v[202:205], v[100:103]
	v_mfma_f32_16x16x32_bf16 v[92:95], v[142:145], v[210:213], v[92:95]
	v_mfma_f32_16x16x32_bf16 v[84:87], v[154:157], v[210:213], v[84:87]
	v_mfma_f32_16x16x32_bf16 v[76:79], v[142:145], v[238:241], v[76:79]
	v_mfma_f32_16x16x32_bf16 v[64:67], v[154:157], v[238:241], v[64:67]
	s_setprio 0
	s_setprio 1
	v_mfma_f32_16x16x32_bf16 v[120:123], v[174:177], v[190:193], v[120:123]
	v_mfma_f32_16x16x32_bf16 v[112:115], v[182:185], v[190:193], v[112:115]
	v_mfma_f32_16x16x32_bf16 v[104:107], v[174:177], v[198:201], v[104:107]
	v_mfma_f32_16x16x32_bf16 v[96:99], v[182:185], v[198:201], v[96:99]
	v_mfma_f32_16x16x32_bf16 v[88:91], v[174:177], v[206:209], v[88:91]
	v_mfma_f32_16x16x32_bf16 v[80:83], v[182:185], v[206:209], v[80:83]
	v_mfma_f32_16x16x32_bf16 v[72:75], v[174:177], v[214:217], v[72:75]
	v_mfma_f32_16x16x32_bf16 v[68:71], v[182:185], v[214:217], v[68:71]
	v_mfma_f32_16x16x32_bf16 v[120:123], v[178:181], v[194:197], v[120:123]
	v_mfma_f32_16x16x32_bf16 v[112:115], v[186:189], v[194:197], v[112:115]
	v_mfma_f32_16x16x32_bf16 v[104:107], v[178:181], v[202:205], v[104:107]
	v_mfma_f32_16x16x32_bf16 v[96:99], v[186:189], v[202:205], v[96:99]
	v_mfma_f32_16x16x32_bf16 v[88:91], v[178:181], v[210:213], v[88:91]
	v_mfma_f32_16x16x32_bf16 v[80:83], v[186:189], v[210:213], v[80:83]
	v_mfma_f32_16x16x32_bf16 v[72:75], v[178:181], v[238:241], v[72:75]
	v_mfma_f32_16x16x32_bf16 v[68:71], v[186:189], v[238:241], v[68:71]
	s_setprio 0
	s_barrier
	s_add_i32 s22, s22, s28
	v_lshl_add_u64 v[158:159], s[12:13], 0, v[160:161]
	s_mov_b32 m0, s22
	ds_read_b128 v[190:193], v149 offset:16384
	ds_read_b128 v[194:197], v149 offset:17408
	ds_read_b128 v[198:201], v149 offset:18432
	ds_read_b128 v[202:205], v149 offset:19456
	ds_read_b128 v[206:209], v149 offset:20480
	ds_read_b128 v[210:213], v149 offset:21504
	ds_read_b128 v[214:217], v149 offset:22528
	ds_read_b128 v[238:241], v149 offset:23552
	global_load_lds_dwordx4 v[158:159], off
	s_add_i32 m0, s22, 0x2000
	s_add_u32 s48, s12, 0x40000
	v_lshl_add_u64 v[162:163], s[12:13], 0, v[128:129]
	s_addc_u32 s49, s13, 0
	s_add_i32 s22, s50, s28
	global_load_lds_dwordx4 v[162:163], off
	v_lshl_add_u64 v[164:165], s[48:49], 0, v[160:161]
	s_mov_b32 m0, s22
	v_lshl_add_u64 v[166:167], s[14:15], 0, v[130:131]
	global_load_lds_dwordx4 v[164:165], off
	v_lshl_add_u64 v[164:165], s[48:49], 0, v[128:129]
	s_add_i32 m0, s22, 0x2000
	s_nop 0
	global_load_lds_dwordx4 v[164:165], off
	v_lshl_add_u64 v[164:165], s[14:15], 0, v[132:133]
	s_mov_b32 m0, s30
	s_nop 0
	global_load_lds_dwordx4 v[164:165], off
	s_mov_b32 m0, s31
	s_nop 0
	global_load_lds_dwordx4 v[166:167], off
	s_waitcnt vmcnt(8)
	s_waitcnt lgkmcnt(0)
	s_barrier
	s_setprio 1
	s_waitcnt lgkmcnt(0)
	v_mfma_f32_16x16x32_bf16 v[60:63], v[138:141], v[190:193], v[60:63]
	v_mfma_f32_16x16x32_bf16 v[48:51], v[150:153], v[190:193], v[48:51]
	v_mfma_f32_16x16x32_bf16 v[44:47], v[138:141], v[198:201], v[44:47]
	v_mfma_f32_16x16x32_bf16 v[32:35], v[150:153], v[198:201], v[32:35]
	v_mfma_f32_16x16x32_bf16 v[28:31], v[138:141], v[206:209], v[28:31]
	v_mfma_f32_16x16x32_bf16 v[16:19], v[150:153], v[206:209], v[16:19]
	v_mfma_f32_16x16x32_bf16 v[12:15], v[138:141], v[214:217], v[12:15]
	v_mfma_f32_16x16x32_bf16 v[0:3], v[150:153], v[214:217], v[0:3]
	v_mfma_f32_16x16x32_bf16 v[60:63], v[142:145], v[194:197], v[60:63]
	v_mfma_f32_16x16x32_bf16 v[48:51], v[154:157], v[194:197], v[48:51]
	v_mfma_f32_16x16x32_bf16 v[44:47], v[142:145], v[202:205], v[44:47]
	v_mfma_f32_16x16x32_bf16 v[32:35], v[154:157], v[202:205], v[32:35]
	v_mfma_f32_16x16x32_bf16 v[28:31], v[142:145], v[210:213], v[28:31]
	v_mfma_f32_16x16x32_bf16 v[16:19], v[154:157], v[210:213], v[16:19]
	v_mfma_f32_16x16x32_bf16 v[12:15], v[142:145], v[238:241], v[12:15]
	v_mfma_f32_16x16x32_bf16 v[0:3], v[154:157], v[238:241], v[0:3]
	s_setprio 0
	s_setprio 1
	v_mfma_f32_16x16x32_bf16 v[56:59], v[174:177], v[190:193], v[56:59]
	v_mfma_f32_16x16x32_bf16 v[52:55], v[182:185], v[190:193], v[52:55]
	v_mfma_f32_16x16x32_bf16 v[40:43], v[174:177], v[198:201], v[40:43]
	v_mfma_f32_16x16x32_bf16 v[36:39], v[182:185], v[198:201], v[36:39]
	v_mfma_f32_16x16x32_bf16 v[24:27], v[174:177], v[206:209], v[24:27]
	v_mfma_f32_16x16x32_bf16 v[20:23], v[182:185], v[206:209], v[20:23]
	v_mfma_f32_16x16x32_bf16 v[8:11], v[174:177], v[214:217], v[8:11]
	v_mfma_f32_16x16x32_bf16 v[4:7], v[182:185], v[214:217], v[4:7]
	v_mfma_f32_16x16x32_bf16 v[56:59], v[178:181], v[194:197], v[56:59]
	v_mfma_f32_16x16x32_bf16 v[52:55], v[186:189], v[194:197], v[52:55]
	v_mfma_f32_16x16x32_bf16 v[40:43], v[178:181], v[202:205], v[40:43]
	v_mfma_f32_16x16x32_bf16 v[36:39], v[186:189], v[202:205], v[36:39]
	v_mfma_f32_16x16x32_bf16 v[24:27], v[178:181], v[210:213], v[24:27]
	v_mfma_f32_16x16x32_bf16 v[20:23], v[186:189], v[210:213], v[20:23]
	v_mfma_f32_16x16x32_bf16 v[8:11], v[178:181], v[238:241], v[8:11]
	v_mfma_f32_16x16x32_bf16 v[4:7], v[186:189], v[238:241], v[4:7]
	s_setprio 0
	s_barrier
	s_add_i32 s22, 0, 0x18000
	s_add_i32 s48, 0, 0x1c000
	v_add_u32_e32 v154, s22, v147
	v_add_u32_e32 v168, s48, v147
	ds_read_b128 v[138:141], v154
	ds_read_b128 v[142:145], v154 offset:1024
	ds_read_b128 v[150:153], v154 offset:2048
	ds_read_b128 v[154:157], v154 offset:3072
	ds_read_b128 v[174:177], v168
	ds_read_b128 v[178:181], v168 offset:1024
	ds_read_b128 v[182:185], v168 offset:2048
	ds_read_b128 v[186:189], v168 offset:3072
	s_add_u32 s14, s14, 0x40000
	s_addc_u32 s15, s15, 0
	s_mov_b32 m0, s33
	v_lshl_add_u64 v[168:169], s[14:15], 0, v[132:133]
	ds_read_b128 v[190:193], v149 offset:32768
	ds_read_b128 v[194:197], v149 offset:33792
	ds_read_b128 v[198:201], v149 offset:34816
	ds_read_b128 v[202:205], v149 offset:35840
	ds_read_b128 v[206:209], v149 offset:36864
	ds_read_b128 v[210:213], v149 offset:37888
	ds_read_b128 v[214:217], v149 offset:38912
	ds_read_b128 v[238:241], v149 offset:39936
	global_load_lds_dwordx4 v[168:169], off
	v_lshl_add_u64 v[168:169], s[14:15], 0, v[130:131]
	s_mov_b32 m0, s34
	s_nop 0
	global_load_lds_dwordx4 v[168:169], off
	s_waitcnt vmcnt(8)
	s_waitcnt lgkmcnt(0)
	s_barrier
	s_setprio 1
	s_waitcnt lgkmcnt(0)
	v_mfma_f32_16x16x32_bf16 v[124:127], v[138:141], v[190:193], v[124:127]
	v_mfma_f32_16x16x32_bf16 v[116:119], v[150:153], v[190:193], v[116:119]
	v_mfma_f32_16x16x32_bf16 v[108:111], v[138:141], v[198:201], v[108:111]
	v_mfma_f32_16x16x32_bf16 v[100:103], v[150:153], v[198:201], v[100:103]
	v_mfma_f32_16x16x32_bf16 v[92:95], v[138:141], v[206:209], v[92:95]
	v_mfma_f32_16x16x32_bf16 v[84:87], v[150:153], v[206:209], v[84:87]
	v_mfma_f32_16x16x32_bf16 v[76:79], v[138:141], v[214:217], v[76:79]
	v_mfma_f32_16x16x32_bf16 v[64:67], v[150:153], v[214:217], v[64:67]
	v_mfma_f32_16x16x32_bf16 v[124:127], v[142:145], v[194:197], v[124:127]
	v_mfma_f32_16x16x32_bf16 v[116:119], v[154:157], v[194:197], v[116:119]
	v_mfma_f32_16x16x32_bf16 v[108:111], v[142:145], v[202:205], v[108:111]
	v_mfma_f32_16x16x32_bf16 v[100:103], v[154:157], v[202:205], v[100:103]
	v_mfma_f32_16x16x32_bf16 v[92:95], v[142:145], v[210:213], v[92:95]
	v_mfma_f32_16x16x32_bf16 v[84:87], v[154:157], v[210:213], v[84:87]
	v_mfma_f32_16x16x32_bf16 v[76:79], v[142:145], v[238:241], v[76:79]
	v_mfma_f32_16x16x32_bf16 v[64:67], v[154:157], v[238:241], v[64:67]
	s_setprio 0
	s_setprio 1
	v_mfma_f32_16x16x32_bf16 v[120:123], v[174:177], v[190:193], v[120:123]
	v_mfma_f32_16x16x32_bf16 v[112:115], v[182:185], v[190:193], v[112:115]
	v_mfma_f32_16x16x32_bf16 v[104:107], v[174:177], v[198:201], v[104:107]
	v_mfma_f32_16x16x32_bf16 v[96:99], v[182:185], v[198:201], v[96:99]
	v_mfma_f32_16x16x32_bf16 v[88:91], v[174:177], v[206:209], v[88:91]
	v_mfma_f32_16x16x32_bf16 v[80:83], v[182:185], v[206:209], v[80:83]
	v_mfma_f32_16x16x32_bf16 v[72:75], v[174:177], v[214:217], v[72:75]
	v_mfma_f32_16x16x32_bf16 v[68:71], v[182:185], v[214:217], v[68:71]
	v_mfma_f32_16x16x32_bf16 v[120:123], v[178:181], v[194:197], v[120:123]
	v_mfma_f32_16x16x32_bf16 v[112:115], v[186:189], v[194:197], v[112:115]
	v_mfma_f32_16x16x32_bf16 v[104:107], v[178:181], v[202:205], v[104:107]
	v_mfma_f32_16x16x32_bf16 v[96:99], v[186:189], v[202:205], v[96:99]
	v_mfma_f32_16x16x32_bf16 v[88:91], v[178:181], v[210:213], v[88:91]
	v_mfma_f32_16x16x32_bf16 v[80:83], v[186:189], v[210:213], v[80:83]
	v_mfma_f32_16x16x32_bf16 v[72:75], v[178:181], v[238:241], v[72:75]
	v_mfma_f32_16x16x32_bf16 v[68:71], v[186:189], v[238:241], v[68:71]
	s_setprio 0
	s_barrier
	s_add_i32 s14, s22, s28
	v_lshl_add_u64 v[158:159], v[158:159], 0, s[88:89]
	s_mov_b32 m0, s14
	ds_read_b128 v[190:193], v149 offset:49152
	ds_read_b128 v[194:197], v149 offset:50176
	ds_read_b128 v[198:201], v149 offset:51200
	ds_read_b128 v[202:205], v149 offset:52224
	ds_read_b128 v[206:209], v149 offset:53248
	ds_read_b128 v[210:213], v149 offset:54272
	ds_read_b128 v[214:217], v149 offset:55296
	ds_read_b128 v[238:241], v149 offset:56320
	global_load_lds_dwordx4 v[158:159], off
	s_add_i32 m0, s14, 0x2000
	s_add_u32 s12, s12, 0x40080
	v_lshl_add_u64 v[158:159], v[162:163], 0, s[88:89]
	s_addc_u32 s13, s13, 0
	s_add_i32 s14, s48, s28
	global_load_lds_dwordx4 v[158:159], off
	v_lshl_add_u64 v[158:159], s[12:13], 0, v[160:161]
	s_mov_b32 m0, s14
	s_nop 0
	global_load_lds_dwordx4 v[158:159], off
	v_lshl_add_u64 v[158:159], s[12:13], 0, v[128:129]
	s_add_i32 m0, s14, 0x2000
	s_nop 0
	global_load_lds_dwordx4 v[158:159], off
	v_lshl_add_u64 v[158:159], v[164:165], 0, s[88:89]
	s_mov_b32 m0, s35
	s_nop 0
	global_load_lds_dwordx4 v[158:159], off
	v_lshl_add_u64 v[158:159], v[166:167], 0, s[88:89]
	s_mov_b32 m0, s90
	s_nop 0
	global_load_lds_dwordx4 v[158:159], off
	s_waitcnt vmcnt(8)
	s_waitcnt lgkmcnt(0)
	s_barrier
	s_setprio 1
	s_waitcnt lgkmcnt(0)
	v_mfma_f32_16x16x32_bf16 v[60:63], v[138:141], v[190:193], v[60:63]
	v_mfma_f32_16x16x32_bf16 v[48:51], v[150:153], v[190:193], v[48:51]
	v_mfma_f32_16x16x32_bf16 v[44:47], v[138:141], v[198:201], v[44:47]
	v_mfma_f32_16x16x32_bf16 v[32:35], v[150:153], v[198:201], v[32:35]
	v_mfma_f32_16x16x32_bf16 v[28:31], v[138:141], v[206:209], v[28:31]
	v_mfma_f32_16x16x32_bf16 v[16:19], v[150:153], v[206:209], v[16:19]
	v_mfma_f32_16x16x32_bf16 v[12:15], v[138:141], v[214:217], v[12:15]
	v_mfma_f32_16x16x32_bf16 v[0:3], v[150:153], v[214:217], v[0:3]
	v_mfma_f32_16x16x32_bf16 v[60:63], v[142:145], v[194:197], v[60:63]
	v_mfma_f32_16x16x32_bf16 v[48:51], v[154:157], v[194:197], v[48:51]
	v_mfma_f32_16x16x32_bf16 v[44:47], v[142:145], v[202:205], v[44:47]
	v_mfma_f32_16x16x32_bf16 v[32:35], v[154:157], v[202:205], v[32:35]
	v_mfma_f32_16x16x32_bf16 v[28:31], v[142:145], v[210:213], v[28:31]
	v_mfma_f32_16x16x32_bf16 v[16:19], v[154:157], v[210:213], v[16:19]
	v_mfma_f32_16x16x32_bf16 v[12:15], v[142:145], v[238:241], v[12:15]
	v_mfma_f32_16x16x32_bf16 v[0:3], v[154:157], v[238:241], v[0:3]
	s_setprio 0
	s_setprio 1
	v_mfma_f32_16x16x32_bf16 v[56:59], v[174:177], v[190:193], v[56:59]
	v_mfma_f32_16x16x32_bf16 v[52:55], v[182:185], v[190:193], v[52:55]
	v_mfma_f32_16x16x32_bf16 v[40:43], v[174:177], v[198:201], v[40:43]
	v_mfma_f32_16x16x32_bf16 v[36:39], v[182:185], v[198:201], v[36:39]
	v_mfma_f32_16x16x32_bf16 v[24:27], v[174:177], v[206:209], v[24:27]
	v_mfma_f32_16x16x32_bf16 v[20:23], v[182:185], v[206:209], v[20:23]
	v_mfma_f32_16x16x32_bf16 v[8:11], v[174:177], v[214:217], v[8:11]
	v_mfma_f32_16x16x32_bf16 v[4:7], v[182:185], v[214:217], v[4:7]
	v_mfma_f32_16x16x32_bf16 v[56:59], v[178:181], v[194:197], v[56:59]
	v_mfma_f32_16x16x32_bf16 v[52:55], v[186:189], v[194:197], v[52:55]
	v_mfma_f32_16x16x32_bf16 v[40:43], v[178:181], v[202:205], v[40:43]
	v_mfma_f32_16x16x32_bf16 v[36:39], v[186:189], v[202:205], v[36:39]
	v_mfma_f32_16x16x32_bf16 v[24:27], v[178:181], v[210:213], v[24:27]
	v_mfma_f32_16x16x32_bf16 v[20:23], v[186:189], v[210:213], v[20:23]
	v_mfma_f32_16x16x32_bf16 v[8:11], v[178:181], v[238:241], v[8:11]
	v_mfma_f32_16x16x32_bf16 v[4:7], v[186:189], v[238:241], v[4:7]
	s_setprio 0
	s_barrier
	s_add_i32 s21, s21, 2
	s_add_u32 s96, s96, 0x100
	s_addc_u32 s97, s97, 0
	s_add_u32 s10, s10, 0x100
	s_addc_u32 s11, s11, 0
	s_cmp_gt_u32 s21, 13
	s_cbranch_scc0 .LBB0_212
	v_lshl_add_u32 v192, s8, 8, v146
	v_lshlrev_b32_e32 v192, 3, v192
	global_load_dwordx2 v[176:177], v192, s[4:5]
	global_load_dwordx2 v[178:179], v192, s[4:5] offset:128
	global_load_dwordx2 v[180:181], v192, s[4:5] offset:256
	global_load_dwordx2 v[182:183], v192, s[4:5] offset:384
	global_load_dwordx2 v[184:185], v192, s[4:5] offset:1024
	global_load_dwordx2 v[186:187], v192, s[4:5] offset:1152
	global_load_dwordx2 v[188:189], v192, s[4:5] offset:1280
	global_load_dwordx2 v[190:191], v192, s[4:5] offset:1408
	s_and_b64 vcc, exec, s[6:7]
	s_cbranch_vccz .LBB0_215
	s_barrier
.LBB0_215:
	v_lshl_or_b32 v142, s9, 7, v148
	v_lshl_add_u32 v138, s8, 8, v146
	v_ashrrev_i32_e32 v143, 31, v142
	v_mov_b64_e32 v[140:141], s[2:3]
	v_ashrrev_i32_e32 v139, 31, v138
	v_mad_i64_i32 v[144:145], s[8:9], v138, s16, v[140:141]
	v_lshlrev_b64 v[142:143], 1, v[142:143]
	v_lshl_add_u64 v[150:151], v[144:145], 0, v[142:143]
	v_lshl_add_u64 v[144:145], v[138:139], 3, s[4:5]
	v_pk_mul_f32 v[120:121], v[124:125], v[120:121]
	v_pk_mul_f32 v[122:123], v[126:127], v[122:123]
	v_pk_mul_f32 v[112:113], v[116:117], v[112:113]
	v_pk_mul_f32 v[114:115], v[118:119], v[114:115]
	v_pk_mul_f32 v[104:105], v[108:109], v[104:105]
	v_pk_mul_f32 v[106:107], v[110:111], v[106:107]
	v_pk_mul_f32 v[96:97], v[100:101], v[96:97]
	v_pk_mul_f32 v[98:99], v[102:103], v[98:99]
	v_pk_mul_f32 v[88:89], v[92:93], v[88:89]
	v_pk_mul_f32 v[90:91], v[94:95], v[90:91]
	v_pk_mul_f32 v[80:81], v[84:85], v[80:81]
	v_pk_mul_f32 v[82:83], v[86:87], v[82:83]
	v_pk_mul_f32 v[72:73], v[76:77], v[72:73]
	v_pk_mul_f32 v[74:75], v[78:79], v[74:75]
	v_pk_mul_f32 v[70:71], v[66:67], v[70:71]
	v_pk_mul_f32 v[56:57], v[60:61], v[56:57]
	v_pk_mul_f32 v[58:59], v[62:63], v[58:59]
	v_pk_mul_f32 v[54:55], v[50:51], v[54:55]
	v_pk_mul_f32 v[40:41], v[44:45], v[40:41]
	v_pk_mul_f32 v[42:43], v[46:47], v[42:43]
	v_pk_mul_f32 v[38:39], v[34:35], v[38:39]
	v_pk_mul_f32 v[24:25], v[28:29], v[24:25]
	v_pk_mul_f32 v[26:27], v[30:31], v[26:27]
	v_pk_mul_f32 v[22:23], v[18:19], v[22:23]
	v_pk_mul_f32 v[8:9], v[12:13], v[8:9]
	v_pk_mul_f32 v[10:11], v[14:15], v[10:11]
	v_pk_mul_f32 v[6:7], v[2:3], v[6:7]
	s_andn2_b64 vcc, exec, s[38:39]
	s_waitcnt vmcnt(0) lgkmcnt(0)
	v_mov_b64_e32 v[152:153], v[176:177]
	v_ffbh_u32_e32 v139, v153
	v_min_u32_e32 v139, 32, v139
	v_lshlrev_b64 v[152:153], v139, v[152:153]
	v_min_u32_e32 v152, 1, v152
	v_or_b32_e32 v152, v153, v152
	v_cvt_f32_u32_e32 v152, v152
	v_sub_u32_e32 v139, 32, v139
	v_ldexp_f32 v139, v152, v139
	v_mul_f32_e32 v139, 0x35800000, v139
	v_fmamk_f32 v139, v139, 0x3a800000, v219
	v_rsq_f32_e32 v139, v139
	s_nop 0
	v_mul_f32_e32 v152, 0xbfb8aa3b, v139
	v_pk_mul_f32 v[156:157], v[124:125], v[152:153] op_sel_hi:[1,0]
	v_mul_f32_e32 v154, v139, v139
	v_exp_f32_e32 v156, v156
	v_exp_f32_e32 v157, v157
	s_nop 0
	v_pk_add_f32 v[156:157], v[156:157], 1.0 op_sel_hi:[1,0]
	s_nop 0
	v_rcp_f32_e32 v156, v156
	v_rcp_f32_e32 v157, v157
	s_nop 0
	v_pk_mul_f32 v[124:125], v[154:155], v[156:157] op_sel_hi:[0,1]
	v_pk_mul_f32 v[120:121], v[120:121], v[124:125]
	v_pk_mul_f32 v[124:125], v[126:127], v[152:153] op_sel_hi:[1,0]
	s_nop 0
	v_exp_f32_e32 v124, v124
	v_exp_f32_e32 v125, v125
	s_nop 0
	v_pk_add_f32 v[124:125], v[124:125], 1.0 op_sel_hi:[1,0]
	s_nop 0
	v_rcp_f32_e32 v124, v124
	v_rcp_f32_e32 v125, v125
	s_nop 0
	v_pk_mul_f32 v[124:125], v[154:155], v[124:125] op_sel_hi:[0,1]
	v_pk_mul_f32 v[122:123], v[122:123], v[124:125]
	v_pk_mul_f32 v[124:125], v[116:117], v[152:153] op_sel_hi:[1,0]
	s_nop 0
	v_exp_f32_e32 v124, v124
	v_exp_f32_e32 v125, v125
	s_nop 0
	v_pk_add_f32 v[124:125], v[124:125], 1.0 op_sel_hi:[1,0]
	s_nop 0
	v_rcp_f32_e32 v124, v124
	v_rcp_f32_e32 v125, v125
	s_nop 0
	v_pk_mul_f32 v[116:117], v[154:155], v[124:125] op_sel_hi:[0,1]
	v_pk_mul_f32 v[116:117], v[112:113], v[116:117]
	v_pk_mul_f32 v[112:113], v[118:119], v[152:153] op_sel_hi:[1,0]
	s_nop 0
	v_exp_f32_e32 v112, v112
	v_exp_f32_e32 v113, v113
	s_nop 0
	v_pk_add_f32 v[112:113], v[112:113], 1.0 op_sel_hi:[1,0]
	s_nop 0
	v_rcp_f32_e32 v112, v112
	v_rcp_f32_e32 v113, v113
	s_nop 0
	v_pk_mul_f32 v[112:113], v[154:155], v[112:113] op_sel_hi:[0,1]
	v_pk_mul_f32 v[118:119], v[114:115], v[112:113]
	v_cvt_pk_bf16_f32 v112, v120, v121
	v_cvt_pk_bf16_f32 v113, v122, v123
	v_cvt_pk_bf16_f32 v114, v116, v117
	v_cvt_pk_bf16_f32 v115, v118, v119
	global_store_dwordx4 v[150:151], v[112:115], off
	s_nop 1
	v_or_b32_e32 v114, 16, v138
	v_ashrrev_i32_e32 v115, 31, v114
	v_mad_i64_i32 v[112:113], s[8:9], v114, s16, v[140:141]
	v_lshl_add_u64 v[114:115], v[114:115], 3, s[4:5]
	s_nop 1
	v_mov_b64_e32 v[114:115], v[178:179]
	v_lshl_add_u64 v[112:113], v[112:113], 0, v[142:143]
	v_ffbh_u32_e32 v116, v115
	v_min_u32_e32 v116, 32, v116
	v_lshlrev_b64 v[114:115], v116, v[114:115]
	v_min_u32_e32 v114, 1, v114
	v_or_b32_e32 v114, v115, v114
	v_cvt_f32_u32_e32 v114, v114
	v_sub_u32_e32 v115, 32, v116
	v_ldexp_f32 v114, v114, v115
	v_mul_f32_e32 v114, 0x35800000, v114
	v_fmamk_f32 v114, v114, 0x3a800000, v219
	v_rsq_f32_e32 v115, v114
	s_nop 0
	v_mul_f32_e32 v114, 0xbfb8aa3b, v115
	v_pk_mul_f32 v[118:119], v[108:109], v[114:115] op_sel_hi:[1,0]
	v_mul_f32_e32 v116, v115, v115
	v_exp_f32_e32 v118, v118
	v_exp_f32_e32 v119, v119
	s_nop 0
	v_pk_add_f32 v[118:119], v[118:119], 1.0 op_sel_hi:[1,0]
	s_nop 0
	v_rcp_f32_e32 v118, v118
	v_rcp_f32_e32 v119, v119
	s_nop 0
	v_pk_mul_f32 v[108:109], v[116:117], v[118:119] op_sel_hi:[0,1]
	v_pk_mul_f32 v[104:105], v[104:105], v[108:109]
	v_pk_mul_f32 v[108:109], v[110:111], v[114:115] op_sel_hi:[1,0]
	s_nop 0
	v_exp_f32_e32 v108, v108
	v_exp_f32_e32 v109, v109
	s_nop 0
	v_pk_add_f32 v[108:109], v[108:109], 1.0 op_sel_hi:[1,0]
	s_nop 0
	v_rcp_f32_e32 v108, v108
	v_rcp_f32_e32 v109, v109
	s_nop 0
	v_pk_mul_f32 v[108:109], v[116:117], v[108:109] op_sel_hi:[0,1]
	v_pk_mul_f32 v[106:107], v[106:107], v[108:109]
	v_pk_mul_f32 v[108:109], v[100:101], v[114:115] op_sel_hi:[1,0]
	s_nop 0
	v_exp_f32_e32 v108, v108
	v_exp_f32_e32 v109, v109
	s_nop 0
	v_pk_add_f32 v[108:109], v[108:109], 1.0 op_sel_hi:[1,0]
	s_nop 0
	v_rcp_f32_e32 v108, v108
	v_rcp_f32_e32 v109, v109
	s_nop 0
	v_pk_mul_f32 v[100:101], v[116:117], v[108:109] op_sel_hi:[0,1]
	v_pk_mul_f32 v[100:101], v[96:97], v[100:101]
	v_pk_mul_f32 v[96:97], v[102:103], v[114:115] op_sel_hi:[1,0]
	s_nop 0
	v_exp_f32_e32 v96, v96
	v_exp_f32_e32 v97, v97
	s_nop 0
	v_pk_add_f32 v[96:97], v[96:97], 1.0 op_sel_hi:[1,0]
	s_nop 0
	v_rcp_f32_e32 v96, v96
	v_rcp_f32_e32 v97, v97
	s_nop 0
	v_pk_mul_f32 v[96:97], v[116:117], v[96:97] op_sel_hi:[0,1]
	v_pk_mul_f32 v[102:103], v[98:99], v[96:97]
	v_cvt_pk_bf16_f32 v96, v104, v105
	v_cvt_pk_bf16_f32 v97, v106, v107
	v_cvt_pk_bf16_f32 v98, v100, v101
	v_cvt_pk_bf16_f32 v99, v102, v103
	global_store_dwordx4 v[112:113], v[96:99], off
	s_nop 1
	v_or_b32_e32 v98, 32, v138
	v_ashrrev_i32_e32 v99, 31, v98
	v_mad_i64_i32 v[96:97], s[8:9], v98, s16, v[140:141]
	v_lshl_add_u64 v[98:99], v[98:99], 3, s[4:5]
	s_nop 1
	v_mov_b64_e32 v[98:99], v[180:181]
	v_lshl_add_u64 v[96:97], v[96:97], 0, v[142:143]
	v_ffbh_u32_e32 v100, v99
	v_min_u32_e32 v100, 32, v100
	v_lshlrev_b64 v[98:99], v100, v[98:99]
	v_min_u32_e32 v98, 1, v98
	v_or_b32_e32 v98, v99, v98
	v_cvt_f32_u32_e32 v98, v98
	v_sub_u32_e32 v99, 32, v100
	v_ldexp_f32 v98, v98, v99
	v_mul_f32_e32 v98, 0x35800000, v98
	v_fmamk_f32 v98, v98, 0x3a800000, v219
	v_rsq_f32_e32 v99, v98
	s_nop 0
	v_mul_f32_e32 v98, 0xbfb8aa3b, v99
	v_pk_mul_f32 v[102:103], v[92:93], v[98:99] op_sel_hi:[1,0]
	v_mul_f32_e32 v100, v99, v99
	v_exp_f32_e32 v102, v102
	v_exp_f32_e32 v103, v103
	s_nop 0
	v_pk_add_f32 v[102:103], v[102:103], 1.0 op_sel_hi:[1,0]
	s_nop 0
	v_rcp_f32_e32 v102, v102
	v_rcp_f32_e32 v103, v103
	s_nop 0
	v_pk_mul_f32 v[92:93], v[100:101], v[102:103] op_sel_hi:[0,1]
	v_pk_mul_f32 v[88:89], v[88:89], v[92:93]
	v_pk_mul_f32 v[92:93], v[94:95], v[98:99] op_sel_hi:[1,0]
	s_nop 0
	v_exp_f32_e32 v92, v92
	v_exp_f32_e32 v93, v93
	s_nop 0
	v_pk_add_f32 v[92:93], v[92:93], 1.0 op_sel_hi:[1,0]
	s_nop 0
	v_rcp_f32_e32 v92, v92
	v_rcp_f32_e32 v93, v93
	s_nop 0
	v_pk_mul_f32 v[92:93], v[100:101], v[92:93] op_sel_hi:[0,1]
	v_pk_mul_f32 v[90:91], v[90:91], v[92:93]
	v_pk_mul_f32 v[92:93], v[84:85], v[98:99] op_sel_hi:[1,0]
	s_nop 0
	v_exp_f32_e32 v92, v92
	v_exp_f32_e32 v93, v93
	s_nop 0
	v_pk_add_f32 v[92:93], v[92:93], 1.0 op_sel_hi:[1,0]
	s_nop 0
	v_rcp_f32_e32 v92, v92
	v_rcp_f32_e32 v93, v93
	s_nop 0
	v_pk_mul_f32 v[84:85], v[100:101], v[92:93] op_sel_hi:[0,1]
	v_pk_mul_f32 v[84:85], v[80:81], v[84:85]
	v_pk_mul_f32 v[80:81], v[86:87], v[98:99] op_sel_hi:[1,0]
	s_nop 0
	v_exp_f32_e32 v80, v80
	v_exp_f32_e32 v81, v81
	s_nop 0
	v_pk_add_f32 v[80:81], v[80:81], 1.0 op_sel_hi:[1,0]
	s_nop 0
	v_rcp_f32_e32 v80, v80
	v_rcp_f32_e32 v81, v81
	s_nop 0
	v_pk_mul_f32 v[80:81], v[100:101], v[80:81] op_sel_hi:[0,1]
	v_pk_mul_f32 v[86:87], v[82:83], v[80:81]
	v_cvt_pk_bf16_f32 v80, v88, v89
	v_cvt_pk_bf16_f32 v81, v90, v91
	v_cvt_pk_bf16_f32 v82, v84, v85
	v_cvt_pk_bf16_f32 v83, v86, v87
	global_store_dwordx4 v[96:97], v[80:83], off
	s_nop 1
	v_or_b32_e32 v82, 48, v138
	v_ashrrev_i32_e32 v83, 31, v82
	v_mad_i64_i32 v[80:81], s[8:9], v82, s16, v[140:141]
	v_lshl_add_u64 v[82:83], v[82:83], 3, s[4:5]
	s_nop 1
	v_mov_b64_e32 v[82:83], v[182:183]
	v_lshl_add_u64 v[80:81], v[80:81], 0, v[142:143]
	v_ffbh_u32_e32 v84, v83
	v_min_u32_e32 v84, 32, v84
	v_lshlrev_b64 v[82:83], v84, v[82:83]
	v_min_u32_e32 v82, 1, v82
	v_or_b32_e32 v82, v83, v82
	v_cvt_f32_u32_e32 v82, v82
	v_sub_u32_e32 v83, 32, v84
	v_ldexp_f32 v82, v82, v83
	v_mul_f32_e32 v82, 0x35800000, v82
	v_fmamk_f32 v82, v82, 0x3a800000, v219
	v_rsq_f32_e32 v82, v82
	s_nop 0
	v_mul_f32_e32 v84, 0xbfb8aa3b, v82
	v_pk_mul_f32 v[86:87], v[76:77], v[84:85] op_sel_hi:[1,0]
	v_mul_f32_e32 v82, v82, v82
	v_exp_f32_e32 v86, v86
	v_exp_f32_e32 v87, v87
	s_nop 0
	v_pk_add_f32 v[86:87], v[86:87], 1.0 op_sel_hi:[1,0]
	s_nop 0
	v_rcp_f32_e32 v86, v86
	v_rcp_f32_e32 v87, v87
	s_nop 0
	v_pk_mul_f32 v[76:77], v[82:83], v[86:87] op_sel_hi:[0,1]
	v_pk_mul_f32 v[72:73], v[72:73], v[76:77]
	v_pk_mul_f32 v[76:77], v[78:79], v[84:85] op_sel_hi:[1,0]
	s_nop 0
	v_exp_f32_e32 v76, v76
	v_exp_f32_e32 v77, v77
	s_nop 0
	v_pk_add_f32 v[76:77], v[76:77], 1.0 op_sel_hi:[1,0]
	s_nop 0
	v_rcp_f32_e32 v76, v76
	v_rcp_f32_e32 v77, v77
	s_nop 0
	v_pk_mul_f32 v[76:77], v[82:83], v[76:77] op_sel_hi:[0,1]
	v_pk_mul_f32 v[74:75], v[74:75], v[76:77]
	v_pk_mul_f32 v[76:77], v[64:65], v[84:85] op_sel_hi:[1,0]
	v_pk_mul_f32 v[64:65], v[64:65], v[68:69]
	v_exp_f32_e32 v76, v76
	v_exp_f32_e32 v77, v77
	s_nop 0
	v_pk_add_f32 v[76:77], v[76:77], 1.0 op_sel_hi:[1,0]
	s_nop 0
	v_rcp_f32_e32 v76, v76
	v_rcp_f32_e32 v77, v77
	s_nop 0
	v_pk_mul_f32 v[68:69], v[82:83], v[76:77] op_sel_hi:[0,1]
	v_pk_mul_f32 v[68:69], v[64:65], v[68:69]
	v_pk_mul_f32 v[64:65], v[66:67], v[84:85] op_sel_hi:[1,0]
	v_cvt_pk_bf16_f32 v66, v68, v69
	v_exp_f32_e32 v64, v64
	v_exp_f32_e32 v65, v65
	s_nop 0
	v_pk_add_f32 v[64:65], v[64:65], 1.0 op_sel_hi:[1,0]
	s_nop 0
	v_rcp_f32_e32 v64, v64
	v_rcp_f32_e32 v65, v65
	s_nop 0
	v_pk_mul_f32 v[64:65], v[82:83], v[64:65] op_sel_hi:[0,1]
	v_pk_mul_f32 v[70:71], v[70:71], v[64:65]
	v_cvt_pk_bf16_f32 v64, v72, v73
	v_cvt_pk_bf16_f32 v65, v74, v75
	v_cvt_pk_bf16_f32 v67, v70, v71
	global_store_dwordx4 v[80:81], v[64:67], off
	s_nop 1
	v_mov_b64_e32 v[66:67], v[184:185]
	v_ffbh_u32_e32 v68, v67
	v_min_u32_e32 v68, 32, v68
	v_lshlrev_b64 v[66:67], v68, v[66:67]
	v_min_u32_e32 v66, 1, v66
	v_or_b32_e32 v66, v67, v66
	v_cvt_f32_u32_e32 v66, v66
	v_sub_u32_e32 v67, 32, v68
	v_add_u32_e32 v64, 0x80, v138
	v_mad_i64_i32 v[64:65], s[8:9], v64, s16, v[140:141]
	v_ldexp_f32 v66, v66, v67
	v_mul_f32_e32 v66, 0x35800000, v66
	v_fmamk_f32 v66, v66, 0x3a800000, v219
	v_rsq_f32_e32 v66, v66
	v_lshl_add_u64 v[64:65], v[64:65], 0, v[142:143]
	v_mul_f32_e32 v68, 0xbfb8aa3b, v66
	v_pk_mul_f32 v[70:71], v[60:61], v[68:69] op_sel_hi:[1,0]
	v_mul_f32_e32 v66, v66, v66
	v_exp_f32_e32 v70, v70
	v_exp_f32_e32 v71, v71
	s_nop 0
	v_pk_add_f32 v[70:71], v[70:71], 1.0 op_sel_hi:[1,0]
	s_nop 0
	v_rcp_f32_e32 v70, v70
	v_rcp_f32_e32 v71, v71
	s_nop 0
	v_pk_mul_f32 v[60:61], v[66:67], v[70:71] op_sel_hi:[0,1]
	v_pk_mul_f32 v[56:57], v[56:57], v[60:61]
	v_pk_mul_f32 v[60:61], v[62:63], v[68:69] op_sel_hi:[1,0]
	s_nop 0
	v_exp_f32_e32 v60, v60
	v_exp_f32_e32 v61, v61
	s_nop 0
	v_pk_add_f32 v[60:61], v[60:61], 1.0 op_sel_hi:[1,0]
	s_nop 0
	v_rcp_f32_e32 v60, v60
	v_rcp_f32_e32 v61, v61
	s_nop 0
	v_pk_mul_f32 v[60:61], v[66:67], v[60:61] op_sel_hi:[0,1]
	v_pk_mul_f32 v[58:59], v[58:59], v[60:61]
	v_pk_mul_f32 v[60:61], v[48:49], v[68:69] op_sel_hi:[1,0]
	v_pk_mul_f32 v[48:49], v[48:49], v[52:53]
	v_exp_f32_e32 v60, v60
	v_exp_f32_e32 v61, v61
	s_nop 0
	v_pk_add_f32 v[60:61], v[60:61], 1.0 op_sel_hi:[1,0]
	s_nop 0
	v_rcp_f32_e32 v60, v60
	v_rcp_f32_e32 v61, v61
	s_nop 0
	v_pk_mul_f32 v[52:53], v[66:67], v[60:61] op_sel_hi:[0,1]
	v_pk_mul_f32 v[52:53], v[48:49], v[52:53]
	v_pk_mul_f32 v[48:49], v[50:51], v[68:69] op_sel_hi:[1,0]
	v_cvt_pk_bf16_f32 v50, v52, v53
	v_exp_f32_e32 v48, v48
	v_exp_f32_e32 v49, v49
	s_nop 0
	v_pk_add_f32 v[48:49], v[48:49], 1.0 op_sel_hi:[1,0]
	s_nop 0
	v_rcp_f32_e32 v48, v48
	v_rcp_f32_e32 v49, v49
	s_nop 0
	v_pk_mul_f32 v[48:49], v[66:67], v[48:49] op_sel_hi:[0,1]
	v_pk_mul_f32 v[54:55], v[54:55], v[48:49]
	v_cvt_pk_bf16_f32 v48, v56, v57
	v_cvt_pk_bf16_f32 v49, v58, v59
	v_cvt_pk_bf16_f32 v51, v54, v55
	global_store_dwordx4 v[64:65], v[48:51], off
	s_nop 1
	v_mov_b64_e32 v[50:51], v[186:187]
	v_ffbh_u32_e32 v52, v51
	v_min_u32_e32 v52, 32, v52
	v_lshlrev_b64 v[50:51], v52, v[50:51]
	v_min_u32_e32 v50, 1, v50
	v_or_b32_e32 v50, v51, v50
	v_cvt_f32_u32_e32 v50, v50
	v_sub_u32_e32 v51, 32, v52
	v_add_u32_e32 v48, 0x90, v138
	v_mad_i64_i32 v[48:49], s[8:9], v48, s16, v[140:141]
	v_ldexp_f32 v50, v50, v51
	v_mul_f32_e32 v50, 0x35800000, v50
	v_fmamk_f32 v50, v50, 0x3a800000, v219
	v_rsq_f32_e32 v50, v50
	v_lshl_add_u64 v[48:49], v[48:49], 0, v[142:143]
	v_mul_f32_e32 v52, 0xbfb8aa3b, v50
	v_pk_mul_f32 v[54:55], v[44:45], v[52:53] op_sel_hi:[1,0]
	v_mul_f32_e32 v50, v50, v50
	v_exp_f32_e32 v54, v54
	v_exp_f32_e32 v55, v55
	s_nop 0
	v_pk_add_f32 v[54:55], v[54:55], 1.0 op_sel_hi:[1,0]
	s_nop 0
	v_rcp_f32_e32 v54, v54
	v_rcp_f32_e32 v55, v55
	s_nop 0
	v_pk_mul_f32 v[44:45], v[50:51], v[54:55] op_sel_hi:[0,1]
	v_pk_mul_f32 v[40:41], v[40:41], v[44:45]
	v_pk_mul_f32 v[44:45], v[46:47], v[52:53] op_sel_hi:[1,0]
	s_nop 0
	v_exp_f32_e32 v44, v44
	v_exp_f32_e32 v45, v45
	s_nop 0
	v_pk_add_f32 v[44:45], v[44:45], 1.0 op_sel_hi:[1,0]
	s_nop 0
	v_rcp_f32_e32 v44, v44
	v_rcp_f32_e32 v45, v45
	s_nop 0
	v_pk_mul_f32 v[44:45], v[50:51], v[44:45] op_sel_hi:[0,1]
	v_pk_mul_f32 v[42:43], v[42:43], v[44:45]
	v_pk_mul_f32 v[44:45], v[32:33], v[52:53] op_sel_hi:[1,0]
	v_pk_mul_f32 v[32:33], v[32:33], v[36:37]
	v_exp_f32_e32 v44, v44
	v_exp_f32_e32 v45, v45
	s_nop 0
	v_pk_add_f32 v[44:45], v[44:45], 1.0 op_sel_hi:[1,0]
	s_nop 0
	v_rcp_f32_e32 v44, v44
	v_rcp_f32_e32 v45, v45
	s_nop 0
	v_pk_mul_f32 v[36:37], v[50:51], v[44:45] op_sel_hi:[0,1]
	v_pk_mul_f32 v[36:37], v[32:33], v[36:37]
	v_pk_mul_f32 v[32:33], v[34:35], v[52:53] op_sel_hi:[1,0]
	v_cvt_pk_bf16_f32 v34, v36, v37
	v_exp_f32_e32 v32, v32
	v_exp_f32_e32 v33, v33
	s_nop 0
	v_pk_add_f32 v[32:33], v[32:33], 1.0 op_sel_hi:[1,0]
	s_nop 0
	v_rcp_f32_e32 v32, v32
	v_rcp_f32_e32 v33, v33
	s_nop 0
	v_pk_mul_f32 v[32:33], v[50:51], v[32:33] op_sel_hi:[0,1]
	v_pk_mul_f32 v[38:39], v[38:39], v[32:33]
	v_cvt_pk_bf16_f32 v32, v40, v41
	v_cvt_pk_bf16_f32 v33, v42, v43
	v_cvt_pk_bf16_f32 v35, v38, v39
	global_store_dwordx4 v[48:49], v[32:35], off
	s_nop 1
	v_mov_b64_e32 v[34:35], v[188:189]
	v_ffbh_u32_e32 v36, v35
	v_min_u32_e32 v36, 32, v36
	v_lshlrev_b64 v[34:35], v36, v[34:35]
	v_min_u32_e32 v34, 1, v34
	v_or_b32_e32 v34, v35, v34
	v_cvt_f32_u32_e32 v34, v34
	v_sub_u32_e32 v35, 32, v36
	v_add_u32_e32 v32, 0xa0, v138
	v_mad_i64_i32 v[32:33], s[8:9], v32, s16, v[140:141]
	v_ldexp_f32 v34, v34, v35
	v_mul_f32_e32 v34, 0x35800000, v34
	v_fmamk_f32 v34, v34, 0x3a800000, v219
	v_rsq_f32_e32 v34, v34
	v_lshl_add_u64 v[32:33], v[32:33], 0, v[142:143]
	v_mul_f32_e32 v36, 0xbfb8aa3b, v34
	v_pk_mul_f32 v[38:39], v[28:29], v[36:37] op_sel_hi:[1,0]
	v_mul_f32_e32 v34, v34, v34
	v_exp_f32_e32 v38, v38
	v_exp_f32_e32 v39, v39
	s_nop 0
	v_pk_add_f32 v[38:39], v[38:39], 1.0 op_sel_hi:[1,0]
	s_nop 0
	v_rcp_f32_e32 v38, v38
	v_rcp_f32_e32 v39, v39
	s_nop 0
	v_pk_mul_f32 v[28:29], v[34:35], v[38:39] op_sel_hi:[0,1]
	v_pk_mul_f32 v[24:25], v[24:25], v[28:29]
	v_pk_mul_f32 v[28:29], v[30:31], v[36:37] op_sel_hi:[1,0]
	s_nop 0
	v_exp_f32_e32 v28, v28
	v_exp_f32_e32 v29, v29
	s_nop 0
	v_pk_add_f32 v[28:29], v[28:29], 1.0 op_sel_hi:[1,0]
	s_nop 0
	v_rcp_f32_e32 v28, v28
	v_rcp_f32_e32 v29, v29
	s_nop 0
	v_pk_mul_f32 v[28:29], v[34:35], v[28:29] op_sel_hi:[0,1]
	v_pk_mul_f32 v[26:27], v[26:27], v[28:29]
	v_pk_mul_f32 v[28:29], v[16:17], v[36:37] op_sel_hi:[1,0]
	v_pk_mul_f32 v[16:17], v[16:17], v[20:21]
	v_exp_f32_e32 v28, v28
	v_exp_f32_e32 v29, v29
	s_nop 0
	v_pk_add_f32 v[28:29], v[28:29], 1.0 op_sel_hi:[1,0]
	s_nop 0
	v_rcp_f32_e32 v28, v28
	v_rcp_f32_e32 v29, v29
	s_nop 0
	v_pk_mul_f32 v[20:21], v[34:35], v[28:29] op_sel_hi:[0,1]
	v_pk_mul_f32 v[20:21], v[16:17], v[20:21]
	v_pk_mul_f32 v[16:17], v[18:19], v[36:37] op_sel_hi:[1,0]
	v_cvt_pk_bf16_f32 v18, v20, v21
	v_exp_f32_e32 v16, v16
	v_exp_f32_e32 v17, v17
	s_nop 0
	v_pk_add_f32 v[16:17], v[16:17], 1.0 op_sel_hi:[1,0]
	s_nop 0
	v_rcp_f32_e32 v16, v16
	v_rcp_f32_e32 v17, v17
	s_nop 0
	v_pk_mul_f32 v[16:17], v[34:35], v[16:17] op_sel_hi:[0,1]
	v_pk_mul_f32 v[22:23], v[22:23], v[16:17]
	v_cvt_pk_bf16_f32 v16, v24, v25
	v_cvt_pk_bf16_f32 v17, v26, v27
	v_cvt_pk_bf16_f32 v19, v22, v23
	global_store_dwordx4 v[32:33], v[16:19], off
	s_nop 1
	v_mov_b64_e32 v[18:19], v[190:191]
	v_ffbh_u32_e32 v20, v19
	v_min_u32_e32 v20, 32, v20
	v_lshlrev_b64 v[18:19], v20, v[18:19]
	v_min_u32_e32 v18, 1, v18
	v_or_b32_e32 v18, v19, v18
	v_cvt_f32_u32_e32 v18, v18
	v_sub_u32_e32 v19, 32, v20
	v_add_u32_e32 v16, 0xb0, v138
	v_mad_i64_i32 v[16:17], s[8:9], v16, s16, v[140:141]
	v_ldexp_f32 v18, v18, v19
	v_mul_f32_e32 v18, 0x35800000, v18
	v_fmamk_f32 v18, v18, 0x3a800000, v219
	v_rsq_f32_e32 v18, v18
	v_lshl_add_u64 v[16:17], v[16:17], 0, v[142:143]
	s_mov_b64 s[8:9], -1
	v_mul_f32_e32 v20, 0xbfb8aa3b, v18
	v_pk_mul_f32 v[22:23], v[12:13], v[20:21] op_sel_hi:[1,0]
	v_mul_f32_e32 v18, v18, v18
	v_exp_f32_e32 v22, v22
	v_exp_f32_e32 v23, v23
	s_nop 0
	v_pk_add_f32 v[22:23], v[22:23], 1.0 op_sel_hi:[1,0]
	s_nop 0
	v_rcp_f32_e32 v22, v22
	v_rcp_f32_e32 v23, v23
	s_nop 0
	v_pk_mul_f32 v[12:13], v[18:19], v[22:23] op_sel_hi:[0,1]
	v_pk_mul_f32 v[8:9], v[8:9], v[12:13]
	v_pk_mul_f32 v[12:13], v[14:15], v[20:21] op_sel_hi:[1,0]
	s_nop 0
	v_exp_f32_e32 v12, v12
	v_exp_f32_e32 v13, v13
	s_nop 0
	v_pk_add_f32 v[12:13], v[12:13], 1.0 op_sel_hi:[1,0]
	s_nop 0
	v_rcp_f32_e32 v12, v12
	v_rcp_f32_e32 v13, v13
	s_nop 0
	v_pk_mul_f32 v[12:13], v[18:19], v[12:13] op_sel_hi:[0,1]
	v_pk_mul_f32 v[10:11], v[10:11], v[12:13]
	v_pk_mul_f32 v[12:13], v[0:1], v[20:21] op_sel_hi:[1,0]
	v_pk_mul_f32 v[0:1], v[0:1], v[4:5]
	v_exp_f32_e32 v12, v12
	v_exp_f32_e32 v13, v13
	s_nop 0
	v_pk_add_f32 v[12:13], v[12:13], 1.0 op_sel_hi:[1,0]
	s_nop 0
	v_rcp_f32_e32 v12, v12
	v_rcp_f32_e32 v13, v13
	s_nop 0
	v_pk_mul_f32 v[4:5], v[18:19], v[12:13] op_sel_hi:[0,1]
	v_pk_mul_f32 v[4:5], v[0:1], v[4:5]
	v_pk_mul_f32 v[0:1], v[2:3], v[20:21] op_sel_hi:[1,0]
	v_cvt_pk_bf16_f32 v2, v4, v5
	v_exp_f32_e32 v0, v0
	v_exp_f32_e32 v1, v1
	s_nop 0
	v_pk_add_f32 v[0:1], v[0:1], 1.0 op_sel_hi:[1,0]
	s_nop 0
	v_rcp_f32_e32 v0, v0
	v_rcp_f32_e32 v1, v1
	s_nop 0
	v_pk_mul_f32 v[0:1], v[18:19], v[0:1] op_sel_hi:[0,1]
	v_pk_mul_f32 v[6:7], v[6:7], v[0:1]
	v_cvt_pk_bf16_f32 v0, v8, v9
	v_cvt_pk_bf16_f32 v1, v10, v11
	v_cvt_pk_bf16_f32 v3, v6, v7
	global_store_dwordx4 v[16:17], v[0:3], off
	s_cbranch_vccnz .LBB0_208
	s_andn2_b64 vcc, exec, s[0:1]
	s_cbranch_vccnz .LBB0_207
	s_barrier
	s_branch .LBB0_207

.LBB0_399:
	s_add_u32 s8, s0, 0xfffc0080
	s_addc_u32 s9, s1, -1
	s_add_i32 s22, 0, 0x10000
	s_cmp_eq_u32 s21, 12
	s_cselect_b32 s11, s7, s9
	s_cselect_b32 s10, s19, s8
	s_cselect_b32 s9, s20, s91
	s_cselect_b32 s8, s33, s90
	s_add_i32 s48, 0, 0x14000
	v_add_u32_e32 v152, s22, v157
	v_add_u32_e32 v162, s48, v157
	ds_read_b128 v[128:131], v152
	ds_read_b128 v[144:147], v152 offset:1024
	ds_read_b128 v[148:151], v152 offset:2048
	ds_read_b128 v[152:155], v152 offset:3072
	ds_read_b128 v[176:179], v162
	ds_read_b128 v[180:183], v162 offset:1024
	ds_read_b128 v[184:187], v162 offset:2048
	ds_read_b128 v[188:191], v162 offset:3072
	v_lshl_add_u64 v[162:163], s[0:1], 0, v[142:143]
	s_add_i32 m0, s27, 0xc000
	ds_read_b128 v[192:195], v159
	ds_read_b128 v[196:199], v159 offset:1024
	ds_read_b128 v[200:203], v159 offset:2048
	ds_read_b128 v[204:207], v159 offset:3072
	ds_read_b128 v[208:211], v159 offset:4096
	ds_read_b128 v[212:215], v159 offset:5120
	ds_read_b128 v[238:241], v159 offset:6144
	ds_read_b128 v[246:249], v159 offset:7168
	global_load_lds_dwordx4 v[162:163], off
	v_lshl_add_u64 v[162:163], s[0:1], 0, v[140:141]
	s_add_i32 m0, s27, 0xe000
	s_nop 0
	global_load_lds_dwordx4 v[162:163], off
	s_waitcnt vmcnt(8)
	s_waitcnt lgkmcnt(0)
	s_barrier
	s_setprio 1
	s_waitcnt lgkmcnt(0)
	v_mfma_f32_16x16x32_bf16 v[124:127], v[128:131], v[192:195], v[124:127]
	v_mfma_f32_16x16x32_bf16 v[116:119], v[148:151], v[192:195], v[116:119]
	v_mfma_f32_16x16x32_bf16 v[108:111], v[128:131], v[200:203], v[108:111]
	v_mfma_f32_16x16x32_bf16 v[100:103], v[148:151], v[200:203], v[100:103]
	v_mfma_f32_16x16x32_bf16 v[92:95], v[128:131], v[208:211], v[92:95]
	v_mfma_f32_16x16x32_bf16 v[84:87], v[148:151], v[208:211], v[84:87]
	v_mfma_f32_16x16x32_bf16 v[76:79], v[128:131], v[238:241], v[76:79]
	v_mfma_f32_16x16x32_bf16 v[68:71], v[148:151], v[238:241], v[68:71]
	v_mfma_f32_16x16x32_bf16 v[124:127], v[144:147], v[196:199], v[124:127]
	v_mfma_f32_16x16x32_bf16 v[116:119], v[152:155], v[196:199], v[116:119]
	v_mfma_f32_16x16x32_bf16 v[108:111], v[144:147], v[204:207], v[108:111]
	v_mfma_f32_16x16x32_bf16 v[100:103], v[152:155], v[204:207], v[100:103]
	v_mfma_f32_16x16x32_bf16 v[92:95], v[144:147], v[212:215], v[92:95]
	v_mfma_f32_16x16x32_bf16 v[84:87], v[152:155], v[212:215], v[84:87]
	v_mfma_f32_16x16x32_bf16 v[76:79], v[144:147], v[246:249], v[76:79]
	v_mfma_f32_16x16x32_bf16 v[68:71], v[152:155], v[246:249], v[68:71]
	s_setprio 0
	s_setprio 1
	v_mfma_f32_16x16x32_bf16 v[120:123], v[176:179], v[192:195], v[120:123]
	v_mfma_f32_16x16x32_bf16 v[112:115], v[184:187], v[192:195], v[112:115]
	v_mfma_f32_16x16x32_bf16 v[104:107], v[176:179], v[200:203], v[104:107]
	v_mfma_f32_16x16x32_bf16 v[96:99], v[184:187], v[200:203], v[96:99]
	v_mfma_f32_16x16x32_bf16 v[88:91], v[176:179], v[208:211], v[88:91]
	v_mfma_f32_16x16x32_bf16 v[80:83], v[184:187], v[208:211], v[80:83]
	v_mfma_f32_16x16x32_bf16 v[72:75], v[176:179], v[238:241], v[72:75]
	v_mfma_f32_16x16x32_bf16 v[64:67], v[184:187], v[238:241], v[64:67]
	v_mfma_f32_16x16x32_bf16 v[120:123], v[180:183], v[196:199], v[120:123]
	v_mfma_f32_16x16x32_bf16 v[112:115], v[188:191], v[196:199], v[112:115]
	v_mfma_f32_16x16x32_bf16 v[104:107], v[180:183], v[204:207], v[104:107]
	v_mfma_f32_16x16x32_bf16 v[96:99], v[188:191], v[204:207], v[96:99]
	v_mfma_f32_16x16x32_bf16 v[88:91], v[180:183], v[212:215], v[88:91]
	v_mfma_f32_16x16x32_bf16 v[80:83], v[188:191], v[212:215], v[80:83]
	v_mfma_f32_16x16x32_bf16 v[72:75], v[180:183], v[246:249], v[72:75]
	v_mfma_f32_16x16x32_bf16 v[64:67], v[188:191], v[246:249], v[64:67]
	s_setprio 0
	s_barrier
	s_add_i32 s22, s22, s25
	v_lshl_add_u64 v[162:163], s[8:9], 0, v[136:137]
	s_mov_b32 m0, s22
	ds_read_b128 v[192:195], v159 offset:16384
	ds_read_b128 v[196:199], v159 offset:17408
	ds_read_b128 v[200:203], v159 offset:18432
	ds_read_b128 v[204:207], v159 offset:19456
	ds_read_b128 v[208:211], v159 offset:20480
	ds_read_b128 v[212:215], v159 offset:21504
	ds_read_b128 v[238:241], v159 offset:22528
	ds_read_b128 v[246:249], v159 offset:23552
	global_load_lds_dwordx4 v[162:163], off
	s_add_i32 m0, s22, 0x2000
	s_add_u32 vcc_lo, s8, 0x40000
	v_lshl_add_u64 v[164:165], s[8:9], 0, v[132:133]
	s_addc_u32 vcc_hi, s9, 0
	s_add_i32 s22, s48, s25
	global_load_lds_dwordx4 v[164:165], off
	v_lshl_add_u64 v[166:167], vcc, 0, v[136:137]
	s_mov_b32 m0, s22
	v_lshl_add_u64 v[168:169], s[10:11], 0, v[134:135]
	global_load_lds_dwordx4 v[166:167], off
	v_lshl_add_u64 v[166:167], vcc, 0, v[132:133]
	s_add_i32 m0, s22, 0x2000
	s_nop 0
	global_load_lds_dwordx4 v[166:167], off
	v_lshl_add_u64 v[166:167], s[10:11], 0, v[138:139]
	s_mov_b32 m0, s27
	s_nop 0
	global_load_lds_dwordx4 v[166:167], off
	s_mov_b32 m0, s45
	s_nop 0
	global_load_lds_dwordx4 v[168:169], off
	s_waitcnt vmcnt(8)
	s_waitcnt lgkmcnt(0)
	s_barrier
	s_setprio 1
	s_waitcnt lgkmcnt(0)
	v_mfma_f32_16x16x32_bf16 v[60:63], v[128:131], v[192:195], v[60:63]
	v_mfma_f32_16x16x32_bf16 v[52:55], v[148:151], v[192:195], v[52:55]
	v_mfma_f32_16x16x32_bf16 v[44:47], v[128:131], v[200:203], v[44:47]
	v_mfma_f32_16x16x32_bf16 v[36:39], v[148:151], v[200:203], v[36:39]
	v_mfma_f32_16x16x32_bf16 v[28:31], v[128:131], v[208:211], v[28:31]
	v_mfma_f32_16x16x32_bf16 v[20:23], v[148:151], v[208:211], v[20:23]
	v_mfma_f32_16x16x32_bf16 v[12:15], v[128:131], v[238:241], v[12:15]
	v_mfma_f32_16x16x32_bf16 v[4:7], v[148:151], v[238:241], v[4:7]
	v_mfma_f32_16x16x32_bf16 v[60:63], v[144:147], v[196:199], v[60:63]
	v_mfma_f32_16x16x32_bf16 v[52:55], v[152:155], v[196:199], v[52:55]
	v_mfma_f32_16x16x32_bf16 v[44:47], v[144:147], v[204:207], v[44:47]
	v_mfma_f32_16x16x32_bf16 v[36:39], v[152:155], v[204:207], v[36:39]
	v_mfma_f32_16x16x32_bf16 v[28:31], v[144:147], v[212:215], v[28:31]
	v_mfma_f32_16x16x32_bf16 v[20:23], v[152:155], v[212:215], v[20:23]
	v_mfma_f32_16x16x32_bf16 v[12:15], v[144:147], v[246:249], v[12:15]
	v_mfma_f32_16x16x32_bf16 v[4:7], v[152:155], v[246:249], v[4:7]
	s_setprio 0
	s_setprio 1
	v_mfma_f32_16x16x32_bf16 v[56:59], v[176:179], v[192:195], v[56:59]
	v_mfma_f32_16x16x32_bf16 v[48:51], v[184:187], v[192:195], v[48:51]
	v_mfma_f32_16x16x32_bf16 v[40:43], v[176:179], v[200:203], v[40:43]
	v_mfma_f32_16x16x32_bf16 v[32:35], v[184:187], v[200:203], v[32:35]
	v_mfma_f32_16x16x32_bf16 v[24:27], v[176:179], v[208:211], v[24:27]
	v_mfma_f32_16x16x32_bf16 v[16:19], v[184:187], v[208:211], v[16:19]
	v_mfma_f32_16x16x32_bf16 v[8:11], v[176:179], v[238:241], v[8:11]
	v_mfma_f32_16x16x32_bf16 v[0:3], v[184:187], v[238:241], v[0:3]
	v_mfma_f32_16x16x32_bf16 v[56:59], v[180:183], v[196:199], v[56:59]
	v_mfma_f32_16x16x32_bf16 v[48:51], v[188:191], v[196:199], v[48:51]
	v_mfma_f32_16x16x32_bf16 v[40:43], v[180:183], v[204:207], v[40:43]
	v_mfma_f32_16x16x32_bf16 v[32:35], v[188:191], v[204:207], v[32:35]
	v_mfma_f32_16x16x32_bf16 v[24:27], v[180:183], v[212:215], v[24:27]
	v_mfma_f32_16x16x32_bf16 v[16:19], v[188:191], v[212:215], v[16:19]
	v_mfma_f32_16x16x32_bf16 v[8:11], v[180:183], v[246:249], v[8:11]
	v_mfma_f32_16x16x32_bf16 v[0:3], v[188:191], v[246:249], v[0:3]
	s_setprio 0
	s_barrier
	s_add_i32 s22, 0, 0x18000
	s_add_i32 s48, 0, 0x1c000
	v_add_u32_e32 v152, s22, v157
	v_add_u32_e32 v170, s48, v157
	ds_read_b128 v[128:131], v152
	ds_read_b128 v[144:147], v152 offset:1024
	ds_read_b128 v[148:151], v152 offset:2048
	ds_read_b128 v[152:155], v152 offset:3072
	ds_read_b128 v[176:179], v170
	ds_read_b128 v[180:183], v170 offset:1024
	ds_read_b128 v[184:187], v170 offset:2048
	ds_read_b128 v[188:191], v170 offset:3072
	s_add_u32 s10, s10, 0x40000
	s_addc_u32 s11, s11, 0
	s_mov_b32 m0, s28
	v_lshl_add_u64 v[170:171], s[10:11], 0, v[138:139]
	ds_read_b128 v[192:195], v159 offset:32768
	ds_read_b128 v[196:199], v159 offset:33792
	ds_read_b128 v[200:203], v159 offset:34816
	ds_read_b128 v[204:207], v159 offset:35840
	ds_read_b128 v[208:211], v159 offset:36864
	ds_read_b128 v[212:215], v159 offset:37888
	ds_read_b128 v[238:241], v159 offset:38912
	ds_read_b128 v[246:249], v159 offset:39936
	global_load_lds_dwordx4 v[170:171], off
	v_lshl_add_u64 v[170:171], s[10:11], 0, v[134:135]
	s_mov_b32 m0, s29
	s_nop 0
	global_load_lds_dwordx4 v[170:171], off
	s_waitcnt vmcnt(8)
	s_waitcnt lgkmcnt(0)
	s_barrier
	s_setprio 1
	s_waitcnt lgkmcnt(0)
	v_mfma_f32_16x16x32_bf16 v[124:127], v[128:131], v[192:195], v[124:127]
	v_mfma_f32_16x16x32_bf16 v[116:119], v[148:151], v[192:195], v[116:119]
	v_mfma_f32_16x16x32_bf16 v[108:111], v[128:131], v[200:203], v[108:111]
	v_mfma_f32_16x16x32_bf16 v[100:103], v[148:151], v[200:203], v[100:103]
	v_mfma_f32_16x16x32_bf16 v[92:95], v[128:131], v[208:211], v[92:95]
	v_mfma_f32_16x16x32_bf16 v[84:87], v[148:151], v[208:211], v[84:87]
	v_mfma_f32_16x16x32_bf16 v[76:79], v[128:131], v[238:241], v[76:79]
	v_mfma_f32_16x16x32_bf16 v[68:71], v[148:151], v[238:241], v[68:71]
	v_mfma_f32_16x16x32_bf16 v[124:127], v[144:147], v[196:199], v[124:127]
	v_mfma_f32_16x16x32_bf16 v[116:119], v[152:155], v[196:199], v[116:119]
	v_mfma_f32_16x16x32_bf16 v[108:111], v[144:147], v[204:207], v[108:111]
	v_mfma_f32_16x16x32_bf16 v[100:103], v[152:155], v[204:207], v[100:103]
	v_mfma_f32_16x16x32_bf16 v[92:95], v[144:147], v[212:215], v[92:95]
	v_mfma_f32_16x16x32_bf16 v[84:87], v[152:155], v[212:215], v[84:87]
	v_mfma_f32_16x16x32_bf16 v[76:79], v[144:147], v[246:249], v[76:79]
	v_mfma_f32_16x16x32_bf16 v[68:71], v[152:155], v[246:249], v[68:71]
	s_setprio 0
	s_setprio 1
	v_mfma_f32_16x16x32_bf16 v[120:123], v[176:179], v[192:195], v[120:123]
	v_mfma_f32_16x16x32_bf16 v[112:115], v[184:187], v[192:195], v[112:115]
	v_mfma_f32_16x16x32_bf16 v[104:107], v[176:179], v[200:203], v[104:107]
	v_mfma_f32_16x16x32_bf16 v[96:99], v[184:187], v[200:203], v[96:99]
	v_mfma_f32_16x16x32_bf16 v[88:91], v[176:179], v[208:211], v[88:91]
	v_mfma_f32_16x16x32_bf16 v[80:83], v[184:187], v[208:211], v[80:83]
	v_mfma_f32_16x16x32_bf16 v[72:75], v[176:179], v[238:241], v[72:75]
	v_mfma_f32_16x16x32_bf16 v[64:67], v[184:187], v[238:241], v[64:67]
	v_mfma_f32_16x16x32_bf16 v[120:123], v[180:183], v[196:199], v[120:123]
	v_mfma_f32_16x16x32_bf16 v[112:115], v[188:191], v[196:199], v[112:115]
	v_mfma_f32_16x16x32_bf16 v[104:107], v[180:183], v[204:207], v[104:107]
	v_mfma_f32_16x16x32_bf16 v[96:99], v[188:191], v[204:207], v[96:99]
	v_mfma_f32_16x16x32_bf16 v[88:91], v[180:183], v[212:215], v[88:91]
	v_mfma_f32_16x16x32_bf16 v[80:83], v[188:191], v[212:215], v[80:83]
	v_mfma_f32_16x16x32_bf16 v[72:75], v[180:183], v[246:249], v[72:75]
	v_mfma_f32_16x16x32_bf16 v[64:67], v[188:191], v[246:249], v[64:67]
	s_setprio 0
	s_barrier
	s_add_i32 s10, s22, s25
	v_lshl_add_u64 v[162:163], v[162:163], 0, s[88:89]
	s_mov_b32 m0, s10
	ds_read_b128 v[192:195], v159 offset:49152
	ds_read_b128 v[196:199], v159 offset:50176
	ds_read_b128 v[200:203], v159 offset:51200
	ds_read_b128 v[204:207], v159 offset:52224
	ds_read_b128 v[208:211], v159 offset:53248
	ds_read_b128 v[212:215], v159 offset:54272
	ds_read_b128 v[238:241], v159 offset:55296
	ds_read_b128 v[246:249], v159 offset:56320
	global_load_lds_dwordx4 v[162:163], off
	s_add_i32 m0, s10, 0x2000
	s_add_u32 s8, s8, 0x40080
	v_lshl_add_u64 v[162:163], v[164:165], 0, s[88:89]
	s_addc_u32 s9, s9, 0
	s_add_i32 s10, s48, s25
	global_load_lds_dwordx4 v[162:163], off
	v_lshl_add_u64 v[162:163], s[8:9], 0, v[136:137]
	s_mov_b32 m0, s10
	s_nop 0
	global_load_lds_dwordx4 v[162:163], off
	v_lshl_add_u64 v[162:163], s[8:9], 0, v[132:133]
	s_add_i32 m0, s10, 0x2000
	s_nop 0
	global_load_lds_dwordx4 v[162:163], off
	v_lshl_add_u64 v[162:163], v[166:167], 0, s[88:89]
	s_mov_b32 m0, s30
	s_nop 0
	global_load_lds_dwordx4 v[162:163], off
	v_lshl_add_u64 v[162:163], v[168:169], 0, s[88:89]
	s_mov_b32 m0, s31
	s_nop 0
	global_load_lds_dwordx4 v[162:163], off
	s_waitcnt vmcnt(8)
	s_waitcnt lgkmcnt(0)
	s_barrier
	s_setprio 1
	s_waitcnt lgkmcnt(0)
	v_mfma_f32_16x16x32_bf16 v[60:63], v[128:131], v[192:195], v[60:63]
	v_mfma_f32_16x16x32_bf16 v[52:55], v[148:151], v[192:195], v[52:55]
	v_mfma_f32_16x16x32_bf16 v[44:47], v[128:131], v[200:203], v[44:47]
	v_mfma_f32_16x16x32_bf16 v[36:39], v[148:151], v[200:203], v[36:39]
	v_mfma_f32_16x16x32_bf16 v[28:31], v[128:131], v[208:211], v[28:31]
	v_mfma_f32_16x16x32_bf16 v[20:23], v[148:151], v[208:211], v[20:23]
	v_mfma_f32_16x16x32_bf16 v[12:15], v[128:131], v[238:241], v[12:15]
	v_mfma_f32_16x16x32_bf16 v[4:7], v[148:151], v[238:241], v[4:7]
	v_mfma_f32_16x16x32_bf16 v[60:63], v[144:147], v[196:199], v[60:63]
	v_mfma_f32_16x16x32_bf16 v[52:55], v[152:155], v[196:199], v[52:55]
	v_mfma_f32_16x16x32_bf16 v[44:47], v[144:147], v[204:207], v[44:47]
	v_mfma_f32_16x16x32_bf16 v[36:39], v[152:155], v[204:207], v[36:39]
	v_mfma_f32_16x16x32_bf16 v[28:31], v[144:147], v[212:215], v[28:31]
	v_mfma_f32_16x16x32_bf16 v[20:23], v[152:155], v[212:215], v[20:23]
	v_mfma_f32_16x16x32_bf16 v[12:15], v[144:147], v[246:249], v[12:15]
	v_mfma_f32_16x16x32_bf16 v[4:7], v[152:155], v[246:249], v[4:7]
	s_setprio 0
	s_setprio 1
	v_mfma_f32_16x16x32_bf16 v[56:59], v[176:179], v[192:195], v[56:59]
	v_mfma_f32_16x16x32_bf16 v[48:51], v[184:187], v[192:195], v[48:51]
	v_mfma_f32_16x16x32_bf16 v[40:43], v[176:179], v[200:203], v[40:43]
	v_mfma_f32_16x16x32_bf16 v[32:35], v[184:187], v[200:203], v[32:35]
	v_mfma_f32_16x16x32_bf16 v[24:27], v[176:179], v[208:211], v[24:27]
	v_mfma_f32_16x16x32_bf16 v[16:19], v[184:187], v[208:211], v[16:19]
	v_mfma_f32_16x16x32_bf16 v[8:11], v[176:179], v[238:241], v[8:11]
	v_mfma_f32_16x16x32_bf16 v[0:3], v[184:187], v[238:241], v[0:3]
	v_mfma_f32_16x16x32_bf16 v[56:59], v[180:183], v[196:199], v[56:59]
	v_mfma_f32_16x16x32_bf16 v[48:51], v[188:191], v[196:199], v[48:51]
	v_mfma_f32_16x16x32_bf16 v[40:43], v[180:183], v[204:207], v[40:43]
	v_mfma_f32_16x16x32_bf16 v[32:35], v[188:191], v[204:207], v[32:35]
	v_mfma_f32_16x16x32_bf16 v[24:27], v[180:183], v[212:215], v[24:27]
	v_mfma_f32_16x16x32_bf16 v[16:19], v[188:191], v[212:215], v[16:19]
	v_mfma_f32_16x16x32_bf16 v[8:11], v[180:183], v[246:249], v[8:11]
	v_mfma_f32_16x16x32_bf16 v[0:3], v[188:191], v[246:249], v[0:3]
	s_setprio 0
	s_barrier
	s_add_i32 s21, s21, 2
	s_add_u32 s90, s90, 0x100
	s_addc_u32 s91, s91, 0
	s_add_u32 s0, s0, 0x100
	s_addc_u32 s1, s1, 0
	s_cmp_gt_u32 s21, 13
	s_cbranch_scc0 .LBB0_399
	v_lshl_add_u32 v212, s44, 8, v156
	v_lshlrev_b32_e32 v212, 3, v212
	global_load_dwordx2 v[196:197], v212, s[36:37]
	global_load_dwordx2 v[198:199], v212, s[36:37] offset:128
	global_load_dwordx2 v[200:201], v212, s[36:37] offset:256
	global_load_dwordx2 v[202:203], v212, s[36:37] offset:384
	global_load_dwordx2 v[204:205], v212, s[36:37] offset:1024
	global_load_dwordx2 v[206:207], v212, s[36:37] offset:1152
	global_load_dwordx2 v[208:209], v212, s[36:37] offset:1280
	global_load_dwordx2 v[210:211], v212, s[36:37] offset:1408
	s_and_b64 vcc, exec, s[92:93]
	s_cbranch_vccnz .LBB0_404
	s_cmp_gt_i32 s35, 3
	s_mov_b64 s[0:1], -1
	s_cbranch_scc1 .LBB0_405

.LBB0_405:
	s_cmp_gt_u32 s35, 7
	s_cbranch_scc0 .LBB0_407
	v_lshl_add_u32 v130, s44, 8, v156
	v_ashrrev_i32_e32 v131, 31, v130
	v_lshl_add_u64 v[146:147], v[130:131], 3, s[36:37]
	v_or_b32_e32 v128, 0xfffffc00, v158
	v_lshl_add_u32 v128, s35, 7, v128
	v_mov_b32_e32 v129, v161
	v_lshl_add_u64 v[128:129], v[128:129], 1, s[46:47]
	s_mov_b32 s0, 0x20000
	s_waitcnt vmcnt(0) lgkmcnt(0)
	v_mov_b64_e32 v[144:145], v[196:197]
	v_ffbh_u32_e32 v148, v145
	v_min_u32_e32 v148, 32, v148
	v_lshlrev_b64 v[144:145], v148, v[144:145]
	v_min_u32_e32 v144, 1, v144
	v_or_b32_e32 v144, v145, v144
	v_cvt_f32_u32_e32 v144, v144
	v_sub_u32_e32 v145, 32, v148
	v_ldexp_f32 v144, v144, v145
	v_mul_f32_e32 v144, 0x35800000, v144
	v_fmamk_f32 v144, v144, 0x3a800000, v219
	v_rsq_f32_e32 v144, v144
	s_nop 0
	v_mul_f32_e32 v145, v120, v144
	v_mul_f32_e32 v145, 0xbfb8aa3b, v145
	v_exp_f32_e32 v145, v145
	s_nop 0
	v_add_f32_e32 v145, 1.0, v145
	v_rcp_f32_e32 v148, v145
	v_mul_f32_e32 v145, v121, v144
	v_mul_f32_e32 v145, 0xbfb8aa3b, v145
	v_exp_f32_e32 v145, v145
	s_nop 0
	v_add_f32_e32 v145, 1.0, v145
	v_rcp_f32_e32 v149, v145
	v_pk_mul_f32 v[150:151], v[124:125], v[144:145] op_sel_hi:[1,0]
	v_mul_f32_e32 v145, v122, v144
	v_mul_f32_e32 v145, 0xbfb8aa3b, v145
	v_exp_f32_e32 v145, v145
	v_pk_mul_f32 v[148:149], v[150:151], v[148:149]
	v_add_f32_e32 v145, 1.0, v145
	v_rcp_f32_e32 v150, v145
	v_mul_f32_e32 v145, v123, v144
	v_mul_f32_e32 v145, 0xbfb8aa3b, v145
	v_exp_f32_e32 v145, v145
	v_cvt_pk_bf16_f32 v148, v148, v149
	v_add_f32_e32 v145, 1.0, v145
	v_rcp_f32_e32 v151, v145
	v_pk_mul_f32 v[152:153], v[126:127], v[144:145] op_sel_hi:[1,0]
	v_mul_f32_e32 v145, v112, v144
	v_mul_f32_e32 v145, 0xbfb8aa3b, v145
	v_exp_f32_e32 v145, v145
	v_pk_mul_f32 v[150:151], v[152:153], v[150:151]
	v_add_f32_e32 v145, 1.0, v145
	v_rcp_f32_e32 v152, v145
	v_mul_f32_e32 v145, v113, v144
	v_mul_f32_e32 v145, 0xbfb8aa3b, v145
	v_exp_f32_e32 v145, v145
	v_cvt_pk_bf16_f32 v149, v150, v151
	v_add_f32_e32 v145, 1.0, v145
	v_rcp_f32_e32 v153, v145
	v_pk_mul_f32 v[154:155], v[116:117], v[144:145] op_sel_hi:[1,0]
	v_mul_f32_e32 v145, v114, v144
	v_mul_f32_e32 v145, 0xbfb8aa3b, v145
	v_exp_f32_e32 v145, v145
	v_pk_mul_f32 v[152:153], v[154:155], v[152:153]
	v_add_f32_e32 v145, 1.0, v145
	v_rcp_f32_e32 v154, v145
	v_mul_f32_e32 v145, v115, v144
	v_mul_f32_e32 v145, 0xbfb8aa3b, v145
	v_exp_f32_e32 v145, v145
	v_cvt_pk_bf16_f32 v150, v152, v153
	v_add_f32_e32 v145, 1.0, v145
	v_rcp_f32_e32 v155, v145
	v_pk_mul_f32 v[144:145], v[118:119], v[144:145] op_sel_hi:[1,0]
	s_nop 0
	v_pk_mul_f32 v[154:155], v[144:145], v[154:155]
	v_lshlrev_b64 v[144:145], 10, v[130:131]
	v_lshl_add_u64 v[144:145], v[128:129], 0, v[144:145]
	v_cvt_pk_bf16_f32 v151, v154, v155
	global_store_dwordx4 v[144:145], v[148:151], off
	s_nop 1
	v_or_b32_e32 v148, 16, v130
	v_ashrrev_i32_e32 v149, 31, v148
	v_lshl_add_u64 v[150:151], v[148:149], 3, s[36:37]
	s_nop 1
	v_mov_b64_e32 v[150:151], v[198:199]
	v_lshlrev_b64 v[148:149], 10, v[148:149]
	v_lshl_add_u64 v[166:167], v[128:129], 0, v[148:149]
	v_ffbh_u32_e32 v131, v151
	v_min_u32_e32 v131, 32, v131
	v_lshlrev_b64 v[150:151], v131, v[150:151]
	v_min_u32_e32 v150, 1, v150
	v_or_b32_e32 v150, v151, v150
	v_cvt_f32_u32_e32 v150, v150
	v_sub_u32_e32 v131, 32, v131
	v_ldexp_f32 v131, v150, v131
	v_mul_f32_e32 v131, 0x35800000, v131
	v_fmamk_f32 v131, v131, 0x3a800000, v219
	v_rsq_f32_e32 v150, v131
	s_nop 0
	v_mul_f32_e32 v131, v104, v150
	v_mul_f32_e32 v131, 0xbfb8aa3b, v131
	v_exp_f32_e32 v131, v131
	v_pk_mul_f32 v[154:155], v[108:109], v[150:151] op_sel_hi:[1,0]
	v_pk_mul_f32 v[162:163], v[110:111], v[150:151] op_sel_hi:[1,0]
	v_pk_mul_f32 v[164:165], v[100:101], v[150:151] op_sel_hi:[1,0]
	v_add_f32_e32 v131, 1.0, v131
	v_rcp_f32_e32 v152, v131
	v_mul_f32_e32 v131, v105, v150
	v_mul_f32_e32 v131, 0xbfb8aa3b, v131
	v_exp_f32_e32 v131, v131
	s_nop 0
	v_add_f32_e32 v131, 1.0, v131
	v_rcp_f32_e32 v153, v131
	v_mul_f32_e32 v131, v106, v150
	v_mul_f32_e32 v131, 0xbfb8aa3b, v131
	v_exp_f32_e32 v131, v131
	v_pk_mul_f32 v[152:153], v[154:155], v[152:153]
	v_add_f32_e32 v131, 1.0, v131
	v_rcp_f32_e32 v154, v131
	v_mul_f32_e32 v131, v107, v150
	v_mul_f32_e32 v131, 0xbfb8aa3b, v131
	v_exp_f32_e32 v131, v131
	v_cvt_pk_bf16_f32 v148, v152, v153
	v_add_f32_e32 v131, 1.0, v131
	v_rcp_f32_e32 v155, v131
	v_mul_f32_e32 v131, v96, v150
	v_mul_f32_e32 v131, 0xbfb8aa3b, v131
	v_exp_f32_e32 v131, v131
	v_pk_mul_f32 v[154:155], v[162:163], v[154:155]
	v_add_f32_e32 v131, 1.0, v131
	v_rcp_f32_e32 v162, v131
	v_mul_f32_e32 v131, v97, v150
	v_mul_f32_e32 v131, 0xbfb8aa3b, v131
	v_exp_f32_e32 v131, v131
	v_cvt_pk_bf16_f32 v149, v154, v155
	v_add_f32_e32 v131, 1.0, v131
	v_rcp_f32_e32 v163, v131
	v_mul_f32_e32 v131, v98, v150
	v_mul_f32_e32 v131, 0xbfb8aa3b, v131
	v_exp_f32_e32 v131, v131
	v_pk_mul_f32 v[162:163], v[164:165], v[162:163]
	v_add_f32_e32 v131, 1.0, v131
	v_rcp_f32_e32 v164, v131
	v_mul_f32_e32 v131, v99, v150
	v_mul_f32_e32 v131, 0xbfb8aa3b, v131
	v_exp_f32_e32 v131, v131
	v_pk_mul_f32 v[150:151], v[102:103], v[150:151] op_sel_hi:[1,0]
	v_add_f32_e32 v131, 1.0, v131
	v_rcp_f32_e32 v165, v131
	s_nop 0
	v_pk_mul_f32 v[164:165], v[150:151], v[164:165]
	v_cvt_pk_bf16_f32 v150, v162, v163
	v_cvt_pk_bf16_f32 v151, v164, v165
	global_store_dwordx4 v[166:167], v[148:151], off
	s_nop 1
	v_or_b32_e32 v148, 32, v130
	v_ashrrev_i32_e32 v149, 31, v148
	v_lshl_add_u64 v[150:151], v[148:149], 3, s[36:37]
	s_nop 1
	v_mov_b64_e32 v[150:151], v[200:201]
	v_lshlrev_b64 v[148:149], 10, v[148:149]
	v_lshl_add_u64 v[166:167], v[128:129], 0, v[148:149]
	v_or_b32_e32 v130, 48, v130
	v_ffbh_u32_e32 v131, v151
	v_min_u32_e32 v131, 32, v131
	v_lshlrev_b64 v[150:151], v131, v[150:151]
	v_min_u32_e32 v150, 1, v150
	v_or_b32_e32 v150, v151, v150
	v_cvt_f32_u32_e32 v150, v150
	v_sub_u32_e32 v131, 32, v131
	v_ldexp_f32 v131, v150, v131
	v_mul_f32_e32 v131, 0x35800000, v131
	v_fmamk_f32 v131, v131, 0x3a800000, v219
	v_rsq_f32_e32 v150, v131
	s_nop 0
	v_mul_f32_e32 v131, v88, v150
	v_mul_f32_e32 v131, 0xbfb8aa3b, v131
	v_exp_f32_e32 v131, v131
	v_pk_mul_f32 v[154:155], v[92:93], v[150:151] op_sel_hi:[1,0]
	v_pk_mul_f32 v[162:163], v[94:95], v[150:151] op_sel_hi:[1,0]
	v_pk_mul_f32 v[164:165], v[84:85], v[150:151] op_sel_hi:[1,0]
	v_add_f32_e32 v131, 1.0, v131
	v_rcp_f32_e32 v152, v131
	v_mul_f32_e32 v131, v89, v150
	v_mul_f32_e32 v131, 0xbfb8aa3b, v131
	v_exp_f32_e32 v131, v131
	s_nop 0
	v_add_f32_e32 v131, 1.0, v131
	v_rcp_f32_e32 v153, v131
	v_mul_f32_e32 v131, v90, v150
	v_mul_f32_e32 v131, 0xbfb8aa3b, v131
	v_exp_f32_e32 v131, v131
	v_pk_mul_f32 v[152:153], v[154:155], v[152:153]
	v_add_f32_e32 v131, 1.0, v131
	v_rcp_f32_e32 v154, v131
	v_mul_f32_e32 v131, v91, v150
	v_mul_f32_e32 v131, 0xbfb8aa3b, v131
	v_exp_f32_e32 v131, v131
	v_cvt_pk_bf16_f32 v148, v152, v153
	v_add_f32_e32 v131, 1.0, v131
	v_rcp_f32_e32 v155, v131
	v_mul_f32_e32 v131, v80, v150
	v_mul_f32_e32 v131, 0xbfb8aa3b, v131
	v_exp_f32_e32 v131, v131
	v_pk_mul_f32 v[154:155], v[162:163], v[154:155]
	v_add_f32_e32 v131, 1.0, v131
	v_rcp_f32_e32 v162, v131
	v_mul_f32_e32 v131, v81, v150
	v_mul_f32_e32 v131, 0xbfb8aa3b, v131
	v_exp_f32_e32 v131, v131
	v_cvt_pk_bf16_f32 v149, v154, v155
	v_add_f32_e32 v131, 1.0, v131
	v_rcp_f32_e32 v163, v131
	v_mul_f32_e32 v131, v82, v150
	v_mul_f32_e32 v131, 0xbfb8aa3b, v131
	v_exp_f32_e32 v131, v131
	v_pk_mul_f32 v[162:163], v[164:165], v[162:163]
	v_add_f32_e32 v131, 1.0, v131
	v_rcp_f32_e32 v164, v131
	v_mul_f32_e32 v131, v83, v150
	v_mul_f32_e32 v131, 0xbfb8aa3b, v131
	v_exp_f32_e32 v131, v131
	v_pk_mul_f32 v[150:151], v[86:87], v[150:151] op_sel_hi:[1,0]
	v_add_f32_e32 v131, 1.0, v131
	v_rcp_f32_e32 v165, v131
	v_ashrrev_i32_e32 v131, 31, v130
	v_pk_mul_f32 v[164:165], v[150:151], v[164:165]
	v_cvt_pk_bf16_f32 v150, v162, v163
	v_cvt_pk_bf16_f32 v151, v164, v165
	global_store_dwordx4 v[166:167], v[148:151], off
	s_nop 1
	v_lshl_add_u64 v[148:149], v[130:131], 3, s[36:37]
	s_nop 1
	v_mov_b64_e32 v[148:149], v[202:203]
	v_lshlrev_b64 v[130:131], 10, v[130:131]
	v_ffbh_u32_e32 v150, v149
	v_min_u32_e32 v150, 32, v150
	v_lshlrev_b64 v[148:149], v150, v[148:149]
	v_min_u32_e32 v148, 1, v148
	v_or_b32_e32 v148, v149, v148
	v_cvt_f32_u32_e32 v148, v148
	v_sub_u32_e32 v149, 32, v150
	v_ldexp_f32 v148, v148, v149
	v_mul_f32_e32 v148, 0x35800000, v148
	v_fmamk_f32 v148, v148, 0x3a800000, v219
	v_rsq_f32_e32 v154, v148
	s_nop 0
	v_mul_f32_e32 v148, v72, v154
	v_mul_f32_e32 v149, v73, v154
	v_mul_f32_e32 v148, 0xbfb8aa3b, v148
	v_mul_f32_e32 v149, 0xbfb8aa3b, v149
	v_exp_f32_e32 v148, v148
	v_exp_f32_e32 v149, v149
	v_pk_mul_f32 v[150:151], v[76:77], v[154:155] op_sel_hi:[1,0]
	v_pk_mul_f32 v[152:153], v[78:79], v[154:155] op_sel_hi:[1,0]
	v_add_f32_e32 v148, 1.0, v148
	v_add_f32_e32 v149, 1.0, v149
	v_rcp_f32_e32 v148, v148
	v_rcp_f32_e32 v149, v149
	v_pk_mul_f32 v[162:163], v[68:69], v[154:155] op_sel_hi:[1,0]
	v_mul_f32_e32 v155, v66, v154
	v_mul_f32_e32 v155, 0xbfb8aa3b, v155
	v_pk_mul_f32 v[148:149], v[150:151], v[148:149]
	v_mul_f32_e32 v150, v74, v154
	v_mul_f32_e32 v151, v75, v154
	v_mul_f32_e32 v150, 0xbfb8aa3b, v150
	v_mul_f32_e32 v151, 0xbfb8aa3b, v151
	v_exp_f32_e32 v150, v150
	v_exp_f32_e32 v151, v151
	v_exp_f32_e32 v155, v155
	v_add_f32_e32 v150, 1.0, v150
	v_add_f32_e32 v151, 1.0, v151
	v_rcp_f32_e32 v150, v150
	v_rcp_f32_e32 v151, v151
	v_add_f32_e32 v155, 1.0, v155
	v_pk_mul_f32 v[150:151], v[152:153], v[150:151]
	v_mul_f32_e32 v152, v64, v154
	v_mul_f32_e32 v153, v65, v154
	v_mul_f32_e32 v152, 0xbfb8aa3b, v152
	v_mul_f32_e32 v153, 0xbfb8aa3b, v153
	v_exp_f32_e32 v152, v152
	v_exp_f32_e32 v153, v153
	v_add_f32_e32 v152, 1.0, v152
	v_add_f32_e32 v153, 1.0, v153
	v_rcp_f32_e32 v152, v152
	v_rcp_f32_e32 v153, v153
	s_nop 0
	v_pk_mul_f32 v[152:153], v[162:163], v[152:153]
	v_rcp_f32_e32 v162, v155
	v_mul_f32_e32 v155, v67, v154
	v_mul_f32_e32 v155, 0xbfb8aa3b, v155
	v_exp_f32_e32 v155, v155
	s_nop 0
	v_add_f32_e32 v155, 1.0, v155
	v_rcp_f32_e32 v163, v155
	v_pk_mul_f32 v[154:155], v[70:71], v[154:155] op_sel_hi:[1,0]
	s_nop 0
	v_pk_mul_f32 v[154:155], v[154:155], v[162:163]
	v_lshl_add_u64 v[162:163], v[128:129], 0, v[130:131]
	v_cvt_pk_bf16_f32 v128, v148, v149
	v_cvt_pk_bf16_f32 v129, v150, v151
	v_cvt_pk_bf16_f32 v130, v152, v153
	v_cvt_pk_bf16_f32 v131, v154, v155
	global_store_dwordx4 v[162:163], v[128:131], off
	s_nop 1
	v_mov_b64_e32 v[128:129], v[204:205]
	v_ffbh_u32_e32 v130, v129
	v_min_u32_e32 v130, 32, v130
	v_lshlrev_b64 v[128:129], v130, v[128:129]
	v_min_u32_e32 v128, 1, v128
	v_or_b32_e32 v128, v129, v128
	v_cvt_f32_u32_e32 v128, v128
	v_sub_u32_e32 v129, 32, v130
	v_ldexp_f32 v128, v128, v129
	v_mul_f32_e32 v128, 0x35800000, v128
	v_fmamk_f32 v128, v128, 0x3a800000, v219
	v_rsq_f32_e32 v128, v128
	s_nop 0
	v_mul_f32_e32 v129, v56, v128
	v_mul_f32_e32 v129, 0xbfb8aa3b, v129
	v_exp_f32_e32 v129, v129
	s_nop 0
	v_add_f32_e32 v129, 1.0, v129
	v_rcp_f32_e32 v130, v129
	v_mul_f32_e32 v129, v57, v128
	v_mul_f32_e32 v129, 0xbfb8aa3b, v129
	v_exp_f32_e32 v129, v129
	s_nop 0
	v_add_f32_e32 v129, 1.0, v129
	v_rcp_f32_e32 v131, v129
	v_pk_mul_f32 v[148:149], v[60:61], v[128:129] op_sel_hi:[1,0]
	v_mul_f32_e32 v129, v58, v128
	v_mul_f32_e32 v129, 0xbfb8aa3b, v129
	v_exp_f32_e32 v129, v129
	v_pk_mul_f32 v[130:131], v[148:149], v[130:131]
	v_add_f32_e32 v129, 1.0, v129
	v_rcp_f32_e32 v148, v129
	v_mul_f32_e32 v129, v59, v128
	v_mul_f32_e32 v129, 0xbfb8aa3b, v129
	v_exp_f32_e32 v129, v129
	s_nop 0
	v_add_f32_e32 v129, 1.0, v129
	v_rcp_f32_e32 v149, v129
	v_pk_mul_f32 v[150:151], v[62:63], v[128:129] op_sel_hi:[1,0]
	v_mul_f32_e32 v129, v48, v128
	v_mul_f32_e32 v129, 0xbfb8aa3b, v129
	v_exp_f32_e32 v129, v129
	v_pk_mul_f32 v[148:149], v[150:151], v[148:149]
	v_add_f32_e32 v129, 1.0, v129
	v_rcp_f32_e32 v150, v129
	v_mul_f32_e32 v129, v49, v128
	v_mul_f32_e32 v129, 0xbfb8aa3b, v129
	v_exp_f32_e32 v129, v129
	s_nop 0
	v_add_f32_e32 v129, 1.0, v129
	v_rcp_f32_e32 v151, v129
	v_pk_mul_f32 v[152:153], v[52:53], v[128:129] op_sel_hi:[1,0]
	v_mul_f32_e32 v129, v50, v128
	v_mul_f32_e32 v129, 0xbfb8aa3b, v129
	v_exp_f32_e32 v129, v129
	v_pk_mul_f32 v[150:151], v[152:153], v[150:151]
	v_add_f32_e32 v129, 1.0, v129
	v_rcp_f32_e32 v152, v129
	v_mul_f32_e32 v129, v51, v128
	v_mul_f32_e32 v129, 0xbfb8aa3b, v129
	v_exp_f32_e32 v129, v129
	s_nop 0
	v_add_f32_e32 v129, 1.0, v129
	v_rcp_f32_e32 v153, v129
	v_pk_mul_f32 v[128:129], v[54:55], v[128:129] op_sel_hi:[1,0]
	s_nop 0
	v_pk_mul_f32 v[152:153], v[128:129], v[152:153]
	v_cvt_pk_bf16_f32 v129, v148, v149
	v_add_co_u32_e32 v148, vcc, s0, v144
	v_cvt_pk_bf16_f32 v128, v130, v131
	v_cvt_pk_bf16_f32 v130, v150, v151
	v_cvt_pk_bf16_f32 v131, v152, v153
	v_addc_co_u32_e32 v149, vcc, 0, v145, vcc
	global_store_dwordx4 v[148:149], v[128:131], off
	s_nop 1
	v_mov_b64_e32 v[128:129], v[206:207]
	s_mov_b32 s0, 0x24000
	v_ffbh_u32_e32 v130, v129
	v_min_u32_e32 v130, 32, v130
	v_lshlrev_b64 v[128:129], v130, v[128:129]
	v_min_u32_e32 v128, 1, v128
	v_or_b32_e32 v128, v129, v128
	v_cvt_f32_u32_e32 v128, v128
	v_sub_u32_e32 v129, 32, v130
	v_ldexp_f32 v128, v128, v129
	v_mul_f32_e32 v128, 0x35800000, v128
	v_fmamk_f32 v128, v128, 0x3a800000, v219
	v_rsq_f32_e32 v128, v128
	s_nop 0
	v_mul_f32_e32 v129, v40, v128
	v_mul_f32_e32 v129, 0xbfb8aa3b, v129
	v_exp_f32_e32 v129, v129
	s_nop 0
	v_add_f32_e32 v129, 1.0, v129
	v_rcp_f32_e32 v130, v129
	v_mul_f32_e32 v129, v41, v128
	v_mul_f32_e32 v129, 0xbfb8aa3b, v129
	v_exp_f32_e32 v129, v129
	s_nop 0
	v_add_f32_e32 v129, 1.0, v129
	v_rcp_f32_e32 v131, v129
	v_pk_mul_f32 v[148:149], v[44:45], v[128:129] op_sel_hi:[1,0]
	v_mul_f32_e32 v129, v42, v128
	v_mul_f32_e32 v129, 0xbfb8aa3b, v129
	v_exp_f32_e32 v129, v129
	v_pk_mul_f32 v[130:131], v[148:149], v[130:131]
	v_add_f32_e32 v129, 1.0, v129
	v_rcp_f32_e32 v148, v129
	v_mul_f32_e32 v129, v43, v128
	v_mul_f32_e32 v129, 0xbfb8aa3b, v129
	v_exp_f32_e32 v129, v129
	s_nop 0
	v_add_f32_e32 v129, 1.0, v129
	v_rcp_f32_e32 v149, v129
	v_pk_mul_f32 v[150:151], v[46:47], v[128:129] op_sel_hi:[1,0]
	v_mul_f32_e32 v129, v32, v128
	v_mul_f32_e32 v129, 0xbfb8aa3b, v129
	v_exp_f32_e32 v129, v129
	v_pk_mul_f32 v[148:149], v[150:151], v[148:149]
	v_add_f32_e32 v129, 1.0, v129
	v_rcp_f32_e32 v150, v129
	v_mul_f32_e32 v129, v33, v128
	v_mul_f32_e32 v129, 0xbfb8aa3b, v129
	v_exp_f32_e32 v129, v129
	s_nop 0
	v_add_f32_e32 v129, 1.0, v129
	v_rcp_f32_e32 v151, v129
	v_pk_mul_f32 v[152:153], v[36:37], v[128:129] op_sel_hi:[1,0]
	v_mul_f32_e32 v129, v34, v128
	v_mul_f32_e32 v129, 0xbfb8aa3b, v129
	v_exp_f32_e32 v129, v129
	v_pk_mul_f32 v[150:151], v[152:153], v[150:151]
	v_add_f32_e32 v129, 1.0, v129
	v_rcp_f32_e32 v152, v129
	v_mul_f32_e32 v129, v35, v128
	v_mul_f32_e32 v129, 0xbfb8aa3b, v129
	v_exp_f32_e32 v129, v129
	s_nop 0
	v_add_f32_e32 v129, 1.0, v129
	v_rcp_f32_e32 v153, v129
	v_pk_mul_f32 v[128:129], v[38:39], v[128:129] op_sel_hi:[1,0]
	s_nop 0
	v_pk_mul_f32 v[152:153], v[128:129], v[152:153]
	v_cvt_pk_bf16_f32 v129, v148, v149
	v_add_co_u32_e32 v148, vcc, s0, v144
	v_cvt_pk_bf16_f32 v128, v130, v131
	v_cvt_pk_bf16_f32 v130, v150, v151
	v_cvt_pk_bf16_f32 v131, v152, v153
	v_addc_co_u32_e32 v149, vcc, 0, v145, vcc
	global_store_dwordx4 v[148:149], v[128:131], off
	s_nop 1
	v_mov_b64_e32 v[128:129], v[208:209]
	s_mov_b32 s0, 0x28000
	v_ffbh_u32_e32 v130, v129
	v_min_u32_e32 v130, 32, v130
	v_lshlrev_b64 v[128:129], v130, v[128:129]
	v_min_u32_e32 v128, 1, v128
	v_or_b32_e32 v128, v129, v128
	v_cvt_f32_u32_e32 v128, v128
	v_sub_u32_e32 v129, 32, v130
	v_ldexp_f32 v128, v128, v129
	v_mul_f32_e32 v128, 0x35800000, v128
	v_fmamk_f32 v128, v128, 0x3a800000, v219
	v_rsq_f32_e32 v128, v128
	s_nop 0
	v_mul_f32_e32 v129, v24, v128
	v_mul_f32_e32 v129, 0xbfb8aa3b, v129
	v_exp_f32_e32 v129, v129
	s_nop 0
	v_add_f32_e32 v129, 1.0, v129
	v_rcp_f32_e32 v130, v129
	v_mul_f32_e32 v129, v25, v128
	v_mul_f32_e32 v129, 0xbfb8aa3b, v129
	v_exp_f32_e32 v129, v129
	s_nop 0
	v_add_f32_e32 v129, 1.0, v129
	v_rcp_f32_e32 v131, v129
	v_pk_mul_f32 v[148:149], v[28:29], v[128:129] op_sel_hi:[1,0]
	v_mul_f32_e32 v129, v26, v128
	v_mul_f32_e32 v129, 0xbfb8aa3b, v129
	v_exp_f32_e32 v129, v129
	v_pk_mul_f32 v[130:131], v[148:149], v[130:131]
	v_add_f32_e32 v129, 1.0, v129
	v_rcp_f32_e32 v148, v129
	v_mul_f32_e32 v129, v27, v128
	v_mul_f32_e32 v129, 0xbfb8aa3b, v129
	v_exp_f32_e32 v129, v129
	s_nop 0
	v_add_f32_e32 v129, 1.0, v129
	v_rcp_f32_e32 v149, v129
	v_pk_mul_f32 v[150:151], v[30:31], v[128:129] op_sel_hi:[1,0]
	v_mul_f32_e32 v129, v16, v128
	v_mul_f32_e32 v129, 0xbfb8aa3b, v129
	v_exp_f32_e32 v129, v129
	v_pk_mul_f32 v[148:149], v[150:151], v[148:149]
	v_add_f32_e32 v129, 1.0, v129
	v_rcp_f32_e32 v150, v129
	v_mul_f32_e32 v129, v17, v128
	v_mul_f32_e32 v129, 0xbfb8aa3b, v129
	v_exp_f32_e32 v129, v129
	s_nop 0
	v_add_f32_e32 v129, 1.0, v129
	v_rcp_f32_e32 v151, v129
	v_pk_mul_f32 v[152:153], v[20:21], v[128:129] op_sel_hi:[1,0]
	v_mul_f32_e32 v129, v18, v128
	v_mul_f32_e32 v129, 0xbfb8aa3b, v129
	v_exp_f32_e32 v129, v129
	v_pk_mul_f32 v[150:151], v[152:153], v[150:151]
	v_add_f32_e32 v129, 1.0, v129
	v_rcp_f32_e32 v152, v129
	v_mul_f32_e32 v129, v19, v128
	v_mul_f32_e32 v129, 0xbfb8aa3b, v129
	v_exp_f32_e32 v129, v129
	s_nop 0
	v_add_f32_e32 v129, 1.0, v129
	v_rcp_f32_e32 v153, v129
	v_pk_mul_f32 v[128:129], v[22:23], v[128:129] op_sel_hi:[1,0]
	s_nop 0
	v_pk_mul_f32 v[152:153], v[128:129], v[152:153]
	v_cvt_pk_bf16_f32 v129, v148, v149
	v_add_co_u32_e32 v148, vcc, s0, v144
	v_cvt_pk_bf16_f32 v128, v130, v131
	v_cvt_pk_bf16_f32 v130, v150, v151
	v_cvt_pk_bf16_f32 v131, v152, v153
	v_addc_co_u32_e32 v149, vcc, 0, v145, vcc
	global_store_dwordx4 v[148:149], v[128:131], off
	s_nop 1
	v_mov_b64_e32 v[128:129], v[210:211]
	v_add_co_u32_e32 v144, vcc, 0x2c000, v144
	s_mov_b64 s[0:1], 0
	s_nop 0
	v_addc_co_u32_e32 v145, vcc, 0, v145, vcc
	v_ffbh_u32_e32 v130, v129
	v_min_u32_e32 v130, 32, v130
	v_lshlrev_b64 v[128:129], v130, v[128:129]
	v_min_u32_e32 v128, 1, v128
	v_or_b32_e32 v128, v129, v128
	v_cvt_f32_u32_e32 v128, v128
	v_sub_u32_e32 v129, 32, v130
	v_ldexp_f32 v128, v128, v129
	v_mul_f32_e32 v128, 0x35800000, v128
	v_fmamk_f32 v128, v128, 0x3a800000, v219
	v_rsq_f32_e32 v128, v128
	s_nop 0
	v_mul_f32_e32 v129, v8, v128
	v_mul_f32_e32 v129, 0xbfb8aa3b, v129
	v_exp_f32_e32 v129, v129
	s_nop 0
	v_add_f32_e32 v129, 1.0, v129
	v_rcp_f32_e32 v130, v129
	v_mul_f32_e32 v129, v9, v128
	v_mul_f32_e32 v129, 0xbfb8aa3b, v129
	v_exp_f32_e32 v129, v129
	s_nop 0
	v_add_f32_e32 v129, 1.0, v129
	v_rcp_f32_e32 v131, v129
	v_pk_mul_f32 v[146:147], v[12:13], v[128:129] op_sel_hi:[1,0]
	v_mul_f32_e32 v129, v10, v128
	v_mul_f32_e32 v129, 0xbfb8aa3b, v129
	v_exp_f32_e32 v129, v129
	v_pk_mul_f32 v[130:131], v[146:147], v[130:131]
	v_add_f32_e32 v129, 1.0, v129
	v_rcp_f32_e32 v146, v129
	v_mul_f32_e32 v129, v11, v128
	v_mul_f32_e32 v129, 0xbfb8aa3b, v129
	v_exp_f32_e32 v129, v129
	s_nop 0
	v_add_f32_e32 v129, 1.0, v129
	v_rcp_f32_e32 v147, v129
	v_pk_mul_f32 v[148:149], v[14:15], v[128:129] op_sel_hi:[1,0]
	v_mul_f32_e32 v129, v0, v128
	v_mul_f32_e32 v129, 0xbfb8aa3b, v129
	v_exp_f32_e32 v129, v129
	v_pk_mul_f32 v[146:147], v[148:149], v[146:147]
	v_add_f32_e32 v129, 1.0, v129
	v_rcp_f32_e32 v148, v129
	v_mul_f32_e32 v129, v1, v128
	v_mul_f32_e32 v129, 0xbfb8aa3b, v129
	v_exp_f32_e32 v129, v129
	s_nop 0
	v_add_f32_e32 v129, 1.0, v129
	v_rcp_f32_e32 v149, v129
	v_pk_mul_f32 v[150:151], v[4:5], v[128:129] op_sel_hi:[1,0]
	v_mul_f32_e32 v129, v2, v128
	v_mul_f32_e32 v129, 0xbfb8aa3b, v129
	v_exp_f32_e32 v129, v129
	v_pk_mul_f32 v[148:149], v[150:151], v[148:149]
	v_add_f32_e32 v129, 1.0, v129
	v_rcp_f32_e32 v150, v129
	v_mul_f32_e32 v129, v3, v128
	v_mul_f32_e32 v129, 0xbfb8aa3b, v129
	v_exp_f32_e32 v129, v129
	s_nop 0
	v_add_f32_e32 v129, 1.0, v129
	v_rcp_f32_e32 v151, v129
	v_pk_mul_f32 v[128:129], v[6:7], v[128:129] op_sel_hi:[1,0]
	s_nop 0
	v_pk_mul_f32 v[150:151], v[128:129], v[150:151]
	v_cvt_pk_bf16_f32 v128, v130, v131
	v_cvt_pk_bf16_f32 v129, v146, v147
	v_cvt_pk_bf16_f32 v130, v148, v149
	v_cvt_pk_bf16_f32 v131, v150, v151
	global_store_dwordx4 v[144:145], v[128:131], off
.LBB0_407:
	s_andn2_b64 vcc, exec, s[0:1]
	s_cbranch_vccnz .LBB0_409
	s_add_i32 s7, s35, -4
	s_cmp_lt_u32 s7, 2
	s_mov_b32 s0, 0xfa00000
	s_cselect_b32 s0, s0, 0x11a00000
	s_add_u32 s0, s94, s0
	s_addc_u32 s1, s95, 0
	s_cmp_gt_u32 s7, 1
	s_cselect_b64 vcc, -1, 0
	s_lshl_b32 s7, s7, 8
	v_lshl_add_u32 v146, s44, 8, v156
	s_and_b32 s7, s7, 0x100
	v_or_b32_e32 v128, s7, v158
	v_ashrrev_i32_e32 v147, 31, v146
	v_lshlrev_b32_e32 v128, 1, v128
	v_mov_b32_e32 v129, v161
	v_lshl_add_u64 v[130:131], v[146:147], 3, s[36:37]
	v_lshl_add_u64 v[144:145], s[0:1], 0, v[128:129]
	s_mov_b64 s[0:1], 0x20000
	s_waitcnt vmcnt(0) lgkmcnt(0)
	v_mov_b64_e32 v[128:129], v[196:197]
	v_ffbh_u32_e32 v148, v129
	v_min_u32_e32 v148, 32, v148
	v_lshlrev_b64 v[128:129], v148, v[128:129]
	v_min_u32_e32 v128, 1, v128
	v_or_b32_e32 v128, v129, v128
	v_cvt_f32_u32_e32 v128, v128
	v_sub_u32_e32 v129, 32, v148
	v_ldexp_f32 v128, v128, v129
	v_mul_f32_e32 v128, 0x35800000, v128
	v_fmamk_f32 v128, v128, 0x3a800000, v219
	v_rsq_f32_e32 v148, v128
	v_lshlrev_b64 v[128:129], 10, v[146:147]
	v_lshl_add_u64 v[128:129], v[144:145], 0, v[128:129]
	v_mul_f32_e32 v147, v124, v148
	v_mul_f32_e32 v149, 0xbfb8aa3b, v147
	v_exp_f32_e32 v149, v149
	s_nop 0
	v_add_f32_e32 v149, 1.0, v149
	v_rcp_f32_e32 v149, v149
	s_nop 0
	v_mul_f32_e32 v149, v147, v149
	v_cndmask_b32_e32 v147, v147, v149, vcc
	v_mul_f32_e32 v149, v125, v148
	v_mul_f32_e32 v150, 0xbfb8aa3b, v149
	v_exp_f32_e32 v150, v150
	s_nop 0
	v_add_f32_e32 v150, 1.0, v150
	v_rcp_f32_e32 v150, v150
	s_nop 0
	v_mul_f32_e32 v150, v149, v150
	v_cndmask_b32_e32 v149, v149, v150, vcc
	v_mul_f32_e32 v150, v126, v148
	v_mul_f32_e32 v151, 0xbfb8aa3b, v150
	v_exp_f32_e32 v151, v151
	s_nop 0
	v_add_f32_e32 v151, 1.0, v151
	v_rcp_f32_e32 v151, v151
	s_nop 0
	v_mul_f32_e32 v151, v150, v151
	v_cndmask_b32_e32 v151, v150, v151, vcc
	v_mul_f32_e32 v150, v127, v148
	v_mul_f32_e32 v152, 0xbfb8aa3b, v150
	v_exp_f32_e32 v152, v152
	s_nop 0
	v_add_f32_e32 v152, 1.0, v152
	v_rcp_f32_e32 v152, v152
	s_nop 0
	v_mul_f32_e32 v152, v150, v152
	v_cndmask_b32_e32 v152, v150, v152, vcc
	v_mul_f32_e32 v150, v116, v148
	v_mul_f32_e32 v153, 0xbfb8aa3b, v150
	v_exp_f32_e32 v153, v153
	v_cvt_pk_bf16_f32 v151, v151, v152
	v_add_f32_e32 v153, 1.0, v153
	v_rcp_f32_e32 v153, v153
	s_nop 0
	v_mul_f32_e32 v153, v150, v153
	v_cndmask_b32_e32 v153, v150, v153, vcc
	v_mul_f32_e32 v150, v117, v148
	v_mul_f32_e32 v154, 0xbfb8aa3b, v150
	v_exp_f32_e32 v154, v154
	s_nop 0
	v_add_f32_e32 v154, 1.0, v154
	v_rcp_f32_e32 v154, v154
	s_nop 0
	v_mul_f32_e32 v154, v150, v154
	v_cndmask_b32_e32 v154, v150, v154, vcc
	v_mul_f32_e32 v150, v118, v148
	v_mul_f32_e32 v155, 0xbfb8aa3b, v150
	v_exp_f32_e32 v155, v155
	v_cvt_pk_bf16_f32 v152, v153, v154
	v_add_f32_e32 v155, 1.0, v155
	v_rcp_f32_e32 v155, v155
	s_nop 0
	v_mul_f32_e32 v155, v150, v155
	v_cndmask_b32_e32 v155, v150, v155, vcc
	v_mul_f32_e32 v150, v119, v148
	v_mul_f32_e32 v162, 0xbfb8aa3b, v150
	v_exp_f32_e32 v162, v162
	s_nop 0
	v_add_f32_e32 v162, 1.0, v162
	v_rcp_f32_e32 v162, v162
	s_nop 0
	v_mul_f32_e32 v162, v150, v162
	v_cndmask_b32_e32 v162, v150, v162, vcc
	v_cvt_pk_bf16_f32 v150, v147, v149
	v_mul_f32_e32 v147, v120, v148
	v_mul_f32_e32 v149, 0xbfb8aa3b, v147
	v_exp_f32_e32 v149, v149
	v_cvt_pk_bf16_f32 v153, v155, v162
	global_store_dwordx4 v[128:129], v[150:153], off
	v_add_f32_e32 v149, 1.0, v149
	v_rcp_f32_e32 v149, v149
	s_nop 0
	v_mul_f32_e32 v149, v147, v149
	v_cndmask_b32_e32 v147, v147, v149, vcc
	v_mul_f32_e32 v149, v121, v148
	v_mul_f32_e32 v150, 0xbfb8aa3b, v149
	v_exp_f32_e32 v150, v150
	s_nop 0
	v_add_f32_e32 v150, 1.0, v150
	v_rcp_f32_e32 v150, v150
	s_nop 0
	v_mul_f32_e32 v150, v149, v150
	v_cndmask_b32_e32 v149, v149, v150, vcc
	v_mul_f32_e32 v150, v122, v148
	v_mul_f32_e32 v151, 0xbfb8aa3b, v150
	v_exp_f32_e32 v151, v151
	s_nop 0
	v_add_f32_e32 v151, 1.0, v151
	v_rcp_f32_e32 v151, v151
	s_nop 0
	v_mul_f32_e32 v151, v150, v151
	v_cndmask_b32_e32 v150, v150, v151, vcc
	v_mul_f32_e32 v151, v123, v148
	v_mul_f32_e32 v152, 0xbfb8aa3b, v151
	v_exp_f32_e32 v152, v152
	s_nop 0
	v_add_f32_e32 v152, 1.0, v152
	v_rcp_f32_e32 v152, v152
	s_nop 0
	v_mul_f32_e32 v152, v151, v152
	v_cndmask_b32_e32 v151, v151, v152, vcc
	v_mul_f32_e32 v152, v112, v148
	v_mul_f32_e32 v153, 0xbfb8aa3b, v152
	v_exp_f32_e32 v153, v153
	s_nop 0
	v_add_f32_e32 v153, 1.0, v153
	v_rcp_f32_e32 v153, v153
	s_nop 0
	v_mul_f32_e32 v153, v152, v153
	v_cndmask_b32_e32 v152, v152, v153, vcc
	v_mul_f32_e32 v153, v113, v148
	v_mul_f32_e32 v154, 0xbfb8aa3b, v153
	v_exp_f32_e32 v154, v154
	s_nop 0
	v_add_f32_e32 v154, 1.0, v154
	v_rcp_f32_e32 v154, v154
	s_nop 0
	v_mul_f32_e32 v154, v153, v154
	v_cndmask_b32_e32 v153, v153, v154, vcc
	v_mul_f32_e32 v154, v114, v148
	v_mul_f32_e32 v155, 0xbfb8aa3b, v154
	v_exp_f32_e32 v155, v155
	v_mul_f32_e32 v148, v115, v148
	v_add_f32_e32 v155, 1.0, v155
	v_rcp_f32_e32 v155, v155
	s_nop 0
	v_mul_f32_e32 v155, v154, v155
	v_cndmask_b32_e32 v154, v154, v155, vcc
	v_mul_f32_e32 v155, 0xbfb8aa3b, v148
	v_exp_f32_e32 v155, v155
	s_nop 0
	v_add_f32_e32 v155, 1.0, v155
	v_rcp_f32_e32 v155, v155
	s_nop 0
	v_mul_f32_e32 v155, v148, v155
	v_cndmask_b32_e32 v155, v148, v155, vcc
	v_cvt_pk_bf16_f32 v148, v147, v149
	v_cvt_pk_bf16_f32 v149, v150, v151
	v_cvt_pk_bf16_f32 v150, v152, v153
	v_cvt_pk_bf16_f32 v151, v154, v155
	global_store_dwordx4 v[128:129], v[148:151], off offset:256
	s_nop 1
	v_or_b32_e32 v148, 16, v146
	v_ashrrev_i32_e32 v149, 31, v148
	v_lshl_add_u64 v[150:151], v[148:149], 3, s[36:37]
	s_nop 1
	v_mov_b64_e32 v[150:151], v[198:199]
	v_lshlrev_b64 v[148:149], 10, v[148:149]
	v_lshl_add_u64 v[148:149], v[144:145], 0, v[148:149]
	v_ffbh_u32_e32 v147, v151
	v_min_u32_e32 v147, 32, v147
	v_lshlrev_b64 v[150:151], v147, v[150:151]
	v_min_u32_e32 v150, 1, v150
	v_or_b32_e32 v150, v151, v150
	v_cvt_f32_u32_e32 v150, v150
	v_sub_u32_e32 v147, 32, v147
	v_ldexp_f32 v147, v150, v147
	v_mul_f32_e32 v147, 0x35800000, v147
	v_fmamk_f32 v147, v147, 0x3a800000, v219
	v_rsq_f32_e32 v147, v147
	s_nop 0
	v_mul_f32_e32 v150, v108, v147
	v_mul_f32_e32 v151, 0xbfb8aa3b, v150
	v_exp_f32_e32 v151, v151
	s_nop 0
	v_add_f32_e32 v151, 1.0, v151
	v_rcp_f32_e32 v151, v151
	s_nop 0
	v_mul_f32_e32 v151, v150, v151
	v_cndmask_b32_e32 v150, v150, v151, vcc
	v_mul_f32_e32 v151, v109, v147
	v_mul_f32_e32 v152, 0xbfb8aa3b, v151
	v_exp_f32_e32 v152, v152
	s_nop 0
	v_add_f32_e32 v152, 1.0, v152
	v_rcp_f32_e32 v152, v152
	s_nop 0
	v_mul_f32_e32 v152, v151, v152
	v_cndmask_b32_e32 v151, v151, v152, vcc
	v_mul_f32_e32 v152, v110, v147
	v_mul_f32_e32 v153, 0xbfb8aa3b, v152
	v_exp_f32_e32 v153, v153
	v_cvt_pk_bf16_f32 v150, v150, v151
	v_add_f32_e32 v153, 1.0, v153
	v_rcp_f32_e32 v153, v153
	s_nop 0
	v_mul_f32_e32 v153, v152, v153
	v_cndmask_b32_e32 v152, v152, v153, vcc
	v_mul_f32_e32 v153, v111, v147
	v_mul_f32_e32 v154, 0xbfb8aa3b, v153
	v_exp_f32_e32 v154, v154
	s_nop 0
	v_add_f32_e32 v154, 1.0, v154
	v_rcp_f32_e32 v154, v154
	s_nop 0
	v_mul_f32_e32 v154, v153, v154
	v_cndmask_b32_e32 v153, v153, v154, vcc
	v_mul_f32_e32 v154, v100, v147
	v_mul_f32_e32 v155, 0xbfb8aa3b, v154
	v_exp_f32_e32 v155, v155
	v_cvt_pk_bf16_f32 v151, v152, v153
	v_add_f32_e32 v155, 1.0, v155
	v_rcp_f32_e32 v155, v155
	s_nop 0
	v_mul_f32_e32 v155, v154, v155
	v_cndmask_b32_e32 v154, v154, v155, vcc
	v_mul_f32_e32 v155, v101, v147
	v_mul_f32_e32 v162, 0xbfb8aa3b, v155
	v_exp_f32_e32 v162, v162
	s_nop 0
	v_add_f32_e32 v162, 1.0, v162
	v_rcp_f32_e32 v162, v162
	s_nop 0
	v_mul_f32_e32 v162, v155, v162
	v_cndmask_b32_e32 v155, v155, v162, vcc
	v_mul_f32_e32 v162, v102, v147
	v_mul_f32_e32 v163, 0xbfb8aa3b, v162
	v_exp_f32_e32 v163, v163
	v_cvt_pk_bf16_f32 v152, v154, v155
	v_add_f32_e32 v163, 1.0, v163
	v_rcp_f32_e32 v163, v163
	s_nop 0
	v_mul_f32_e32 v163, v162, v163
	v_cndmask_b32_e32 v162, v162, v163, vcc
	v_mul_f32_e32 v163, v103, v147
	v_mul_f32_e32 v164, 0xbfb8aa3b, v163
	v_exp_f32_e32 v164, v164
	s_nop 0
	v_add_f32_e32 v164, 1.0, v164
	v_rcp_f32_e32 v164, v164
	s_nop 0
	v_mul_f32_e32 v164, v163, v164
	v_cndmask_b32_e32 v163, v163, v164, vcc
	v_cvt_pk_bf16_f32 v153, v162, v163
	global_store_dwordx4 v[148:149], v[150:153], off
	s_nop 1
	v_mul_f32_e32 v150, v104, v147
	v_mul_f32_e32 v151, 0xbfb8aa3b, v150
	v_exp_f32_e32 v151, v151
	s_nop 0
	v_add_f32_e32 v151, 1.0, v151
	v_rcp_f32_e32 v151, v151
	s_nop 0
	v_mul_f32_e32 v151, v150, v151
	v_cndmask_b32_e32 v150, v150, v151, vcc
	v_mul_f32_e32 v151, v105, v147
	v_mul_f32_e32 v152, 0xbfb8aa3b, v151
	v_exp_f32_e32 v152, v152
	s_nop 0
	v_add_f32_e32 v152, 1.0, v152
	v_rcp_f32_e32 v152, v152
	s_nop 0
	v_mul_f32_e32 v152, v151, v152
	v_cndmask_b32_e32 v151, v151, v152, vcc
	v_mul_f32_e32 v152, v106, v147
	v_mul_f32_e32 v153, 0xbfb8aa3b, v152
	v_exp_f32_e32 v153, v153
	v_cvt_pk_bf16_f32 v150, v150, v151
	v_add_f32_e32 v153, 1.0, v153
	v_rcp_f32_e32 v153, v153
	s_nop 0
	v_mul_f32_e32 v153, v152, v153
	v_cndmask_b32_e32 v152, v152, v153, vcc
	v_mul_f32_e32 v153, v107, v147
	v_mul_f32_e32 v154, 0xbfb8aa3b, v153
	v_exp_f32_e32 v154, v154
	s_nop 0
	v_add_f32_e32 v154, 1.0, v154
	v_rcp_f32_e32 v154, v154
	s_nop 0
	v_mul_f32_e32 v154, v153, v154
	v_cndmask_b32_e32 v153, v153, v154, vcc
	v_mul_f32_e32 v154, v96, v147
	v_mul_f32_e32 v155, 0xbfb8aa3b, v154
	v_exp_f32_e32 v155, v155
	v_cvt_pk_bf16_f32 v151, v152, v153
	v_add_f32_e32 v155, 1.0, v155
	v_rcp_f32_e32 v155, v155
	s_nop 0
	v_mul_f32_e32 v155, v154, v155
	v_cndmask_b32_e32 v154, v154, v155, vcc
	v_mul_f32_e32 v155, v97, v147
	v_mul_f32_e32 v162, 0xbfb8aa3b, v155
	v_exp_f32_e32 v162, v162
	s_nop 0
	v_add_f32_e32 v162, 1.0, v162
	v_rcp_f32_e32 v162, v162
	s_nop 0
	v_mul_f32_e32 v162, v155, v162
	v_cndmask_b32_e32 v155, v155, v162, vcc
	v_mul_f32_e32 v162, v98, v147
	v_mul_f32_e32 v163, 0xbfb8aa3b, v162
	v_exp_f32_e32 v163, v163
	v_mul_f32_e32 v147, v99, v147
	v_cvt_pk_bf16_f32 v152, v154, v155
	v_add_f32_e32 v163, 1.0, v163
	v_rcp_f32_e32 v163, v163
	s_nop 0
	v_mul_f32_e32 v163, v162, v163
	v_cndmask_b32_e32 v162, v162, v163, vcc
	v_mul_f32_e32 v163, 0xbfb8aa3b, v147
	v_exp_f32_e32 v163, v163
	s_nop 0
	v_add_f32_e32 v163, 1.0, v163
	v_rcp_f32_e32 v163, v163
	s_nop 0
	v_mul_f32_e32 v163, v147, v163
	v_cndmask_b32_e32 v147, v147, v163, vcc
	v_cvt_pk_bf16_f32 v153, v162, v147
	global_store_dwordx4 v[148:149], v[150:153], off offset:256
	v_or_b32_e32 v148, 32, v146
	v_ashrrev_i32_e32 v149, 31, v148
	v_lshl_add_u64 v[150:151], v[148:149], 3, s[36:37]
	s_nop 1
	v_mov_b64_e32 v[150:151], v[200:201]
	v_lshlrev_b64 v[148:149], 10, v[148:149]
	v_lshl_add_u64 v[148:149], v[144:145], 0, v[148:149]
	v_or_b32_e32 v146, 48, v146
	v_ffbh_u32_e32 v147, v151
	v_min_u32_e32 v147, 32, v147
	v_lshlrev_b64 v[150:151], v147, v[150:151]
	v_min_u32_e32 v150, 1, v150
	v_or_b32_e32 v150, v151, v150
	v_cvt_f32_u32_e32 v150, v150
	v_sub_u32_e32 v147, 32, v147
	v_ldexp_f32 v147, v150, v147
	v_mul_f32_e32 v147, 0x35800000, v147
	v_fmamk_f32 v147, v147, 0x3a800000, v219
	v_rsq_f32_e32 v147, v147
	s_nop 0
	v_mul_f32_e32 v150, v92, v147
	v_mul_f32_e32 v151, 0xbfb8aa3b, v150
	v_exp_f32_e32 v151, v151
	s_nop 0
	v_add_f32_e32 v151, 1.0, v151
	v_rcp_f32_e32 v151, v151
	s_nop 0
	v_mul_f32_e32 v151, v150, v151
	v_cndmask_b32_e32 v150, v150, v151, vcc
	v_mul_f32_e32 v151, v93, v147
	v_mul_f32_e32 v152, 0xbfb8aa3b, v151
	v_exp_f32_e32 v152, v152
	s_nop 0
	v_add_f32_e32 v152, 1.0, v152
	v_rcp_f32_e32 v152, v152
	s_nop 0
	v_mul_f32_e32 v152, v151, v152
	v_cndmask_b32_e32 v151, v151, v152, vcc
	v_mul_f32_e32 v152, v94, v147
	v_mul_f32_e32 v153, 0xbfb8aa3b, v152
	v_exp_f32_e32 v153, v153
	v_cvt_pk_bf16_f32 v150, v150, v151
	v_add_f32_e32 v153, 1.0, v153
	v_rcp_f32_e32 v153, v153
	s_nop 0
	v_mul_f32_e32 v153, v152, v153
	v_cndmask_b32_e32 v152, v152, v153, vcc
	v_mul_f32_e32 v153, v95, v147
	v_mul_f32_e32 v154, 0xbfb8aa3b, v153
	v_exp_f32_e32 v154, v154
	s_nop 0
	v_add_f32_e32 v154, 1.0, v154
	v_rcp_f32_e32 v154, v154
	s_nop 0
	v_mul_f32_e32 v154, v153, v154
	v_cndmask_b32_e32 v153, v153, v154, vcc
	v_mul_f32_e32 v154, v84, v147
	v_mul_f32_e32 v155, 0xbfb8aa3b, v154
	v_exp_f32_e32 v155, v155
	v_cvt_pk_bf16_f32 v151, v152, v153
	v_add_f32_e32 v155, 1.0, v155
	v_rcp_f32_e32 v155, v155
	s_nop 0
	v_mul_f32_e32 v155, v154, v155
	v_cndmask_b32_e32 v154, v154, v155, vcc
	v_mul_f32_e32 v155, v85, v147
	v_mul_f32_e32 v162, 0xbfb8aa3b, v155
	v_exp_f32_e32 v162, v162
	s_nop 0
	v_add_f32_e32 v162, 1.0, v162
	v_rcp_f32_e32 v162, v162
	s_nop 0
	v_mul_f32_e32 v162, v155, v162
	v_cndmask_b32_e32 v155, v155, v162, vcc
	v_mul_f32_e32 v162, v86, v147
	v_mul_f32_e32 v163, 0xbfb8aa3b, v162
	v_exp_f32_e32 v163, v163
	v_cvt_pk_bf16_f32 v152, v154, v155
	v_add_f32_e32 v163, 1.0, v163
	v_rcp_f32_e32 v163, v163
	s_nop 0
	v_mul_f32_e32 v163, v162, v163
	v_cndmask_b32_e32 v162, v162, v163, vcc
	v_mul_f32_e32 v163, v87, v147
	v_mul_f32_e32 v164, 0xbfb8aa3b, v163
	v_exp_f32_e32 v164, v164
	s_nop 0
	v_add_f32_e32 v164, 1.0, v164
	v_rcp_f32_e32 v164, v164
	s_nop 0
	v_mul_f32_e32 v164, v163, v164
	v_cndmask_b32_e32 v163, v163, v164, vcc
	v_cvt_pk_bf16_f32 v153, v162, v163
	global_store_dwordx4 v[148:149], v[150:153], off
	s_nop 1
	v_mul_f32_e32 v150, v88, v147
	v_mul_f32_e32 v151, 0xbfb8aa3b, v150
	v_exp_f32_e32 v151, v151
	s_nop 0
	v_add_f32_e32 v151, 1.0, v151
	v_rcp_f32_e32 v151, v151
	s_nop 0
	v_mul_f32_e32 v151, v150, v151
	v_cndmask_b32_e32 v150, v150, v151, vcc
	v_mul_f32_e32 v151, v89, v147
	v_mul_f32_e32 v152, 0xbfb8aa3b, v151
	v_exp_f32_e32 v152, v152
	s_nop 0
	v_add_f32_e32 v152, 1.0, v152
	v_rcp_f32_e32 v152, v152
	s_nop 0
	v_mul_f32_e32 v152, v151, v152
	v_cndmask_b32_e32 v151, v151, v152, vcc
	v_mul_f32_e32 v152, v90, v147
	v_mul_f32_e32 v153, 0xbfb8aa3b, v152
	v_exp_f32_e32 v153, v153
	v_cvt_pk_bf16_f32 v150, v150, v151
	v_add_f32_e32 v153, 1.0, v153
	v_rcp_f32_e32 v153, v153
	s_nop 0
	v_mul_f32_e32 v153, v152, v153
	v_cndmask_b32_e32 v152, v152, v153, vcc
	v_mul_f32_e32 v153, v91, v147
	v_mul_f32_e32 v154, 0xbfb8aa3b, v153
	v_exp_f32_e32 v154, v154
	s_nop 0
	v_add_f32_e32 v154, 1.0, v154
	v_rcp_f32_e32 v154, v154
	s_nop 0
	v_mul_f32_e32 v154, v153, v154
	v_cndmask_b32_e32 v153, v153, v154, vcc
	v_mul_f32_e32 v154, v80, v147
	v_mul_f32_e32 v155, 0xbfb8aa3b, v154
	v_exp_f32_e32 v155, v155
	v_cvt_pk_bf16_f32 v151, v152, v153
	v_add_f32_e32 v155, 1.0, v155
	v_rcp_f32_e32 v155, v155
	s_nop 0
	v_mul_f32_e32 v155, v154, v155
	v_cndmask_b32_e32 v154, v154, v155, vcc
	v_mul_f32_e32 v155, v81, v147
	v_mul_f32_e32 v162, 0xbfb8aa3b, v155
	v_exp_f32_e32 v162, v162
	s_nop 0
	v_add_f32_e32 v162, 1.0, v162
	v_rcp_f32_e32 v162, v162
	s_nop 0
	v_mul_f32_e32 v162, v155, v162
	v_cndmask_b32_e32 v155, v155, v162, vcc
	v_mul_f32_e32 v162, v82, v147
	v_mul_f32_e32 v163, 0xbfb8aa3b, v162
	v_exp_f32_e32 v163, v163
	v_mul_f32_e32 v147, v83, v147
	v_cvt_pk_bf16_f32 v152, v154, v155
	v_add_f32_e32 v163, 1.0, v163
	v_rcp_f32_e32 v163, v163
	s_nop 0
	v_mul_f32_e32 v163, v162, v163
	v_cndmask_b32_e32 v162, v162, v163, vcc
	v_mul_f32_e32 v163, 0xbfb8aa3b, v147
	v_exp_f32_e32 v163, v163
	s_nop 0
	v_add_f32_e32 v163, 1.0, v163
	v_rcp_f32_e32 v163, v163
	s_nop 0
	v_mul_f32_e32 v163, v147, v163
	v_cndmask_b32_e32 v147, v147, v163, vcc
	v_cvt_pk_bf16_f32 v153, v162, v147
	global_store_dwordx4 v[148:149], v[150:153], off offset:256
	v_ashrrev_i32_e32 v147, 31, v146
	v_lshl_add_u64 v[148:149], v[146:147], 3, s[36:37]
	s_nop 1
	v_mov_b64_e32 v[148:149], v[202:203]
	v_lshlrev_b64 v[146:147], 10, v[146:147]
	v_lshl_add_u64 v[144:145], v[144:145], 0, v[146:147]
	v_ffbh_u32_e32 v150, v149
	v_min_u32_e32 v150, 32, v150
	v_lshlrev_b64 v[148:149], v150, v[148:149]
	v_min_u32_e32 v148, 1, v148
	v_or_b32_e32 v148, v149, v148
	v_cvt_f32_u32_e32 v148, v148
	v_sub_u32_e32 v149, 32, v150
	v_ldexp_f32 v148, v148, v149
	v_mul_f32_e32 v148, 0x35800000, v148
	v_fmamk_f32 v148, v148, 0x3a800000, v219
	v_rsq_f32_e32 v150, v148
	s_nop 0
	v_mul_f32_e32 v146, v76, v150
	v_mul_f32_e32 v147, 0xbfb8aa3b, v146
	v_exp_f32_e32 v147, v147
	s_nop 0
	v_add_f32_e32 v147, 1.0, v147
	v_rcp_f32_e32 v147, v147
	s_nop 0
	v_mul_f32_e32 v147, v146, v147
	v_cndmask_b32_e32 v146, v146, v147, vcc
	v_mul_f32_e32 v147, v77, v150
	v_mul_f32_e32 v148, 0xbfb8aa3b, v147
	v_exp_f32_e32 v148, v148
	s_nop 0
	v_add_f32_e32 v148, 1.0, v148
	v_rcp_f32_e32 v148, v148
	s_nop 0
	v_mul_f32_e32 v148, v147, v148
	v_cndmask_b32_e32 v147, v147, v148, vcc
	v_mul_f32_e32 v148, v78, v150
	v_mul_f32_e32 v149, 0xbfb8aa3b, v148
	v_exp_f32_e32 v149, v149
	v_cvt_pk_bf16_f32 v146, v146, v147
	v_add_f32_e32 v149, 1.0, v149
	v_rcp_f32_e32 v149, v149
	s_nop 0
	v_mul_f32_e32 v149, v148, v149
	v_cndmask_b32_e32 v148, v148, v149, vcc
	v_mul_f32_e32 v149, v79, v150
	v_mul_f32_e32 v151, 0xbfb8aa3b, v149
	v_exp_f32_e32 v151, v151
	s_nop 0
	v_add_f32_e32 v151, 1.0, v151
	v_rcp_f32_e32 v151, v151
	s_nop 0
	v_mul_f32_e32 v151, v149, v151
	v_cndmask_b32_e32 v149, v149, v151, vcc
	v_mul_f32_e32 v151, v68, v150
	v_mul_f32_e32 v152, 0xbfb8aa3b, v151
	v_exp_f32_e32 v152, v152
	v_cvt_pk_bf16_f32 v147, v148, v149
	v_add_f32_e32 v152, 1.0, v152
	v_rcp_f32_e32 v152, v152
	s_nop 0
	v_mul_f32_e32 v152, v151, v152
	v_cndmask_b32_e32 v151, v151, v152, vcc
	v_mul_f32_e32 v152, v69, v150
	v_mul_f32_e32 v153, 0xbfb8aa3b, v152
	v_exp_f32_e32 v153, v153
	s_nop 0
	v_add_f32_e32 v153, 1.0, v153
	v_rcp_f32_e32 v153, v153
	s_nop 0
	v_mul_f32_e32 v153, v152, v153
	v_cndmask_b32_e32 v152, v152, v153, vcc
	v_mul_f32_e32 v153, v70, v150
	v_mul_f32_e32 v154, 0xbfb8aa3b, v153
	v_exp_f32_e32 v154, v154
	v_cvt_pk_bf16_f32 v148, v151, v152
	v_add_f32_e32 v154, 1.0, v154
	v_rcp_f32_e32 v154, v154
	s_nop 0
	v_mul_f32_e32 v154, v153, v154
	v_cndmask_b32_e32 v153, v153, v154, vcc
	v_mul_f32_e32 v154, v71, v150
	v_mul_f32_e32 v155, 0xbfb8aa3b, v154
	v_exp_f32_e32 v155, v155
	s_nop 0
	v_add_f32_e32 v155, 1.0, v155
	v_rcp_f32_e32 v155, v155
	s_nop 0
	v_mul_f32_e32 v155, v154, v155
	v_cndmask_b32_e32 v154, v154, v155, vcc
	v_cvt_pk_bf16_f32 v149, v153, v154
	global_store_dwordx4 v[144:145], v[146:149], off
	s_nop 1
	v_mul_f32_e32 v146, v72, v150
	v_mul_f32_e32 v147, 0xbfb8aa3b, v146
	v_exp_f32_e32 v147, v147
	s_nop 0
	v_add_f32_e32 v147, 1.0, v147
	v_rcp_f32_e32 v147, v147
	s_nop 0
	v_mul_f32_e32 v147, v146, v147
	v_cndmask_b32_e32 v146, v146, v147, vcc
	v_mul_f32_e32 v147, v73, v150
	v_mul_f32_e32 v148, 0xbfb8aa3b, v147
	v_exp_f32_e32 v148, v148
	s_nop 0
	v_add_f32_e32 v148, 1.0, v148
	v_rcp_f32_e32 v148, v148
	s_nop 0
	v_mul_f32_e32 v148, v147, v148
	v_cndmask_b32_e32 v147, v147, v148, vcc
	v_mul_f32_e32 v148, v74, v150
	v_mul_f32_e32 v149, 0xbfb8aa3b, v148
	v_exp_f32_e32 v149, v149
	v_cvt_pk_bf16_f32 v146, v146, v147
	v_add_f32_e32 v149, 1.0, v149
	v_rcp_f32_e32 v149, v149
	s_nop 0
	v_mul_f32_e32 v149, v148, v149
	v_cndmask_b32_e32 v148, v148, v149, vcc
	v_mul_f32_e32 v149, v75, v150
	v_mul_f32_e32 v151, 0xbfb8aa3b, v149
	v_exp_f32_e32 v151, v151
	s_nop 0
	v_add_f32_e32 v151, 1.0, v151
	v_rcp_f32_e32 v151, v151
	s_nop 0
	v_mul_f32_e32 v151, v149, v151
	v_cndmask_b32_e32 v149, v149, v151, vcc
	v_mul_f32_e32 v151, v64, v150
	v_mul_f32_e32 v152, 0xbfb8aa3b, v151
	v_exp_f32_e32 v152, v152
	v_cvt_pk_bf16_f32 v147, v148, v149
	v_add_f32_e32 v152, 1.0, v152
	v_rcp_f32_e32 v152, v152
	s_nop 0
	v_mul_f32_e32 v152, v151, v152
	v_cndmask_b32_e32 v151, v151, v152, vcc
	v_mul_f32_e32 v152, v65, v150
	v_mul_f32_e32 v153, 0xbfb8aa3b, v152
	v_exp_f32_e32 v153, v153
	s_nop 0
	v_add_f32_e32 v153, 1.0, v153
	v_rcp_f32_e32 v153, v153
	s_nop 0
	v_mul_f32_e32 v153, v152, v153
	v_cndmask_b32_e32 v152, v152, v153, vcc
	v_mul_f32_e32 v153, v66, v150
	v_mul_f32_e32 v154, 0xbfb8aa3b, v153
	v_exp_f32_e32 v154, v154
	v_mul_f32_e32 v150, v67, v150
	v_cvt_pk_bf16_f32 v148, v151, v152
	v_add_f32_e32 v154, 1.0, v154
	v_rcp_f32_e32 v154, v154
	s_nop 0
	v_mul_f32_e32 v154, v153, v154
	v_cndmask_b32_e32 v153, v153, v154, vcc
	v_mul_f32_e32 v154, 0xbfb8aa3b, v150
	v_exp_f32_e32 v154, v154
	s_nop 0
	v_add_f32_e32 v154, 1.0, v154
	v_rcp_f32_e32 v154, v154
	s_nop 0
	v_mul_f32_e32 v154, v150, v154
	v_cndmask_b32_e32 v150, v150, v154, vcc
	v_cvt_pk_bf16_f32 v149, v153, v150
	global_store_dwordx4 v[144:145], v[146:149], off offset:256
	s_nop 1
	v_mov_b64_e32 v[144:145], v[204:205]
	v_ffbh_u32_e32 v146, v145
	v_min_u32_e32 v146, 32, v146
	v_lshlrev_b64 v[144:145], v146, v[144:145]
	v_min_u32_e32 v144, 1, v144
	v_or_b32_e32 v144, v145, v144
	v_cvt_f32_u32_e32 v144, v144
	v_sub_u32_e32 v145, 32, v146
	v_ldexp_f32 v144, v144, v145
	v_mul_f32_e32 v144, 0x35800000, v144
	v_fmamk_f32 v144, v144, 0x3a800000, v219
	v_rsq_f32_e32 v152, v144
	v_lshl_add_u64 v[144:145], v[128:129], 0, s[0:1]
	s_mov_b32 s0, 0x20000
	v_mul_f32_e32 v146, v60, v152
	v_mul_f32_e32 v147, 0xbfb8aa3b, v146
	v_exp_f32_e32 v147, v147
	s_nop 0
	v_add_f32_e32 v147, 1.0, v147
	v_rcp_f32_e32 v147, v147
	s_nop 0
	v_mul_f32_e32 v147, v146, v147
	v_cndmask_b32_e32 v146, v146, v147, vcc
	v_mul_f32_e32 v147, v61, v152
	v_mul_f32_e32 v148, 0xbfb8aa3b, v147
	v_exp_f32_e32 v148, v148
	s_nop 0
	v_add_f32_e32 v148, 1.0, v148
	v_rcp_f32_e32 v148, v148
	s_nop 0
	v_mul_f32_e32 v148, v147, v148
	v_cndmask_b32_e32 v147, v147, v148, vcc
	v_mul_f32_e32 v148, v62, v152
	v_mul_f32_e32 v149, 0xbfb8aa3b, v148
	v_exp_f32_e32 v149, v149
	v_cvt_pk_bf16_f32 v146, v146, v147
	v_add_f32_e32 v149, 1.0, v149
	v_rcp_f32_e32 v149, v149
	s_nop 0
	v_mul_f32_e32 v149, v148, v149
	v_cndmask_b32_e32 v148, v148, v149, vcc
	v_mul_f32_e32 v149, v63, v152
	v_mul_f32_e32 v150, 0xbfb8aa3b, v149
	v_exp_f32_e32 v150, v150
	s_nop 0
	v_add_f32_e32 v150, 1.0, v150
	v_rcp_f32_e32 v150, v150
	s_nop 0
	v_mul_f32_e32 v150, v149, v150
	v_cndmask_b32_e32 v149, v149, v150, vcc
	v_mul_f32_e32 v150, v52, v152
	v_mul_f32_e32 v151, 0xbfb8aa3b, v150
	v_exp_f32_e32 v151, v151
	v_cvt_pk_bf16_f32 v147, v148, v149
	v_add_f32_e32 v151, 1.0, v151
	v_rcp_f32_e32 v151, v151
	s_nop 0
	v_mul_f32_e32 v151, v150, v151
	v_cndmask_b32_e32 v150, v150, v151, vcc
	v_mul_f32_e32 v151, v53, v152
	v_mul_f32_e32 v153, 0xbfb8aa3b, v151
	v_exp_f32_e32 v153, v153
	s_nop 0
	v_add_f32_e32 v153, 1.0, v153
	v_rcp_f32_e32 v153, v153
	s_nop 0
	v_mul_f32_e32 v153, v151, v153
	v_cndmask_b32_e32 v151, v151, v153, vcc
	v_mul_f32_e32 v153, v54, v152
	v_mul_f32_e32 v154, 0xbfb8aa3b, v153
	v_exp_f32_e32 v154, v154
	v_cvt_pk_bf16_f32 v148, v150, v151
	v_add_co_u32_e64 v150, s[0:1], s0, v128
	v_add_f32_e32 v154, 1.0, v154
	v_rcp_f32_e32 v154, v154
	v_addc_co_u32_e64 v151, s[0:1], 0, v129, s[0:1]
	s_mov_b64 s[0:1], 0x24000
	v_mul_f32_e32 v154, v153, v154
	v_cndmask_b32_e32 v153, v153, v154, vcc
	v_mul_f32_e32 v154, v55, v152
	v_mul_f32_e32 v155, 0xbfb8aa3b, v154
	v_exp_f32_e32 v155, v155
	s_nop 0
	v_add_f32_e32 v155, 1.0, v155
	v_rcp_f32_e32 v155, v155
	s_nop 0
	v_mul_f32_e32 v155, v154, v155
	v_cndmask_b32_e32 v154, v154, v155, vcc
	v_cvt_pk_bf16_f32 v149, v153, v154
	global_store_dwordx4 v[150:151], v[146:149], off
	s_nop 1
	v_mul_f32_e32 v146, v56, v152
	v_mul_f32_e32 v147, 0xbfb8aa3b, v146
	v_exp_f32_e32 v147, v147
	s_nop 0
	v_add_f32_e32 v147, 1.0, v147
	v_rcp_f32_e32 v147, v147
	s_nop 0
	v_mul_f32_e32 v147, v146, v147
	v_cndmask_b32_e32 v146, v146, v147, vcc
	v_mul_f32_e32 v147, v57, v152
	v_mul_f32_e32 v148, 0xbfb8aa3b, v147
	v_exp_f32_e32 v148, v148
	s_nop 0
	v_add_f32_e32 v148, 1.0, v148
	v_rcp_f32_e32 v148, v148
	s_nop 0
	v_mul_f32_e32 v148, v147, v148
	v_cndmask_b32_e32 v147, v147, v148, vcc
	v_mul_f32_e32 v148, v58, v152
	v_mul_f32_e32 v149, 0xbfb8aa3b, v148
	v_exp_f32_e32 v149, v149
	v_cvt_pk_bf16_f32 v146, v146, v147
	v_add_f32_e32 v149, 1.0, v149
	v_rcp_f32_e32 v149, v149
	s_nop 0
	v_mul_f32_e32 v149, v148, v149
	v_cndmask_b32_e32 v148, v148, v149, vcc
	v_mul_f32_e32 v149, v59, v152
	v_mul_f32_e32 v150, 0xbfb8aa3b, v149
	v_exp_f32_e32 v150, v150
	s_nop 0
	v_add_f32_e32 v150, 1.0, v150
	v_rcp_f32_e32 v150, v150
	s_nop 0
	v_mul_f32_e32 v150, v149, v150
	v_cndmask_b32_e32 v149, v149, v150, vcc
	v_mul_f32_e32 v150, v48, v152
	v_mul_f32_e32 v151, 0xbfb8aa3b, v150
	v_exp_f32_e32 v151, v151
	v_cvt_pk_bf16_f32 v147, v148, v149
	v_add_f32_e32 v151, 1.0, v151
	v_rcp_f32_e32 v151, v151
	s_nop 0
	v_mul_f32_e32 v151, v150, v151
	v_cndmask_b32_e32 v150, v150, v151, vcc
	v_mul_f32_e32 v151, v49, v152
	v_mul_f32_e32 v153, 0xbfb8aa3b, v151
	v_exp_f32_e32 v153, v153
	s_nop 0
	v_add_f32_e32 v153, 1.0, v153
	v_rcp_f32_e32 v153, v153
	s_nop 0
	v_mul_f32_e32 v153, v151, v153
	v_cndmask_b32_e32 v151, v151, v153, vcc
	v_mul_f32_e32 v153, v50, v152
	v_mul_f32_e32 v154, 0xbfb8aa3b, v153
	v_exp_f32_e32 v154, v154
	v_mul_f32_e32 v152, v51, v152
	v_cvt_pk_bf16_f32 v148, v150, v151
	v_add_f32_e32 v154, 1.0, v154
	v_rcp_f32_e32 v154, v154
	s_nop 0
	v_mul_f32_e32 v154, v153, v154
	v_cndmask_b32_e32 v153, v153, v154, vcc
	v_mul_f32_e32 v154, 0xbfb8aa3b, v152
	v_exp_f32_e32 v154, v154
	s_nop 0
	v_add_f32_e32 v154, 1.0, v154
	v_rcp_f32_e32 v154, v154
	s_nop 0
	v_mul_f32_e32 v154, v152, v154
	v_cndmask_b32_e32 v152, v152, v154, vcc
	v_cvt_pk_bf16_f32 v149, v153, v152
	global_store_dwordx4 v[144:145], v[146:149], off offset:256
	s_nop 1
	v_mov_b64_e32 v[144:145], v[206:207]
	v_ffbh_u32_e32 v146, v145
	v_min_u32_e32 v146, 32, v146
	v_lshlrev_b64 v[144:145], v146, v[144:145]
	v_min_u32_e32 v144, 1, v144
	v_or_b32_e32 v144, v145, v144
	v_cvt_f32_u32_e32 v144, v144
	v_sub_u32_e32 v145, 32, v146
	v_ldexp_f32 v144, v144, v145
	v_mul_f32_e32 v144, 0x35800000, v144
	v_fmamk_f32 v144, v144, 0x3a800000, v219
	v_rsq_f32_e32 v152, v144
	v_lshl_add_u64 v[144:145], v[128:129], 0, s[0:1]
	s_mov_b32 s0, 0x24000
	v_mul_f32_e32 v146, v44, v152
	v_mul_f32_e32 v147, 0xbfb8aa3b, v146
	v_exp_f32_e32 v147, v147
	s_nop 0
	v_add_f32_e32 v147, 1.0, v147
	v_rcp_f32_e32 v147, v147
	s_nop 0
	v_mul_f32_e32 v147, v146, v147
	v_cndmask_b32_e32 v146, v146, v147, vcc
	v_mul_f32_e32 v147, v45, v152
	v_mul_f32_e32 v148, 0xbfb8aa3b, v147
	v_exp_f32_e32 v148, v148
	s_nop 0
	v_add_f32_e32 v148, 1.0, v148
	v_rcp_f32_e32 v148, v148
	s_nop 0
	v_mul_f32_e32 v148, v147, v148
	v_cndmask_b32_e32 v147, v147, v148, vcc
	v_mul_f32_e32 v148, v46, v152
	v_mul_f32_e32 v149, 0xbfb8aa3b, v148
	v_exp_f32_e32 v149, v149
	v_cvt_pk_bf16_f32 v146, v146, v147
	v_add_f32_e32 v149, 1.0, v149
	v_rcp_f32_e32 v149, v149
	s_nop 0
	v_mul_f32_e32 v149, v148, v149
	v_cndmask_b32_e32 v148, v148, v149, vcc
	v_mul_f32_e32 v149, v47, v152
	v_mul_f32_e32 v150, 0xbfb8aa3b, v149
	v_exp_f32_e32 v150, v150
	s_nop 0
	v_add_f32_e32 v150, 1.0, v150
	v_rcp_f32_e32 v150, v150
	s_nop 0
	v_mul_f32_e32 v150, v149, v150
	v_cndmask_b32_e32 v149, v149, v150, vcc
	v_mul_f32_e32 v150, v36, v152
	v_mul_f32_e32 v151, 0xbfb8aa3b, v150
	v_exp_f32_e32 v151, v151
	v_cvt_pk_bf16_f32 v147, v148, v149
	v_add_f32_e32 v151, 1.0, v151
	v_rcp_f32_e32 v151, v151
	s_nop 0
	v_mul_f32_e32 v151, v150, v151
	v_cndmask_b32_e32 v150, v150, v151, vcc
	v_mul_f32_e32 v151, v37, v152
	v_mul_f32_e32 v153, 0xbfb8aa3b, v151
	v_exp_f32_e32 v153, v153
	s_nop 0
	v_add_f32_e32 v153, 1.0, v153
	v_rcp_f32_e32 v153, v153
	s_nop 0
	v_mul_f32_e32 v153, v151, v153
	v_cndmask_b32_e32 v151, v151, v153, vcc
	v_mul_f32_e32 v153, v38, v152
	v_mul_f32_e32 v154, 0xbfb8aa3b, v153
	v_exp_f32_e32 v154, v154
	v_cvt_pk_bf16_f32 v148, v150, v151
	v_add_co_u32_e64 v150, s[0:1], s0, v128
	v_add_f32_e32 v154, 1.0, v154
	v_rcp_f32_e32 v154, v154
	v_addc_co_u32_e64 v151, s[0:1], 0, v129, s[0:1]
	s_mov_b64 s[0:1], 0x28000
	v_mul_f32_e32 v154, v153, v154
	v_cndmask_b32_e32 v153, v153, v154, vcc
	v_mul_f32_e32 v154, v39, v152
	v_mul_f32_e32 v155, 0xbfb8aa3b, v154
	v_exp_f32_e32 v155, v155
	s_nop 0
	v_add_f32_e32 v155, 1.0, v155
	v_rcp_f32_e32 v155, v155
	s_nop 0
	v_mul_f32_e32 v155, v154, v155
	v_cndmask_b32_e32 v154, v154, v155, vcc
	v_cvt_pk_bf16_f32 v149, v153, v154
	global_store_dwordx4 v[150:151], v[146:149], off
	s_nop 1
	v_mul_f32_e32 v146, v40, v152
	v_mul_f32_e32 v147, 0xbfb8aa3b, v146
	v_exp_f32_e32 v147, v147
	s_nop 0
	v_add_f32_e32 v147, 1.0, v147
	v_rcp_f32_e32 v147, v147
	s_nop 0
	v_mul_f32_e32 v147, v146, v147
	v_cndmask_b32_e32 v146, v146, v147, vcc
	v_mul_f32_e32 v147, v41, v152
	v_mul_f32_e32 v148, 0xbfb8aa3b, v147
	v_exp_f32_e32 v148, v148
	s_nop 0
	v_add_f32_e32 v148, 1.0, v148
	v_rcp_f32_e32 v148, v148
	s_nop 0
	v_mul_f32_e32 v148, v147, v148
	v_cndmask_b32_e32 v147, v147, v148, vcc
	v_mul_f32_e32 v148, v42, v152
	v_mul_f32_e32 v149, 0xbfb8aa3b, v148
	v_exp_f32_e32 v149, v149
	v_cvt_pk_bf16_f32 v146, v146, v147
	v_add_f32_e32 v149, 1.0, v149
	v_rcp_f32_e32 v149, v149
	s_nop 0
	v_mul_f32_e32 v149, v148, v149
	v_cndmask_b32_e32 v148, v148, v149, vcc
	v_mul_f32_e32 v149, v43, v152
	v_mul_f32_e32 v150, 0xbfb8aa3b, v149
	v_exp_f32_e32 v150, v150
	s_nop 0
	v_add_f32_e32 v150, 1.0, v150
	v_rcp_f32_e32 v150, v150
	s_nop 0
	v_mul_f32_e32 v150, v149, v150
	v_cndmask_b32_e32 v149, v149, v150, vcc
	v_mul_f32_e32 v150, v32, v152
	v_mul_f32_e32 v151, 0xbfb8aa3b, v150
	v_exp_f32_e32 v151, v151
	v_cvt_pk_bf16_f32 v147, v148, v149
	v_add_f32_e32 v151, 1.0, v151
	v_rcp_f32_e32 v151, v151
	s_nop 0
	v_mul_f32_e32 v151, v150, v151
	v_cndmask_b32_e32 v150, v150, v151, vcc
	v_mul_f32_e32 v151, v33, v152
	v_mul_f32_e32 v153, 0xbfb8aa3b, v151
	v_exp_f32_e32 v153, v153
	s_nop 0
	v_add_f32_e32 v153, 1.0, v153
	v_rcp_f32_e32 v153, v153
	s_nop 0
	v_mul_f32_e32 v153, v151, v153
	v_cndmask_b32_e32 v151, v151, v153, vcc
	v_mul_f32_e32 v153, v34, v152
	v_mul_f32_e32 v154, 0xbfb8aa3b, v153
	v_exp_f32_e32 v154, v154
	v_mul_f32_e32 v152, v35, v152
	v_cvt_pk_bf16_f32 v148, v150, v151
	v_add_f32_e32 v154, 1.0, v154
	v_rcp_f32_e32 v154, v154
	s_nop 0
	v_mul_f32_e32 v154, v153, v154
	v_cndmask_b32_e32 v153, v153, v154, vcc
	v_mul_f32_e32 v154, 0xbfb8aa3b, v152
	v_exp_f32_e32 v154, v154
	s_nop 0
	v_add_f32_e32 v154, 1.0, v154
	v_rcp_f32_e32 v154, v154
	s_nop 0
	v_mul_f32_e32 v154, v152, v154
	v_cndmask_b32_e32 v152, v152, v154, vcc
	v_cvt_pk_bf16_f32 v149, v153, v152
	global_store_dwordx4 v[144:145], v[146:149], off offset:256
	s_nop 1
	v_mov_b64_e32 v[144:145], v[208:209]
	v_ffbh_u32_e32 v146, v145
	v_min_u32_e32 v146, 32, v146
	v_lshlrev_b64 v[144:145], v146, v[144:145]
	v_min_u32_e32 v144, 1, v144
	v_or_b32_e32 v144, v145, v144
	v_cvt_f32_u32_e32 v144, v144
	v_sub_u32_e32 v145, 32, v146
	v_ldexp_f32 v144, v144, v145
	v_mul_f32_e32 v144, 0x35800000, v144
	v_fmamk_f32 v144, v144, 0x3a800000, v219
	v_rsq_f32_e32 v152, v144
	v_lshl_add_u64 v[144:145], v[128:129], 0, s[0:1]
	s_mov_b32 s0, 0x28000
	v_mul_f32_e32 v146, v28, v152
	v_mul_f32_e32 v147, 0xbfb8aa3b, v146
	v_exp_f32_e32 v147, v147
	s_nop 0
	v_add_f32_e32 v147, 1.0, v147
	v_rcp_f32_e32 v147, v147
	s_nop 0
	v_mul_f32_e32 v147, v146, v147
	v_cndmask_b32_e32 v146, v146, v147, vcc
	v_mul_f32_e32 v147, v29, v152
	v_mul_f32_e32 v148, 0xbfb8aa3b, v147
	v_exp_f32_e32 v148, v148
	s_nop 0
	v_add_f32_e32 v148, 1.0, v148
	v_rcp_f32_e32 v148, v148
	s_nop 0
	v_mul_f32_e32 v148, v147, v148
	v_cndmask_b32_e32 v147, v147, v148, vcc
	v_mul_f32_e32 v148, v30, v152
	v_mul_f32_e32 v149, 0xbfb8aa3b, v148
	v_exp_f32_e32 v149, v149
	v_cvt_pk_bf16_f32 v146, v146, v147
	v_add_f32_e32 v149, 1.0, v149
	v_rcp_f32_e32 v149, v149
	s_nop 0
	v_mul_f32_e32 v149, v148, v149
	v_cndmask_b32_e32 v148, v148, v149, vcc
	v_mul_f32_e32 v149, v31, v152
	v_mul_f32_e32 v150, 0xbfb8aa3b, v149
	v_exp_f32_e32 v150, v150
	s_nop 0
	v_add_f32_e32 v150, 1.0, v150
	v_rcp_f32_e32 v150, v150
	s_nop 0
	v_mul_f32_e32 v150, v149, v150
	v_cndmask_b32_e32 v149, v149, v150, vcc
	v_mul_f32_e32 v150, v20, v152
	v_mul_f32_e32 v151, 0xbfb8aa3b, v150
	v_exp_f32_e32 v151, v151
	v_cvt_pk_bf16_f32 v147, v148, v149
	v_add_f32_e32 v151, 1.0, v151
	v_rcp_f32_e32 v151, v151
	s_nop 0
	v_mul_f32_e32 v151, v150, v151
	v_cndmask_b32_e32 v150, v150, v151, vcc
	v_mul_f32_e32 v151, v21, v152
	v_mul_f32_e32 v153, 0xbfb8aa3b, v151
	v_exp_f32_e32 v153, v153
	s_nop 0
	v_add_f32_e32 v153, 1.0, v153
	v_rcp_f32_e32 v153, v153
	s_nop 0
	v_mul_f32_e32 v153, v151, v153
	v_cndmask_b32_e32 v151, v151, v153, vcc
	v_mul_f32_e32 v153, v22, v152
	v_mul_f32_e32 v154, 0xbfb8aa3b, v153
	v_exp_f32_e32 v154, v154
	v_cvt_pk_bf16_f32 v148, v150, v151
	v_add_co_u32_e64 v150, s[0:1], s0, v128
	v_add_f32_e32 v154, 1.0, v154
	v_rcp_f32_e32 v154, v154
	v_addc_co_u32_e64 v151, s[0:1], 0, v129, s[0:1]
	s_mov_b64 s[0:1], 0x2c000
	v_mul_f32_e32 v154, v153, v154
	v_cndmask_b32_e32 v153, v153, v154, vcc
	v_mul_f32_e32 v154, v23, v152
	v_mul_f32_e32 v155, 0xbfb8aa3b, v154
	v_exp_f32_e32 v155, v155
	s_nop 0
	v_add_f32_e32 v155, 1.0, v155
	v_rcp_f32_e32 v155, v155
	s_nop 0
	v_mul_f32_e32 v155, v154, v155
	v_cndmask_b32_e32 v154, v154, v155, vcc
	v_cvt_pk_bf16_f32 v149, v153, v154
	global_store_dwordx4 v[150:151], v[146:149], off
	s_nop 1
	v_mul_f32_e32 v146, v24, v152
	v_mul_f32_e32 v147, 0xbfb8aa3b, v146
	v_exp_f32_e32 v147, v147
	s_nop 0
	v_add_f32_e32 v147, 1.0, v147
	v_rcp_f32_e32 v147, v147
	s_nop 0
	v_mul_f32_e32 v147, v146, v147
	v_cndmask_b32_e32 v146, v146, v147, vcc
	v_mul_f32_e32 v147, v25, v152
	v_mul_f32_e32 v148, 0xbfb8aa3b, v147
	v_exp_f32_e32 v148, v148
	s_nop 0
	v_add_f32_e32 v148, 1.0, v148
	v_rcp_f32_e32 v148, v148
	s_nop 0
	v_mul_f32_e32 v148, v147, v148
	v_cndmask_b32_e32 v147, v147, v148, vcc
	v_mul_f32_e32 v148, v26, v152
	v_mul_f32_e32 v149, 0xbfb8aa3b, v148
	v_exp_f32_e32 v149, v149
	v_cvt_pk_bf16_f32 v146, v146, v147
	v_add_f32_e32 v149, 1.0, v149
	v_rcp_f32_e32 v149, v149
	s_nop 0
	v_mul_f32_e32 v149, v148, v149
	v_cndmask_b32_e32 v148, v148, v149, vcc
	v_mul_f32_e32 v149, v27, v152
	v_mul_f32_e32 v150, 0xbfb8aa3b, v149
	v_exp_f32_e32 v150, v150
	s_nop 0
	v_add_f32_e32 v150, 1.0, v150
	v_rcp_f32_e32 v150, v150
	s_nop 0
	v_mul_f32_e32 v150, v149, v150
	v_cndmask_b32_e32 v149, v149, v150, vcc
	v_mul_f32_e32 v150, v16, v152
	v_mul_f32_e32 v151, 0xbfb8aa3b, v150
	v_exp_f32_e32 v151, v151
	v_cvt_pk_bf16_f32 v147, v148, v149
	v_add_f32_e32 v151, 1.0, v151
	v_rcp_f32_e32 v151, v151
	s_nop 0
	v_mul_f32_e32 v151, v150, v151
	v_cndmask_b32_e32 v150, v150, v151, vcc
	v_mul_f32_e32 v151, v17, v152
	v_mul_f32_e32 v153, 0xbfb8aa3b, v151
	v_exp_f32_e32 v153, v153
	s_nop 0
	v_add_f32_e32 v153, 1.0, v153
	v_rcp_f32_e32 v153, v153
	s_nop 0
	v_mul_f32_e32 v153, v151, v153
	v_cndmask_b32_e32 v151, v151, v153, vcc
	v_mul_f32_e32 v153, v18, v152
	v_mul_f32_e32 v154, 0xbfb8aa3b, v153
	v_exp_f32_e32 v154, v154
	v_mul_f32_e32 v152, v19, v152
	v_cvt_pk_bf16_f32 v148, v150, v151
	v_add_f32_e32 v154, 1.0, v154
	v_rcp_f32_e32 v154, v154
	s_nop 0
	v_mul_f32_e32 v154, v153, v154
	v_cndmask_b32_e32 v153, v153, v154, vcc
	v_mul_f32_e32 v154, 0xbfb8aa3b, v152
	v_exp_f32_e32 v154, v154
	s_nop 0
	v_add_f32_e32 v154, 1.0, v154
	v_rcp_f32_e32 v154, v154
	s_nop 0
	v_mul_f32_e32 v154, v152, v154
	v_cndmask_b32_e32 v152, v152, v154, vcc
	v_cvt_pk_bf16_f32 v149, v153, v152
	global_store_dwordx4 v[144:145], v[146:149], off offset:256
	s_nop 1
	v_mov_b64_e32 v[130:131], v[210:211]
	v_ffbh_u32_e32 v144, v131
	v_min_u32_e32 v144, 32, v144
	v_lshlrev_b64 v[130:131], v144, v[130:131]
	v_min_u32_e32 v130, 1, v130
	v_or_b32_e32 v130, v131, v130
	v_cvt_f32_u32_e32 v130, v130
	v_sub_u32_e32 v131, 32, v144
	v_ldexp_f32 v130, v130, v131
	v_mul_f32_e32 v130, 0x35800000, v130
	v_fmamk_f32 v130, v130, 0x3a800000, v219
	v_rsq_f32_e32 v148, v130
	v_lshl_add_u64 v[130:131], v[128:129], 0, s[0:1]
	s_mov_b32 s0, 0x2c000
	v_add_co_u32_e64 v128, s[0:1], s0, v128
	v_mul_f32_e32 v144, v12, v148
	v_mul_f32_e32 v145, 0xbfb8aa3b, v144
	v_exp_f32_e32 v145, v145
	v_addc_co_u32_e64 v129, s[0:1], 0, v129, s[0:1]
	v_add_f32_e32 v145, 1.0, v145
	v_rcp_f32_e32 v145, v145
	s_nop 0
	v_mul_f32_e32 v145, v144, v145
	v_cndmask_b32_e32 v144, v144, v145, vcc
	v_mul_f32_e32 v145, v13, v148
	v_mul_f32_e32 v146, 0xbfb8aa3b, v145
	v_exp_f32_e32 v146, v146
	s_nop 0
	v_add_f32_e32 v146, 1.0, v146
	v_rcp_f32_e32 v146, v146
	s_nop 0
	v_mul_f32_e32 v146, v145, v146
	v_cndmask_b32_e32 v145, v145, v146, vcc
	v_mul_f32_e32 v146, v14, v148
	v_mul_f32_e32 v147, 0xbfb8aa3b, v146
	v_exp_f32_e32 v147, v147
	v_cvt_pk_bf16_f32 v144, v144, v145
	v_add_f32_e32 v147, 1.0, v147
	v_rcp_f32_e32 v147, v147
	s_nop 0
	v_mul_f32_e32 v147, v146, v147
	v_cndmask_b32_e32 v146, v146, v147, vcc
	v_mul_f32_e32 v147, v15, v148
	v_mul_f32_e32 v149, 0xbfb8aa3b, v147
	v_exp_f32_e32 v149, v149
	s_nop 0
	v_add_f32_e32 v149, 1.0, v149
	v_rcp_f32_e32 v149, v149
	s_nop 0
	v_mul_f32_e32 v149, v147, v149
	v_cndmask_b32_e32 v147, v147, v149, vcc
	v_mul_f32_e32 v149, v4, v148
	v_mul_f32_e32 v150, 0xbfb8aa3b, v149
	v_exp_f32_e32 v150, v150
	v_cvt_pk_bf16_f32 v145, v146, v147
	v_add_f32_e32 v150, 1.0, v150
	v_rcp_f32_e32 v150, v150
	s_nop 0
	v_mul_f32_e32 v150, v149, v150
	v_cndmask_b32_e32 v149, v149, v150, vcc
	v_mul_f32_e32 v150, v5, v148
	v_mul_f32_e32 v151, 0xbfb8aa3b, v150
	v_exp_f32_e32 v151, v151
	s_nop 0
	v_add_f32_e32 v151, 1.0, v151
	v_rcp_f32_e32 v151, v151
	s_nop 0
	v_mul_f32_e32 v151, v150, v151
	v_cndmask_b32_e32 v150, v150, v151, vcc
	v_mul_f32_e32 v151, v6, v148
	v_mul_f32_e32 v152, 0xbfb8aa3b, v151
	v_exp_f32_e32 v152, v152
	v_cvt_pk_bf16_f32 v146, v149, v150
	v_add_f32_e32 v152, 1.0, v152
	v_rcp_f32_e32 v152, v152
	s_nop 0
	v_mul_f32_e32 v152, v151, v152
	v_cndmask_b32_e32 v151, v151, v152, vcc
	v_mul_f32_e32 v152, v7, v148
	v_mul_f32_e32 v153, 0xbfb8aa3b, v152
	v_exp_f32_e32 v153, v153
	s_nop 0
	v_add_f32_e32 v153, 1.0, v153
	v_rcp_f32_e32 v153, v153
	s_nop 0
	v_mul_f32_e32 v153, v152, v153
	v_cndmask_b32_e32 v152, v152, v153, vcc
	v_cvt_pk_bf16_f32 v147, v151, v152
	global_store_dwordx4 v[128:129], v[144:147], off
	v_mul_f32_e32 v128, v8, v148
	v_mul_f32_e32 v129, 0xbfb8aa3b, v128
	v_exp_f32_e32 v129, v129
	s_nop 0
	v_add_f32_e32 v129, 1.0, v129
	v_rcp_f32_e32 v129, v129
	s_nop 0
	v_mul_f32_e32 v129, v128, v129
	v_cndmask_b32_e32 v128, v128, v129, vcc
	v_mul_f32_e32 v129, v9, v148
	v_mul_f32_e32 v144, 0xbfb8aa3b, v129
	v_exp_f32_e32 v144, v144
	s_nop 0
	v_add_f32_e32 v144, 1.0, v144
	v_rcp_f32_e32 v144, v144
	s_nop 0
	v_mul_f32_e32 v144, v129, v144
	v_cndmask_b32_e32 v129, v129, v144, vcc
	v_mul_f32_e32 v144, v10, v148
	v_mul_f32_e32 v145, 0xbfb8aa3b, v144
	v_exp_f32_e32 v145, v145
	s_nop 0
	v_add_f32_e32 v145, 1.0, v145
	v_rcp_f32_e32 v145, v145
	s_nop 0
	v_mul_f32_e32 v145, v144, v145
	v_cndmask_b32_e32 v145, v144, v145, vcc
	v_mul_f32_e32 v144, v11, v148
	v_mul_f32_e32 v146, 0xbfb8aa3b, v144
	v_exp_f32_e32 v146, v146
	s_nop 0
	v_add_f32_e32 v146, 1.0, v146
	v_rcp_f32_e32 v146, v146
	s_nop 0
	v_mul_f32_e32 v146, v144, v146
	v_cndmask_b32_e32 v146, v144, v146, vcc
	v_mul_f32_e32 v144, v0, v148
	v_mul_f32_e32 v147, 0xbfb8aa3b, v144
	v_exp_f32_e32 v147, v147
	v_cvt_pk_bf16_f32 v145, v145, v146
	v_add_f32_e32 v147, 1.0, v147
	v_rcp_f32_e32 v147, v147
	s_nop 0
	v_mul_f32_e32 v147, v144, v147
	v_cndmask_b32_e32 v147, v144, v147, vcc
	v_mul_f32_e32 v144, v1, v148
	v_mul_f32_e32 v149, 0xbfb8aa3b, v144
	v_exp_f32_e32 v149, v149
	s_nop 0
	v_add_f32_e32 v149, 1.0, v149
	v_rcp_f32_e32 v149, v149
	s_nop 0
	v_mul_f32_e32 v149, v144, v149
	v_cndmask_b32_e32 v149, v144, v149, vcc
	v_mul_f32_e32 v144, v2, v148
	v_mul_f32_e32 v150, 0xbfb8aa3b, v144
	v_exp_f32_e32 v150, v150
	v_cvt_pk_bf16_f32 v146, v147, v149
	v_add_f32_e32 v150, 1.0, v150
	v_rcp_f32_e32 v150, v150
	s_nop 0
	v_mul_f32_e32 v150, v144, v150
	v_cndmask_b32_e32 v150, v144, v150, vcc
	v_mul_f32_e32 v144, v3, v148
	v_mul_f32_e32 v148, 0xbfb8aa3b, v144
	v_exp_f32_e32 v148, v148
	s_nop 0
	v_add_f32_e32 v148, 1.0, v148
	v_rcp_f32_e32 v148, v148
	s_nop 0
	v_mul_f32_e32 v148, v144, v148
	v_cndmask_b32_e32 v148, v144, v148, vcc
	v_cvt_pk_bf16_f32 v144, v128, v129
	v_cvt_pk_bf16_f32 v147, v150, v148
	global_store_dwordx4 v[130:131], v[144:147], off offset:256

.LBB0_410:
	s_lshl_b32 s0, s35, 1
	s_and_b32 s0, s0, 2
	s_or_b32 s7, s0, s34
	s_cmp_lt_i32 s35, 2
	s_cselect_b64 s[0:1], -1, 0
	v_mov_b32_e32 v128, 0x3db504f3
	v_cndmask_b32_e64 v146, v128, 1.0, s[0:1]
	s_and_b64 s[0:1], s[0:1], exec
	s_mov_b32 s0, 0x9a00000
	s_cselect_b32 s1, s0, 0xda00000
	s_cselect_b32 s0, 10, 9
	s_add_u32 s1, s94, s1
	s_addc_u32 s9, s95, 0
	s_lshl_b32 s7, s7, 8
	v_lshl_add_u32 v130, s44, 8, v156
	s_add_u32 s8, s1, s7
	s_movk_i32 s1, 0x4000
	v_cmp_gt_i32_e32 vcc, s1, v130
	s_addc_u32 s9, s9, 0
	v_lshl_add_u64 v[128:129], s[8:9], 0, v[160:161]
	v_cndmask_b32_e32 v131, v228, v229, vcc
	v_and_b32_e32 v147, v131, v130
	v_ashrrev_i32_e32 v131, 31, v130
	v_lshl_add_u64 v[144:145], v[130:131], 3, s[36:37]
	s_waitcnt vmcnt(0) lgkmcnt(0)
	v_mov_b64_e32 v[148:149], v[196:197]
	v_ffbh_u32_e32 v150, v149
	v_min_u32_e32 v150, 32, v150
	v_lshlrev_b64 v[148:149], v150, v[148:149]
	v_min_u32_e32 v148, 1, v148
	v_or_b32_e32 v148, v149, v148
	v_cvt_f32_u32_e32 v148, v148
	v_sub_u32_e32 v149, 32, v150
	v_ldexp_f32 v148, v148, v149
	v_mul_f32_e32 v148, 0x35800000, v148
	v_fmamk_f32 v148, v148, 0x3a800000, v219
	v_rsq_f32_e32 v148, v148
	v_mov_b32_e32 v149, v161
	v_mul_f32_e32 v162, v146, v148
	v_lshl_or_b32 v148, v147, 9, v174
	v_lshl_add_u64 v[164:165], s[94:95], 0, v[148:149]
	global_load_dwordx4 v[148:151], v[164:165], off
	global_load_dwordx4 v[152:155], v[164:165], off offset:16
	v_pk_mul_f32 v[120:121], v[120:121], v[162:163] op_sel_hi:[1,0]
	v_pk_mul_f32 v[124:125], v[124:125], v[162:163] op_sel_hi:[1,0]
	v_pk_mul_f32 v[122:123], v[122:123], v[162:163] op_sel_hi:[1,0]
	v_pk_mul_f32 v[126:127], v[126:127], v[162:163] op_sel_hi:[1,0]
	v_pk_mul_f32 v[118:119], v[118:119], v[162:163] op_sel_hi:[1,0]
	v_pk_mul_f32 v[116:117], v[116:117], v[162:163] op_sel_hi:[1,0]
	v_pk_mul_f32 v[114:115], v[114:115], v[162:163] op_sel_hi:[1,0]
	v_pk_mul_f32 v[112:113], v[112:113], v[162:163] op_sel_hi:[1,0]
	s_waitcnt vmcnt(0) lgkmcnt(0)
	v_mov_b32_e32 v166, v148
	v_mov_b32_e32 v167, v150
	v_mov_b32_e32 v150, v149
	v_pk_mul_f32 v[148:149], v[150:151], v[120:121]
	v_pk_mul_f32 v[120:121], v[166:167], v[120:121]
	v_pk_fma_f32 v[148:149], v[166:167], v[124:125], v[148:149] neg_lo:[0,0,1] neg_hi:[0,0,1]
	v_pk_fma_f32 v[150:151], v[150:151], v[124:125], v[120:121]
	v_mov_b32_e32 v121, v154
	v_mov_b32_e32 v154, v153
	v_mov_b32_e32 v120, v152
	v_pk_mul_f32 v[124:125], v[154:155], v[122:123]
	s_nop 0
	v_pk_fma_f32 v[152:153], v[120:121], v[126:127], v[124:125] neg_lo:[0,0,1] neg_hi:[0,0,1]
	v_pk_mul_f32 v[120:121], v[120:121], v[122:123]
	s_nop 0
	v_pk_fma_f32 v[154:155], v[154:155], v[126:127], v[120:121]
	global_load_dwordx4 v[120:123], v[164:165], off offset:32
	global_load_dwordx4 v[124:127], v[164:165], off offset:48
	s_waitcnt vmcnt(0) lgkmcnt(0)
	v_mov_b32_e32 v162, v120
	v_mov_b32_e32 v163, v122
	v_mov_b32_e32 v122, v121
	v_pk_mul_f32 v[120:121], v[122:123], v[112:113]
	v_pk_mul_f32 v[112:113], v[162:163], v[112:113]
	v_pk_fma_f32 v[120:121], v[162:163], v[116:117], v[120:121] neg_lo:[0,0,1] neg_hi:[0,0,1]
	v_pk_fma_f32 v[116:117], v[122:123], v[116:117], v[112:113]
	v_mov_b32_e32 v113, v126
	v_mov_b32_e32 v126, v125
	v_mov_b32_e32 v112, v124
	v_pk_mul_f32 v[122:123], v[126:127], v[114:115]
	s_nop 0
	v_pk_fma_f32 v[122:123], v[112:113], v[118:119], v[122:123] neg_lo:[0,0,1] neg_hi:[0,0,1]
	v_pk_mul_f32 v[112:113], v[112:113], v[114:115]
	v_cvt_pk_bf16_f32 v114, v120, v121
	v_pk_fma_f32 v[118:119], v[126:127], v[118:119], v[112:113]
	v_lshlrev_b64 v[112:113], s0, v[130:131]
	v_lshl_add_u64 v[124:125], v[112:113], 1, v[128:129]
	v_cvt_pk_bf16_f32 v112, v148, v149
	v_cvt_pk_bf16_f32 v113, v152, v153
	v_cvt_pk_bf16_f32 v115, v122, v123
	global_store_dwordx4 v[124:125], v[112:115], off
	s_nop 1
	v_cvt_pk_bf16_f32 v112, v150, v151
	v_cvt_pk_bf16_f32 v113, v154, v155
	v_cvt_pk_bf16_f32 v114, v116, v117
	v_cvt_pk_bf16_f32 v115, v118, v119
	global_store_dwordx4 v[124:125], v[112:115], off offset:128
	s_nop 1
	v_or_b32_e32 v112, 16, v130
	v_cmp_gt_i32_e32 vcc, s1, v112
	s_nop 1
	v_cndmask_b32_e32 v113, v230, v231, vcc
	v_bitop3_b32 v116, v113, v130, 16 bitop3:0xe0
	v_ashrrev_i32_e32 v113, 31, v112
	v_lshl_add_u64 v[114:115], v[112:113], 3, s[36:37]
	s_nop 1
	v_mov_b64_e32 v[114:115], v[198:199]
	v_lshl_or_b32 v116, v116, 9, v174
	v_ffbh_u32_e32 v117, v115
	v_min_u32_e32 v117, 32, v117
	v_lshlrev_b64 v[114:115], v117, v[114:115]
	v_min_u32_e32 v114, 1, v114
	v_or_b32_e32 v114, v115, v114
	v_sub_u32_e32 v115, 32, v117
	v_mov_b32_e32 v117, v161
	v_lshl_add_u64 v[116:117], s[94:95], 0, v[116:117]
	global_load_dwordx4 v[118:121], v[116:117], off
	global_load_dwordx4 v[122:125], v[116:117], off offset:16
	v_cvt_f32_u32_e32 v114, v114
	v_ldexp_f32 v114, v114, v115
	v_mul_f32_e32 v114, 0x35800000, v114
	v_fmamk_f32 v114, v114, 0x3a800000, v219
	v_rsq_f32_e32 v114, v114
	s_waitcnt vmcnt(0) lgkmcnt(0)
	v_mov_b32_e32 v126, v118
	v_mul_f32_e32 v114, v146, v114
	v_pk_mul_f32 v[104:105], v[104:105], v[114:115] op_sel_hi:[1,0]
	v_mov_b32_e32 v127, v120
	v_mov_b32_e32 v120, v119
	v_pk_mul_f32 v[108:109], v[108:109], v[114:115] op_sel_hi:[1,0]
	v_pk_mul_f32 v[118:119], v[120:121], v[104:105]
	v_pk_mul_f32 v[104:105], v[126:127], v[104:105]
	v_pk_mul_f32 v[106:107], v[106:107], v[114:115] op_sel_hi:[1,0]
	v_pk_fma_f32 v[120:121], v[120:121], v[108:109], v[104:105]
	v_mov_b32_e32 v105, v124
	v_mov_b32_e32 v124, v123
	v_pk_mul_f32 v[110:111], v[110:111], v[114:115] op_sel_hi:[1,0]
	v_pk_fma_f32 v[118:119], v[126:127], v[108:109], v[118:119] neg_lo:[0,0,1] neg_hi:[0,0,1]
	v_mov_b32_e32 v104, v122
	v_pk_mul_f32 v[108:109], v[124:125], v[106:107]
	v_pk_mul_f32 v[102:103], v[102:103], v[114:115] op_sel_hi:[1,0]
	v_pk_fma_f32 v[122:123], v[104:105], v[110:111], v[108:109] neg_lo:[0,0,1] neg_hi:[0,0,1]
	v_pk_mul_f32 v[104:105], v[104:105], v[106:107]
	v_pk_mul_f32 v[100:101], v[100:101], v[114:115] op_sel_hi:[1,0]
	v_pk_fma_f32 v[124:125], v[124:125], v[110:111], v[104:105]
	global_load_dwordx4 v[104:107], v[116:117], off offset:32
	global_load_dwordx4 v[108:111], v[116:117], off offset:48
	v_pk_mul_f32 v[98:99], v[98:99], v[114:115] op_sel_hi:[1,0]
	v_pk_mul_f32 v[96:97], v[96:97], v[114:115] op_sel_hi:[1,0]
	s_waitcnt vmcnt(0) lgkmcnt(0)
	v_mov_b32_e32 v114, v104
	v_mov_b32_e32 v115, v106
	v_mov_b32_e32 v106, v105
	v_pk_mul_f32 v[104:105], v[106:107], v[96:97]
	v_pk_mul_f32 v[96:97], v[114:115], v[96:97]
	v_pk_fma_f32 v[104:105], v[114:115], v[100:101], v[104:105] neg_lo:[0,0,1] neg_hi:[0,0,1]
	v_pk_fma_f32 v[100:101], v[106:107], v[100:101], v[96:97]
	v_mov_b32_e32 v97, v110
	v_mov_b32_e32 v110, v109
	v_mov_b32_e32 v96, v108
	v_pk_mul_f32 v[106:107], v[110:111], v[98:99]
	s_nop 0
	v_pk_fma_f32 v[106:107], v[96:97], v[102:103], v[106:107] neg_lo:[0,0,1] neg_hi:[0,0,1]
	v_pk_mul_f32 v[96:97], v[96:97], v[98:99]
	v_cvt_pk_bf16_f32 v98, v104, v105
	v_pk_fma_f32 v[102:103], v[110:111], v[102:103], v[96:97]
	v_lshlrev_b64 v[96:97], s0, v[112:113]
	v_lshl_add_u64 v[108:109], v[96:97], 1, v[128:129]
	v_cvt_pk_bf16_f32 v96, v118, v119
	v_cvt_pk_bf16_f32 v97, v122, v123
	v_cvt_pk_bf16_f32 v99, v106, v107
	global_store_dwordx4 v[108:109], v[96:99], off
	s_nop 1
	v_cvt_pk_bf16_f32 v96, v120, v121
	v_cvt_pk_bf16_f32 v97, v124, v125
	v_cvt_pk_bf16_f32 v98, v100, v101
	v_cvt_pk_bf16_f32 v99, v102, v103
	global_store_dwordx4 v[108:109], v[96:99], off offset:128
	s_nop 1
	v_or_b32_e32 v96, 32, v130
	v_cmp_gt_i32_e32 vcc, s1, v96
	s_nop 1
	v_cndmask_b32_e32 v97, v222, v236, vcc
	v_bitop3_b32 v100, v97, v130, 32 bitop3:0xe0
	v_ashrrev_i32_e32 v97, 31, v96
	v_lshl_add_u64 v[98:99], v[96:97], 3, s[36:37]
	s_nop 1
	v_mov_b64_e32 v[98:99], v[200:201]
	v_lshl_or_b32 v100, v100, 9, v174
	v_ffbh_u32_e32 v101, v99
	v_min_u32_e32 v101, 32, v101
	v_lshlrev_b64 v[98:99], v101, v[98:99]
	v_min_u32_e32 v98, 1, v98
	v_or_b32_e32 v98, v99, v98
	v_sub_u32_e32 v99, 32, v101
	v_mov_b32_e32 v101, v161
	v_lshl_add_u64 v[100:101], s[94:95], 0, v[100:101]
	global_load_dwordx4 v[102:105], v[100:101], off
	global_load_dwordx4 v[106:109], v[100:101], off offset:16
	v_cvt_f32_u32_e32 v98, v98
	v_ldexp_f32 v98, v98, v99
	v_mul_f32_e32 v98, 0x35800000, v98
	v_fmamk_f32 v98, v98, 0x3a800000, v219
	v_rsq_f32_e32 v98, v98
	s_waitcnt vmcnt(0) lgkmcnt(0)
	v_mov_b32_e32 v110, v102
	v_mul_f32_e32 v98, v146, v98
	v_pk_mul_f32 v[88:89], v[88:89], v[98:99] op_sel_hi:[1,0]
	v_mov_b32_e32 v111, v104
	v_mov_b32_e32 v104, v103
	v_pk_mul_f32 v[92:93], v[92:93], v[98:99] op_sel_hi:[1,0]
	v_pk_mul_f32 v[102:103], v[104:105], v[88:89]
	v_pk_mul_f32 v[88:89], v[110:111], v[88:89]
	v_pk_mul_f32 v[90:91], v[90:91], v[98:99] op_sel_hi:[1,0]
	v_pk_fma_f32 v[104:105], v[104:105], v[92:93], v[88:89]
	v_mov_b32_e32 v89, v108
	v_mov_b32_e32 v108, v107
	v_pk_mul_f32 v[94:95], v[94:95], v[98:99] op_sel_hi:[1,0]
	v_pk_fma_f32 v[102:103], v[110:111], v[92:93], v[102:103] neg_lo:[0,0,1] neg_hi:[0,0,1]
	v_mov_b32_e32 v88, v106
	v_pk_mul_f32 v[92:93], v[108:109], v[90:91]
	v_pk_mul_f32 v[86:87], v[86:87], v[98:99] op_sel_hi:[1,0]
	v_pk_fma_f32 v[106:107], v[88:89], v[94:95], v[92:93] neg_lo:[0,0,1] neg_hi:[0,0,1]
	v_pk_mul_f32 v[88:89], v[88:89], v[90:91]
	v_pk_mul_f32 v[84:85], v[84:85], v[98:99] op_sel_hi:[1,0]
	v_pk_fma_f32 v[108:109], v[108:109], v[94:95], v[88:89]
	global_load_dwordx4 v[88:91], v[100:101], off offset:32
	global_load_dwordx4 v[92:95], v[100:101], off offset:48
	v_pk_mul_f32 v[82:83], v[82:83], v[98:99] op_sel_hi:[1,0]
	v_pk_mul_f32 v[80:81], v[80:81], v[98:99] op_sel_hi:[1,0]
	s_waitcnt vmcnt(0) lgkmcnt(0)
	v_mov_b32_e32 v98, v88
	v_mov_b32_e32 v99, v90
	v_mov_b32_e32 v90, v89
	v_pk_mul_f32 v[88:89], v[90:91], v[80:81]
	v_pk_mul_f32 v[80:81], v[98:99], v[80:81]
	v_pk_fma_f32 v[88:89], v[98:99], v[84:85], v[88:89] neg_lo:[0,0,1] neg_hi:[0,0,1]
	v_pk_fma_f32 v[84:85], v[90:91], v[84:85], v[80:81]
	v_mov_b32_e32 v81, v94
	v_mov_b32_e32 v94, v93
	v_mov_b32_e32 v80, v92
	v_pk_mul_f32 v[90:91], v[94:95], v[82:83]
	s_nop 0
	v_pk_fma_f32 v[90:91], v[80:81], v[86:87], v[90:91] neg_lo:[0,0,1] neg_hi:[0,0,1]
	v_pk_mul_f32 v[80:81], v[80:81], v[82:83]
	v_cvt_pk_bf16_f32 v82, v88, v89
	v_pk_fma_f32 v[86:87], v[94:95], v[86:87], v[80:81]
	v_lshlrev_b64 v[80:81], s0, v[96:97]
	v_lshl_add_u64 v[92:93], v[80:81], 1, v[128:129]
	v_cvt_pk_bf16_f32 v80, v102, v103
	v_cvt_pk_bf16_f32 v81, v106, v107
	v_cvt_pk_bf16_f32 v83, v90, v91
	global_store_dwordx4 v[92:93], v[80:83], off
	s_nop 1
	v_cvt_pk_bf16_f32 v80, v104, v105
	v_cvt_pk_bf16_f32 v81, v108, v109
	v_cvt_pk_bf16_f32 v82, v84, v85
	v_cvt_pk_bf16_f32 v83, v86, v87
	global_store_dwordx4 v[92:93], v[80:83], off offset:128
	s_nop 1
	v_or_b32_e32 v80, 48, v130
	v_cmp_gt_i32_e32 vcc, s1, v80
	s_movk_i32 s1, 0x3f80
	s_nop 0
	v_cndmask_b32_e32 v81, v232, v243, vcc
	v_bitop3_b32 v84, v81, v130, 48 bitop3:0xe0
	v_ashrrev_i32_e32 v81, 31, v80
	v_lshl_add_u64 v[82:83], v[80:81], 3, s[36:37]
	s_nop 1
	v_mov_b64_e32 v[82:83], v[202:203]
	v_lshl_or_b32 v84, v84, 9, v174
	v_cmp_gt_i32_e32 vcc, s1, v130
	s_movk_i32 s1, 0x3f70
	v_ffbh_u32_e32 v85, v83
	v_min_u32_e32 v85, 32, v85
	v_lshlrev_b64 v[82:83], v85, v[82:83]
	v_min_u32_e32 v82, 1, v82
	v_or_b32_e32 v82, v83, v82
	v_sub_u32_e32 v83, 32, v85
	v_mov_b32_e32 v85, v161
	v_lshl_add_u64 v[84:85], s[94:95], 0, v[84:85]
	global_load_dwordx4 v[86:89], v[84:85], off
	global_load_dwordx4 v[90:93], v[84:85], off offset:16
	v_cvt_f32_u32_e32 v82, v82
	v_ldexp_f32 v82, v82, v83
	v_mul_f32_e32 v82, 0x35800000, v82
	v_fmamk_f32 v82, v82, 0x3a800000, v219
	v_rsq_f32_e32 v82, v82
	s_waitcnt vmcnt(0) lgkmcnt(0)
	v_mov_b32_e32 v94, v86
	v_mul_f32_e32 v82, v146, v82
	v_pk_mul_f32 v[72:73], v[72:73], v[82:83] op_sel_hi:[1,0]
	v_mov_b32_e32 v95, v88
	v_mov_b32_e32 v88, v87
	v_pk_mul_f32 v[76:77], v[76:77], v[82:83] op_sel_hi:[1,0]
	v_pk_mul_f32 v[86:87], v[88:89], v[72:73]
	v_pk_mul_f32 v[72:73], v[94:95], v[72:73]
	v_pk_mul_f32 v[74:75], v[74:75], v[82:83] op_sel_hi:[1,0]
	v_pk_fma_f32 v[88:89], v[88:89], v[76:77], v[72:73]
	v_mov_b32_e32 v73, v92
	v_mov_b32_e32 v92, v91
	v_pk_mul_f32 v[78:79], v[78:79], v[82:83] op_sel_hi:[1,0]
	v_pk_fma_f32 v[86:87], v[94:95], v[76:77], v[86:87] neg_lo:[0,0,1] neg_hi:[0,0,1]
	v_mov_b32_e32 v72, v90
	v_pk_mul_f32 v[76:77], v[92:93], v[74:75]
	v_pk_mul_f32 v[70:71], v[70:71], v[82:83] op_sel_hi:[1,0]
	v_pk_fma_f32 v[90:91], v[72:73], v[78:79], v[76:77] neg_lo:[0,0,1] neg_hi:[0,0,1]
	v_pk_mul_f32 v[72:73], v[72:73], v[74:75]
	v_pk_mul_f32 v[68:69], v[68:69], v[82:83] op_sel_hi:[1,0]
	v_pk_fma_f32 v[92:93], v[92:93], v[78:79], v[72:73]
	global_load_dwordx4 v[72:75], v[84:85], off offset:32
	global_load_dwordx4 v[76:79], v[84:85], off offset:48
	v_pk_mul_f32 v[66:67], v[66:67], v[82:83] op_sel_hi:[1,0]
	v_pk_mul_f32 v[64:65], v[64:65], v[82:83] op_sel_hi:[1,0]
	s_waitcnt vmcnt(0) lgkmcnt(0)
	v_mov_b32_e32 v82, v72
	v_mov_b32_e32 v83, v74
	v_mov_b32_e32 v74, v73
	v_pk_mul_f32 v[72:73], v[74:75], v[64:65]
	v_pk_mul_f32 v[64:65], v[82:83], v[64:65]
	v_pk_fma_f32 v[72:73], v[82:83], v[68:69], v[72:73] neg_lo:[0,0,1] neg_hi:[0,0,1]
	v_pk_fma_f32 v[68:69], v[74:75], v[68:69], v[64:65]
	v_mov_b32_e32 v65, v78
	v_mov_b32_e32 v78, v77
	v_mov_b32_e32 v64, v76
	v_pk_mul_f32 v[74:75], v[78:79], v[66:67]
	s_nop 0
	v_pk_fma_f32 v[74:75], v[64:65], v[70:71], v[74:75] neg_lo:[0,0,1] neg_hi:[0,0,1]
	v_pk_mul_f32 v[64:65], v[64:65], v[66:67]
	v_cvt_pk_bf16_f32 v66, v72, v73
	v_pk_fma_f32 v[70:71], v[78:79], v[70:71], v[64:65]
	v_lshlrev_b64 v[64:65], s0, v[80:81]
	v_lshl_add_u64 v[76:77], v[64:65], 1, v[128:129]
	v_cvt_pk_bf16_f32 v64, v86, v87
	v_cvt_pk_bf16_f32 v65, v90, v91
	v_cvt_pk_bf16_f32 v67, v74, v75
	global_store_dwordx4 v[76:77], v[64:67], off
	s_nop 1
	v_cvt_pk_bf16_f32 v64, v88, v89
	v_cvt_pk_bf16_f32 v65, v92, v93
	v_cvt_pk_bf16_f32 v66, v68, v69
	v_cvt_pk_bf16_f32 v67, v70, v71
	global_store_dwordx4 v[76:77], v[64:67], off offset:128
	s_nop 1
	v_mov_b64_e32 v[66:67], v[204:205]
	v_ffbh_u32_e32 v69, v67
	v_min_u32_e32 v69, 32, v69
	v_add_u32_e32 v64, 0x80, v130
	v_cndmask_b32_e32 v65, v228, v229, vcc
	v_lshlrev_b64 v[66:67], v69, v[66:67]
	v_and_b32_e32 v68, v65, v64
	v_min_u32_e32 v66, 1, v66
	v_or_b32_e32 v66, v67, v66
	v_sub_u32_e32 v67, 32, v69
	v_lshl_or_b32 v68, v68, 9, v174
	v_mov_b32_e32 v69, v161
	v_lshl_add_u64 v[68:69], s[94:95], 0, v[68:69]
	global_load_dwordx4 v[70:73], v[68:69], off
	global_load_dwordx4 v[74:77], v[68:69], off offset:16
	v_cvt_f32_u32_e32 v66, v66
	v_ashrrev_i32_e32 v65, 31, v64
	v_cmp_gt_i32_e32 vcc, s1, v130
	s_movk_i32 s1, 0x3f60
	v_ldexp_f32 v66, v66, v67
	v_mul_f32_e32 v66, 0x35800000, v66
	v_fmamk_f32 v66, v66, 0x3a800000, v219
	v_rsq_f32_e32 v66, v66
	s_waitcnt vmcnt(0) lgkmcnt(0)
	v_mov_b32_e32 v78, v70
	v_mul_f32_e32 v66, v146, v66
	v_pk_mul_f32 v[56:57], v[56:57], v[66:67] op_sel_hi:[1,0]
	v_mov_b32_e32 v79, v72
	v_mov_b32_e32 v72, v71
	v_pk_mul_f32 v[60:61], v[60:61], v[66:67] op_sel_hi:[1,0]
	v_pk_mul_f32 v[70:71], v[72:73], v[56:57]
	v_pk_mul_f32 v[56:57], v[78:79], v[56:57]
	v_pk_mul_f32 v[58:59], v[58:59], v[66:67] op_sel_hi:[1,0]
	v_pk_fma_f32 v[72:73], v[72:73], v[60:61], v[56:57]
	v_mov_b32_e32 v57, v76
	v_mov_b32_e32 v76, v75
	v_pk_mul_f32 v[62:63], v[62:63], v[66:67] op_sel_hi:[1,0]
	v_pk_fma_f32 v[70:71], v[78:79], v[60:61], v[70:71] neg_lo:[0,0,1] neg_hi:[0,0,1]
	v_mov_b32_e32 v56, v74
	v_pk_mul_f32 v[60:61], v[76:77], v[58:59]
	v_pk_mul_f32 v[54:55], v[54:55], v[66:67] op_sel_hi:[1,0]
	v_pk_fma_f32 v[74:75], v[56:57], v[62:63], v[60:61] neg_lo:[0,0,1] neg_hi:[0,0,1]
	v_pk_mul_f32 v[56:57], v[56:57], v[58:59]
	v_pk_mul_f32 v[52:53], v[52:53], v[66:67] op_sel_hi:[1,0]
	v_pk_fma_f32 v[76:77], v[76:77], v[62:63], v[56:57]
	global_load_dwordx4 v[56:59], v[68:69], off offset:32
	global_load_dwordx4 v[60:63], v[68:69], off offset:48
	v_pk_mul_f32 v[50:51], v[50:51], v[66:67] op_sel_hi:[1,0]
	v_pk_mul_f32 v[48:49], v[48:49], v[66:67] op_sel_hi:[1,0]
	s_waitcnt vmcnt(0) lgkmcnt(0)
	v_mov_b32_e32 v66, v56
	v_mov_b32_e32 v67, v58
	v_mov_b32_e32 v58, v57
	v_pk_mul_f32 v[56:57], v[58:59], v[48:49]
	v_pk_mul_f32 v[48:49], v[66:67], v[48:49]
	v_pk_fma_f32 v[56:57], v[66:67], v[52:53], v[56:57] neg_lo:[0,0,1] neg_hi:[0,0,1]
	v_pk_fma_f32 v[52:53], v[58:59], v[52:53], v[48:49]
	v_mov_b32_e32 v49, v62
	v_mov_b32_e32 v62, v61
	v_mov_b32_e32 v48, v60
	v_pk_mul_f32 v[58:59], v[62:63], v[50:51]
	s_nop 0
	v_pk_fma_f32 v[58:59], v[48:49], v[54:55], v[58:59] neg_lo:[0,0,1] neg_hi:[0,0,1]
	v_pk_mul_f32 v[48:49], v[48:49], v[50:51]
	v_cvt_pk_bf16_f32 v50, v56, v57
	v_pk_fma_f32 v[54:55], v[62:63], v[54:55], v[48:49]
	v_lshlrev_b64 v[48:49], s0, v[64:65]
	v_lshl_add_u64 v[60:61], v[48:49], 1, v[128:129]
	v_cvt_pk_bf16_f32 v48, v70, v71
	v_cvt_pk_bf16_f32 v49, v74, v75
	v_cvt_pk_bf16_f32 v51, v58, v59
	global_store_dwordx4 v[60:61], v[48:51], off
	s_nop 1
	v_cvt_pk_bf16_f32 v48, v72, v73
	v_cvt_pk_bf16_f32 v49, v76, v77
	v_cvt_pk_bf16_f32 v50, v52, v53
	v_cvt_pk_bf16_f32 v51, v54, v55
	global_store_dwordx4 v[60:61], v[48:51], off offset:128
	s_nop 1
	v_mov_b64_e32 v[50:51], v[206:207]
	v_ffbh_u32_e32 v53, v51
	v_min_u32_e32 v53, 32, v53
	v_add_u32_e32 v48, 0x90, v130
	v_cndmask_b32_e32 v49, v230, v231, vcc
	v_lshlrev_b64 v[50:51], v53, v[50:51]
	v_and_b32_e32 v52, v49, v48
	v_min_u32_e32 v50, 1, v50
	v_or_b32_e32 v50, v51, v50
	v_sub_u32_e32 v51, 32, v53
	v_lshl_or_b32 v52, v52, 9, v174
	v_mov_b32_e32 v53, v161
	v_lshl_add_u64 v[52:53], s[94:95], 0, v[52:53]
	global_load_dwordx4 v[54:57], v[52:53], off
	global_load_dwordx4 v[58:61], v[52:53], off offset:16
	v_cvt_f32_u32_e32 v50, v50
	v_ashrrev_i32_e32 v49, 31, v48
	v_cmp_gt_i32_e32 vcc, s1, v130
	s_movk_i32 s1, 0x3f50
	v_ldexp_f32 v50, v50, v51
	v_mul_f32_e32 v50, 0x35800000, v50
	v_fmamk_f32 v50, v50, 0x3a800000, v219
	v_rsq_f32_e32 v50, v50
	s_waitcnt vmcnt(0) lgkmcnt(0)
	v_mov_b32_e32 v62, v54
	v_mul_f32_e32 v50, v146, v50
	v_pk_mul_f32 v[40:41], v[40:41], v[50:51] op_sel_hi:[1,0]
	v_mov_b32_e32 v63, v56
	v_mov_b32_e32 v56, v55
	v_pk_mul_f32 v[44:45], v[44:45], v[50:51] op_sel_hi:[1,0]
	v_pk_mul_f32 v[54:55], v[56:57], v[40:41]
	v_pk_mul_f32 v[40:41], v[62:63], v[40:41]
	v_pk_mul_f32 v[42:43], v[42:43], v[50:51] op_sel_hi:[1,0]
	v_pk_fma_f32 v[56:57], v[56:57], v[44:45], v[40:41]
	v_mov_b32_e32 v41, v60
	v_mov_b32_e32 v60, v59
	v_pk_mul_f32 v[46:47], v[46:47], v[50:51] op_sel_hi:[1,0]
	v_pk_fma_f32 v[54:55], v[62:63], v[44:45], v[54:55] neg_lo:[0,0,1] neg_hi:[0,0,1]
	v_mov_b32_e32 v40, v58
	v_pk_mul_f32 v[44:45], v[60:61], v[42:43]
	v_pk_mul_f32 v[38:39], v[38:39], v[50:51] op_sel_hi:[1,0]
	v_pk_fma_f32 v[58:59], v[40:41], v[46:47], v[44:45] neg_lo:[0,0,1] neg_hi:[0,0,1]
	v_pk_mul_f32 v[40:41], v[40:41], v[42:43]
	v_pk_mul_f32 v[36:37], v[36:37], v[50:51] op_sel_hi:[1,0]
	v_pk_fma_f32 v[60:61], v[60:61], v[46:47], v[40:41]
	global_load_dwordx4 v[40:43], v[52:53], off offset:32
	global_load_dwordx4 v[44:47], v[52:53], off offset:48
	v_pk_mul_f32 v[34:35], v[34:35], v[50:51] op_sel_hi:[1,0]
	v_pk_mul_f32 v[32:33], v[32:33], v[50:51] op_sel_hi:[1,0]
	s_waitcnt vmcnt(0) lgkmcnt(0)
	v_mov_b32_e32 v50, v40
	v_mov_b32_e32 v51, v42
	v_mov_b32_e32 v42, v41
	v_pk_mul_f32 v[40:41], v[42:43], v[32:33]
	v_pk_mul_f32 v[32:33], v[50:51], v[32:33]
	v_pk_fma_f32 v[40:41], v[50:51], v[36:37], v[40:41] neg_lo:[0,0,1] neg_hi:[0,0,1]
	v_pk_fma_f32 v[36:37], v[42:43], v[36:37], v[32:33]
	v_mov_b32_e32 v33, v46
	v_mov_b32_e32 v46, v45
	v_mov_b32_e32 v32, v44
	v_pk_mul_f32 v[42:43], v[46:47], v[34:35]
	s_nop 0
	v_pk_fma_f32 v[42:43], v[32:33], v[38:39], v[42:43] neg_lo:[0,0,1] neg_hi:[0,0,1]
	v_pk_mul_f32 v[32:33], v[32:33], v[34:35]
	v_cvt_pk_bf16_f32 v34, v40, v41
	v_pk_fma_f32 v[38:39], v[46:47], v[38:39], v[32:33]
	v_lshlrev_b64 v[32:33], s0, v[48:49]
	v_lshl_add_u64 v[44:45], v[32:33], 1, v[128:129]
	v_cvt_pk_bf16_f32 v32, v54, v55
	v_cvt_pk_bf16_f32 v33, v58, v59
	v_cvt_pk_bf16_f32 v35, v42, v43
	global_store_dwordx4 v[44:45], v[32:35], off
	s_nop 1
	v_cvt_pk_bf16_f32 v32, v56, v57
	v_cvt_pk_bf16_f32 v33, v60, v61
	v_cvt_pk_bf16_f32 v34, v36, v37
	v_cvt_pk_bf16_f32 v35, v38, v39
	global_store_dwordx4 v[44:45], v[32:35], off offset:128
	s_nop 1
	v_mov_b64_e32 v[34:35], v[208:209]
	v_ffbh_u32_e32 v37, v35
	v_min_u32_e32 v37, 32, v37
	v_add_u32_e32 v32, 0xa0, v130
	v_cndmask_b32_e32 v33, v222, v236, vcc
	v_lshlrev_b64 v[34:35], v37, v[34:35]
	v_and_b32_e32 v36, v33, v32
	v_min_u32_e32 v34, 1, v34
	v_or_b32_e32 v34, v35, v34
	v_sub_u32_e32 v35, 32, v37
	v_lshl_or_b32 v36, v36, 9, v174
	v_mov_b32_e32 v37, v161
	v_lshl_add_u64 v[36:37], s[94:95], 0, v[36:37]
	global_load_dwordx4 v[38:41], v[36:37], off
	global_load_dwordx4 v[42:45], v[36:37], off offset:16
	v_cvt_f32_u32_e32 v34, v34
	v_ashrrev_i32_e32 v33, 31, v32
	v_cmp_gt_i32_e32 vcc, s1, v130
	v_ldexp_f32 v34, v34, v35
	v_mul_f32_e32 v34, 0x35800000, v34
	v_fmamk_f32 v34, v34, 0x3a800000, v219
	v_rsq_f32_e32 v34, v34
	s_waitcnt vmcnt(0) lgkmcnt(0)
	v_mov_b32_e32 v46, v38
	v_mul_f32_e32 v34, v146, v34
	v_pk_mul_f32 v[24:25], v[24:25], v[34:35] op_sel_hi:[1,0]
	v_mov_b32_e32 v47, v40
	v_mov_b32_e32 v40, v39
	v_pk_mul_f32 v[28:29], v[28:29], v[34:35] op_sel_hi:[1,0]
	v_pk_mul_f32 v[38:39], v[40:41], v[24:25]
	v_pk_mul_f32 v[24:25], v[46:47], v[24:25]
	v_pk_mul_f32 v[26:27], v[26:27], v[34:35] op_sel_hi:[1,0]
	v_pk_fma_f32 v[40:41], v[40:41], v[28:29], v[24:25]
	v_mov_b32_e32 v25, v44
	v_mov_b32_e32 v44, v43
	v_pk_mul_f32 v[30:31], v[30:31], v[34:35] op_sel_hi:[1,0]
	v_pk_fma_f32 v[38:39], v[46:47], v[28:29], v[38:39] neg_lo:[0,0,1] neg_hi:[0,0,1]
	v_mov_b32_e32 v24, v42
	v_pk_mul_f32 v[28:29], v[44:45], v[26:27]
	v_pk_mul_f32 v[22:23], v[22:23], v[34:35] op_sel_hi:[1,0]
	v_pk_fma_f32 v[42:43], v[24:25], v[30:31], v[28:29] neg_lo:[0,0,1] neg_hi:[0,0,1]
	v_pk_mul_f32 v[24:25], v[24:25], v[26:27]
	v_pk_mul_f32 v[20:21], v[20:21], v[34:35] op_sel_hi:[1,0]
	v_pk_fma_f32 v[44:45], v[44:45], v[30:31], v[24:25]
	global_load_dwordx4 v[24:27], v[36:37], off offset:32
	global_load_dwordx4 v[28:31], v[36:37], off offset:48
	v_pk_mul_f32 v[18:19], v[18:19], v[34:35] op_sel_hi:[1,0]
	v_pk_mul_f32 v[16:17], v[16:17], v[34:35] op_sel_hi:[1,0]
	s_waitcnt vmcnt(0) lgkmcnt(0)
	v_mov_b32_e32 v34, v24
	v_mov_b32_e32 v35, v26
	v_mov_b32_e32 v26, v25
	v_pk_mul_f32 v[24:25], v[26:27], v[16:17]
	v_pk_mul_f32 v[16:17], v[34:35], v[16:17]
	v_pk_fma_f32 v[24:25], v[34:35], v[20:21], v[24:25] neg_lo:[0,0,1] neg_hi:[0,0,1]
	v_pk_fma_f32 v[20:21], v[26:27], v[20:21], v[16:17]
	v_mov_b32_e32 v17, v30
	v_mov_b32_e32 v30, v29
	v_mov_b32_e32 v16, v28
	v_pk_mul_f32 v[26:27], v[30:31], v[18:19]
	s_nop 0
	v_pk_fma_f32 v[26:27], v[16:17], v[22:23], v[26:27] neg_lo:[0,0,1] neg_hi:[0,0,1]
	v_pk_mul_f32 v[16:17], v[16:17], v[18:19]
	v_cvt_pk_bf16_f32 v18, v24, v25
	v_pk_fma_f32 v[22:23], v[30:31], v[22:23], v[16:17]
	v_lshlrev_b64 v[16:17], s0, v[32:33]
	v_lshl_add_u64 v[28:29], v[16:17], 1, v[128:129]
	v_cvt_pk_bf16_f32 v16, v38, v39
	v_cvt_pk_bf16_f32 v17, v42, v43
	v_cvt_pk_bf16_f32 v19, v26, v27
	global_store_dwordx4 v[28:29], v[16:19], off
	s_nop 1
	v_cvt_pk_bf16_f32 v16, v40, v41
	v_cvt_pk_bf16_f32 v17, v44, v45
	v_cvt_pk_bf16_f32 v18, v20, v21
	v_cvt_pk_bf16_f32 v19, v22, v23
	global_store_dwordx4 v[28:29], v[16:19], off offset:128
	s_nop 1
	v_mov_b64_e32 v[18:19], v[210:211]
	v_ffbh_u32_e32 v21, v19
	v_min_u32_e32 v21, 32, v21
	v_add_u32_e32 v16, 0xb0, v130
	v_cndmask_b32_e32 v17, v232, v243, vcc
	v_lshlrev_b64 v[18:19], v21, v[18:19]
	v_and_b32_e32 v20, v17, v16
	v_min_u32_e32 v18, 1, v18
	v_or_b32_e32 v18, v19, v18
	v_sub_u32_e32 v19, 32, v21
	v_lshl_or_b32 v20, v20, 9, v174
	v_mov_b32_e32 v21, v161
	v_lshl_add_u64 v[20:21], s[94:95], 0, v[20:21]
	global_load_dwordx4 v[22:25], v[20:21], off
	global_load_dwordx4 v[26:29], v[20:21], off offset:16
	v_cvt_f32_u32_e32 v18, v18
	v_ashrrev_i32_e32 v17, 31, v16
	v_lshlrev_b64 v[16:17], s0, v[16:17]
	v_lshl_add_u64 v[16:17], v[16:17], 1, v[128:129]
	v_ldexp_f32 v18, v18, v19
	v_mul_f32_e32 v18, 0x35800000, v18
	v_fmamk_f32 v18, v18, 0x3a800000, v219
	v_rsq_f32_e32 v18, v18
	s_waitcnt vmcnt(0) lgkmcnt(0)
	v_mov_b32_e32 v32, v22
	v_mul_f32_e32 v18, v146, v18
	v_pk_mul_f32 v[8:9], v[8:9], v[18:19] op_sel_hi:[1,0]
	v_mov_b32_e32 v33, v24
	v_mov_b32_e32 v24, v23
	v_pk_mul_f32 v[30:31], v[14:15], v[18:19] op_sel_hi:[1,0]
	v_pk_mul_f32 v[14:15], v[12:13], v[18:19] op_sel_hi:[1,0]
	v_pk_mul_f32 v[10:11], v[10:11], v[18:19] op_sel_hi:[1,0]
	v_pk_mul_f32 v[12:13], v[24:25], v[8:9]
	v_pk_mul_f32 v[8:9], v[32:33], v[8:9]
	v_mov_b32_e32 v22, v26
	v_mov_b32_e32 v23, v28
	v_mov_b32_e32 v28, v27
	v_pk_fma_f32 v[12:13], v[32:33], v[14:15], v[12:13] neg_lo:[0,0,1] neg_hi:[0,0,1]
	v_pk_fma_f32 v[8:9], v[24:25], v[14:15], v[8:9]
	v_pk_mul_f32 v[14:15], v[28:29], v[10:11]
	v_pk_mul_f32 v[10:11], v[22:23], v[10:11]
	v_pk_fma_f32 v[14:15], v[22:23], v[30:31], v[14:15] neg_lo:[0,0,1] neg_hi:[0,0,1]
	v_pk_fma_f32 v[10:11], v[28:29], v[30:31], v[10:11]
	global_load_dwordx4 v[22:25], v[20:21], off offset:32
	global_load_dwordx4 v[26:29], v[20:21], off offset:48
	v_pk_mul_f32 v[20:21], v[6:7], v[18:19] op_sel_hi:[1,0]
	v_pk_mul_f32 v[6:7], v[4:5], v[18:19] op_sel_hi:[1,0]
	v_pk_mul_f32 v[2:3], v[2:3], v[18:19] op_sel_hi:[1,0]
	v_pk_mul_f32 v[0:1], v[0:1], v[18:19] op_sel_hi:[1,0]
	v_cvt_pk_bf16_f32 v12, v12, v13
	v_cvt_pk_bf16_f32 v13, v14, v15
	s_waitcnt vmcnt(0) lgkmcnt(0)
	v_mov_b32_e32 v19, v24
	v_mov_b32_e32 v24, v23
	v_mov_b32_e32 v18, v22
	v_pk_mul_f32 v[4:5], v[24:25], v[0:1]
	v_pk_mul_f32 v[0:1], v[18:19], v[0:1]
	v_pk_fma_f32 v[4:5], v[18:19], v[6:7], v[4:5] neg_lo:[0,0,1] neg_hi:[0,0,1]
	v_mov_b32_e32 v18, v26
	v_mov_b32_e32 v19, v28
	v_mov_b32_e32 v28, v27
	v_pk_fma_f32 v[0:1], v[24:25], v[6:7], v[0:1]
	v_pk_mul_f32 v[6:7], v[28:29], v[2:3]
	v_pk_mul_f32 v[2:3], v[18:19], v[2:3]
	v_pk_fma_f32 v[6:7], v[18:19], v[20:21], v[6:7] neg_lo:[0,0,1] neg_hi:[0,0,1]
	v_pk_fma_f32 v[2:3], v[28:29], v[20:21], v[2:3]
	v_cvt_pk_bf16_f32 v14, v4, v5
	v_cvt_pk_bf16_f32 v15, v6, v7
	v_cvt_pk_bf16_f32 v4, v8, v9
	v_cvt_pk_bf16_f32 v5, v10, v11
	v_cvt_pk_bf16_f32 v6, v0, v1
	v_cvt_pk_bf16_f32 v7, v2, v3
	global_store_dwordx4 v[16:17], v[12:15], off
	global_store_dwordx4 v[16:17], v[4:7], off offset:128
	s_andn2_b64 vcc, exec, s[38:39]
	s_mov_b64 s[0:1], -1
	s_cbranch_vccnz .LBB0_395

.LBB0_474:
	s_add_u32 s12, s10, 0xfffc0080
	s_addc_u32 s13, s11, -1
	s_add_i32 s22, 0, 0x10000
	s_cmp_eq_u32 s21, 12
	s_cselect_b32 s15, s20, s13
	s_cselect_b32 s14, s37, s12
	s_cselect_b32 s13, s41, s93
	s_cselect_b32 s12, s91, s92
	s_add_i32 s48, 0, 0x14000
	v_add_u32_e32 v154, s22, v147
	v_add_u32_e32 v158, s48, v147
	ds_read_b128 v[138:141], v154
	ds_read_b128 v[142:145], v154 offset:1024
	ds_read_b128 v[150:153], v154 offset:2048
	ds_read_b128 v[154:157], v154 offset:3072
	ds_read_b128 v[174:177], v158
	ds_read_b128 v[178:181], v158 offset:1024
	ds_read_b128 v[182:185], v158 offset:2048
	ds_read_b128 v[186:189], v158 offset:3072
	v_lshl_add_u64 v[158:159], s[10:11], 0, v[136:137]
	s_add_i32 m0, s30, 0xc000
	ds_read_b128 v[190:193], v149
	ds_read_b128 v[194:197], v149 offset:1024
	ds_read_b128 v[198:201], v149 offset:2048
	ds_read_b128 v[202:205], v149 offset:3072
	ds_read_b128 v[206:209], v149 offset:4096
	ds_read_b128 v[210:213], v149 offset:5120
	ds_read_b128 v[214:217], v149 offset:6144
	ds_read_b128 v[238:241], v149 offset:7168
	global_load_lds_dwordx4 v[158:159], off
	v_lshl_add_u64 v[158:159], s[10:11], 0, v[134:135]
	s_add_i32 m0, s30, 0xe000
	s_nop 0
	global_load_lds_dwordx4 v[158:159], off
	s_waitcnt vmcnt(8)
	s_waitcnt lgkmcnt(0)
	s_barrier
	s_setprio 1
	s_waitcnt lgkmcnt(0)
	v_mfma_f32_16x16x32_bf16 v[124:127], v[138:141], v[190:193], v[124:127]
	v_mfma_f32_16x16x32_bf16 v[116:119], v[150:153], v[190:193], v[116:119]
	v_mfma_f32_16x16x32_bf16 v[108:111], v[138:141], v[198:201], v[108:111]
	v_mfma_f32_16x16x32_bf16 v[100:103], v[150:153], v[198:201], v[100:103]
	v_mfma_f32_16x16x32_bf16 v[92:95], v[138:141], v[206:209], v[92:95]
	v_mfma_f32_16x16x32_bf16 v[84:87], v[150:153], v[206:209], v[84:87]
	v_mfma_f32_16x16x32_bf16 v[76:79], v[138:141], v[214:217], v[76:79]
	v_mfma_f32_16x16x32_bf16 v[64:67], v[150:153], v[214:217], v[64:67]
	v_mfma_f32_16x16x32_bf16 v[124:127], v[142:145], v[194:197], v[124:127]
	v_mfma_f32_16x16x32_bf16 v[116:119], v[154:157], v[194:197], v[116:119]
	v_mfma_f32_16x16x32_bf16 v[108:111], v[142:145], v[202:205], v[108:111]
	v_mfma_f32_16x16x32_bf16 v[100:103], v[154:157], v[202:205], v[100:103]
	v_mfma_f32_16x16x32_bf16 v[92:95], v[142:145], v[210:213], v[92:95]
	v_mfma_f32_16x16x32_bf16 v[84:87], v[154:157], v[210:213], v[84:87]
	v_mfma_f32_16x16x32_bf16 v[76:79], v[142:145], v[238:241], v[76:79]
	v_mfma_f32_16x16x32_bf16 v[64:67], v[154:157], v[238:241], v[64:67]
	s_setprio 0
	s_setprio 1
	v_mfma_f32_16x16x32_bf16 v[120:123], v[174:177], v[190:193], v[120:123]
	v_mfma_f32_16x16x32_bf16 v[112:115], v[182:185], v[190:193], v[112:115]
	v_mfma_f32_16x16x32_bf16 v[104:107], v[174:177], v[198:201], v[104:107]
	v_mfma_f32_16x16x32_bf16 v[96:99], v[182:185], v[198:201], v[96:99]
	v_mfma_f32_16x16x32_bf16 v[88:91], v[174:177], v[206:209], v[88:91]
	v_mfma_f32_16x16x32_bf16 v[80:83], v[182:185], v[206:209], v[80:83]
	v_mfma_f32_16x16x32_bf16 v[72:75], v[174:177], v[214:217], v[72:75]
	v_mfma_f32_16x16x32_bf16 v[68:71], v[182:185], v[214:217], v[68:71]
	v_mfma_f32_16x16x32_bf16 v[120:123], v[178:181], v[194:197], v[120:123]
	v_mfma_f32_16x16x32_bf16 v[112:115], v[186:189], v[194:197], v[112:115]
	v_mfma_f32_16x16x32_bf16 v[104:107], v[178:181], v[202:205], v[104:107]
	v_mfma_f32_16x16x32_bf16 v[96:99], v[186:189], v[202:205], v[96:99]
	v_mfma_f32_16x16x32_bf16 v[88:91], v[178:181], v[210:213], v[88:91]
	v_mfma_f32_16x16x32_bf16 v[80:83], v[186:189], v[210:213], v[80:83]
	v_mfma_f32_16x16x32_bf16 v[72:75], v[178:181], v[238:241], v[72:75]
	v_mfma_f32_16x16x32_bf16 v[68:71], v[186:189], v[238:241], v[68:71]
	s_setprio 0
	s_barrier
	s_add_i32 s22, s22, s28
	v_lshl_add_u64 v[158:159], s[12:13], 0, v[160:161]
	s_mov_b32 m0, s22
	ds_read_b128 v[190:193], v149 offset:16384
	ds_read_b128 v[194:197], v149 offset:17408
	ds_read_b128 v[198:201], v149 offset:18432
	ds_read_b128 v[202:205], v149 offset:19456
	ds_read_b128 v[206:209], v149 offset:20480
	ds_read_b128 v[210:213], v149 offset:21504
	ds_read_b128 v[214:217], v149 offset:22528
	ds_read_b128 v[238:241], v149 offset:23552
	global_load_lds_dwordx4 v[158:159], off
	s_add_i32 m0, s22, 0x2000
	s_add_u32 s96, s12, 0x40000
	v_lshl_add_u64 v[162:163], s[12:13], 0, v[128:129]
	s_addc_u32 s97, s13, 0
	s_add_i32 s22, s48, s28
	global_load_lds_dwordx4 v[162:163], off
	v_lshl_add_u64 v[164:165], s[96:97], 0, v[160:161]
	s_mov_b32 m0, s22
	v_lshl_add_u64 v[166:167], s[14:15], 0, v[130:131]
	global_load_lds_dwordx4 v[164:165], off
	v_lshl_add_u64 v[164:165], s[96:97], 0, v[128:129]
	s_add_i32 m0, s22, 0x2000
	s_nop 0
	global_load_lds_dwordx4 v[164:165], off
	v_lshl_add_u64 v[164:165], s[14:15], 0, v[132:133]
	s_mov_b32 m0, s30
	s_nop 0
	global_load_lds_dwordx4 v[164:165], off
	s_mov_b32 m0, s31
	s_nop 0
	global_load_lds_dwordx4 v[166:167], off
	s_waitcnt vmcnt(8)
	s_waitcnt lgkmcnt(0)
	s_barrier
	s_setprio 1
	s_waitcnt lgkmcnt(0)
	v_mfma_f32_16x16x32_bf16 v[60:63], v[138:141], v[190:193], v[60:63]
	v_mfma_f32_16x16x32_bf16 v[48:51], v[150:153], v[190:193], v[48:51]
	v_mfma_f32_16x16x32_bf16 v[44:47], v[138:141], v[198:201], v[44:47]
	v_mfma_f32_16x16x32_bf16 v[32:35], v[150:153], v[198:201], v[32:35]
	v_mfma_f32_16x16x32_bf16 v[28:31], v[138:141], v[206:209], v[28:31]
	v_mfma_f32_16x16x32_bf16 v[16:19], v[150:153], v[206:209], v[16:19]
	v_mfma_f32_16x16x32_bf16 v[12:15], v[138:141], v[214:217], v[12:15]
	v_mfma_f32_16x16x32_bf16 v[0:3], v[150:153], v[214:217], v[0:3]
	v_mfma_f32_16x16x32_bf16 v[60:63], v[142:145], v[194:197], v[60:63]
	v_mfma_f32_16x16x32_bf16 v[48:51], v[154:157], v[194:197], v[48:51]
	v_mfma_f32_16x16x32_bf16 v[44:47], v[142:145], v[202:205], v[44:47]
	v_mfma_f32_16x16x32_bf16 v[32:35], v[154:157], v[202:205], v[32:35]
	v_mfma_f32_16x16x32_bf16 v[28:31], v[142:145], v[210:213], v[28:31]
	v_mfma_f32_16x16x32_bf16 v[16:19], v[154:157], v[210:213], v[16:19]
	v_mfma_f32_16x16x32_bf16 v[12:15], v[142:145], v[238:241], v[12:15]
	v_mfma_f32_16x16x32_bf16 v[0:3], v[154:157], v[238:241], v[0:3]
	s_setprio 0
	s_setprio 1
	v_mfma_f32_16x16x32_bf16 v[56:59], v[174:177], v[190:193], v[56:59]
	v_mfma_f32_16x16x32_bf16 v[52:55], v[182:185], v[190:193], v[52:55]
	v_mfma_f32_16x16x32_bf16 v[40:43], v[174:177], v[198:201], v[40:43]
	v_mfma_f32_16x16x32_bf16 v[36:39], v[182:185], v[198:201], v[36:39]
	v_mfma_f32_16x16x32_bf16 v[24:27], v[174:177], v[206:209], v[24:27]
	v_mfma_f32_16x16x32_bf16 v[20:23], v[182:185], v[206:209], v[20:23]
	v_mfma_f32_16x16x32_bf16 v[8:11], v[174:177], v[214:217], v[8:11]
	v_mfma_f32_16x16x32_bf16 v[4:7], v[182:185], v[214:217], v[4:7]
	v_mfma_f32_16x16x32_bf16 v[56:59], v[178:181], v[194:197], v[56:59]
	v_mfma_f32_16x16x32_bf16 v[52:55], v[186:189], v[194:197], v[52:55]
	v_mfma_f32_16x16x32_bf16 v[40:43], v[178:181], v[202:205], v[40:43]
	v_mfma_f32_16x16x32_bf16 v[36:39], v[186:189], v[202:205], v[36:39]
	v_mfma_f32_16x16x32_bf16 v[24:27], v[178:181], v[210:213], v[24:27]
	v_mfma_f32_16x16x32_bf16 v[20:23], v[186:189], v[210:213], v[20:23]
	v_mfma_f32_16x16x32_bf16 v[8:11], v[178:181], v[238:241], v[8:11]
	v_mfma_f32_16x16x32_bf16 v[4:7], v[186:189], v[238:241], v[4:7]
	s_setprio 0
	s_barrier
	s_add_i32 s22, 0, 0x18000
	s_add_i32 s48, 0, 0x1c000
	v_add_u32_e32 v154, s22, v147
	v_add_u32_e32 v168, s48, v147
	ds_read_b128 v[138:141], v154
	ds_read_b128 v[142:145], v154 offset:1024
	ds_read_b128 v[150:153], v154 offset:2048
	ds_read_b128 v[154:157], v154 offset:3072
	ds_read_b128 v[174:177], v168
	ds_read_b128 v[178:181], v168 offset:1024
	ds_read_b128 v[182:185], v168 offset:2048
	ds_read_b128 v[186:189], v168 offset:3072
	s_add_u32 s14, s14, 0x40000
	s_addc_u32 s15, s15, 0
	s_mov_b32 m0, s33
	v_lshl_add_u64 v[168:169], s[14:15], 0, v[132:133]
	ds_read_b128 v[190:193], v149 offset:32768
	ds_read_b128 v[194:197], v149 offset:33792
	ds_read_b128 v[198:201], v149 offset:34816
	ds_read_b128 v[202:205], v149 offset:35840
	ds_read_b128 v[206:209], v149 offset:36864
	ds_read_b128 v[210:213], v149 offset:37888
	ds_read_b128 v[214:217], v149 offset:38912
	ds_read_b128 v[238:241], v149 offset:39936
	global_load_lds_dwordx4 v[168:169], off
	v_lshl_add_u64 v[168:169], s[14:15], 0, v[130:131]
	s_mov_b32 m0, s34
	s_nop 0
	global_load_lds_dwordx4 v[168:169], off
	s_waitcnt vmcnt(8)
	s_waitcnt lgkmcnt(0)
	s_barrier
	s_setprio 1
	s_waitcnt lgkmcnt(0)
	v_mfma_f32_16x16x32_bf16 v[124:127], v[138:141], v[190:193], v[124:127]
	v_mfma_f32_16x16x32_bf16 v[116:119], v[150:153], v[190:193], v[116:119]
	v_mfma_f32_16x16x32_bf16 v[108:111], v[138:141], v[198:201], v[108:111]
	v_mfma_f32_16x16x32_bf16 v[100:103], v[150:153], v[198:201], v[100:103]
	v_mfma_f32_16x16x32_bf16 v[92:95], v[138:141], v[206:209], v[92:95]
	v_mfma_f32_16x16x32_bf16 v[84:87], v[150:153], v[206:209], v[84:87]
	v_mfma_f32_16x16x32_bf16 v[76:79], v[138:141], v[214:217], v[76:79]
	v_mfma_f32_16x16x32_bf16 v[64:67], v[150:153], v[214:217], v[64:67]
	v_mfma_f32_16x16x32_bf16 v[124:127], v[142:145], v[194:197], v[124:127]
	v_mfma_f32_16x16x32_bf16 v[116:119], v[154:157], v[194:197], v[116:119]
	v_mfma_f32_16x16x32_bf16 v[108:111], v[142:145], v[202:205], v[108:111]
	v_mfma_f32_16x16x32_bf16 v[100:103], v[154:157], v[202:205], v[100:103]
	v_mfma_f32_16x16x32_bf16 v[92:95], v[142:145], v[210:213], v[92:95]
	v_mfma_f32_16x16x32_bf16 v[84:87], v[154:157], v[210:213], v[84:87]
	v_mfma_f32_16x16x32_bf16 v[76:79], v[142:145], v[238:241], v[76:79]
	v_mfma_f32_16x16x32_bf16 v[64:67], v[154:157], v[238:241], v[64:67]
	s_setprio 0
	s_setprio 1
	v_mfma_f32_16x16x32_bf16 v[120:123], v[174:177], v[190:193], v[120:123]
	v_mfma_f32_16x16x32_bf16 v[112:115], v[182:185], v[190:193], v[112:115]
	v_mfma_f32_16x16x32_bf16 v[104:107], v[174:177], v[198:201], v[104:107]
	v_mfma_f32_16x16x32_bf16 v[96:99], v[182:185], v[198:201], v[96:99]
	v_mfma_f32_16x16x32_bf16 v[88:91], v[174:177], v[206:209], v[88:91]
	v_mfma_f32_16x16x32_bf16 v[80:83], v[182:185], v[206:209], v[80:83]
	v_mfma_f32_16x16x32_bf16 v[72:75], v[174:177], v[214:217], v[72:75]
	v_mfma_f32_16x16x32_bf16 v[68:71], v[182:185], v[214:217], v[68:71]
	v_mfma_f32_16x16x32_bf16 v[120:123], v[178:181], v[194:197], v[120:123]
	v_mfma_f32_16x16x32_bf16 v[112:115], v[186:189], v[194:197], v[112:115]
	v_mfma_f32_16x16x32_bf16 v[104:107], v[178:181], v[202:205], v[104:107]
	v_mfma_f32_16x16x32_bf16 v[96:99], v[186:189], v[202:205], v[96:99]
	v_mfma_f32_16x16x32_bf16 v[88:91], v[178:181], v[210:213], v[88:91]
	v_mfma_f32_16x16x32_bf16 v[80:83], v[186:189], v[210:213], v[80:83]
	v_mfma_f32_16x16x32_bf16 v[72:75], v[178:181], v[238:241], v[72:75]
	v_mfma_f32_16x16x32_bf16 v[68:71], v[186:189], v[238:241], v[68:71]
	s_setprio 0
	s_barrier
	s_add_i32 s14, s22, s28
	v_lshl_add_u64 v[158:159], v[158:159], 0, s[88:89]
	s_mov_b32 m0, s14
	ds_read_b128 v[190:193], v149 offset:49152
	ds_read_b128 v[194:197], v149 offset:50176
	ds_read_b128 v[198:201], v149 offset:51200
	ds_read_b128 v[202:205], v149 offset:52224
	ds_read_b128 v[206:209], v149 offset:53248
	ds_read_b128 v[210:213], v149 offset:54272
	ds_read_b128 v[214:217], v149 offset:55296
	ds_read_b128 v[238:241], v149 offset:56320
	global_load_lds_dwordx4 v[158:159], off
	s_add_i32 m0, s14, 0x2000
	s_add_u32 s12, s12, 0x40080
	v_lshl_add_u64 v[158:159], v[162:163], 0, s[88:89]
	s_addc_u32 s13, s13, 0
	s_add_i32 s14, s48, s28
	global_load_lds_dwordx4 v[158:159], off
	v_lshl_add_u64 v[158:159], s[12:13], 0, v[160:161]
	s_mov_b32 m0, s14
	s_nop 0
	global_load_lds_dwordx4 v[158:159], off
	v_lshl_add_u64 v[158:159], s[12:13], 0, v[128:129]
	s_add_i32 m0, s14, 0x2000
	s_nop 0
	global_load_lds_dwordx4 v[158:159], off
	v_lshl_add_u64 v[158:159], v[164:165], 0, s[88:89]
	s_mov_b32 m0, s35
	s_nop 0
	global_load_lds_dwordx4 v[158:159], off
	v_lshl_add_u64 v[158:159], v[166:167], 0, s[88:89]
	s_mov_b32 m0, s90
	s_nop 0
	global_load_lds_dwordx4 v[158:159], off
	s_waitcnt vmcnt(8)
	s_waitcnt lgkmcnt(0)
	s_barrier
	s_setprio 1
	s_waitcnt lgkmcnt(0)
	v_mfma_f32_16x16x32_bf16 v[60:63], v[138:141], v[190:193], v[60:63]
	v_mfma_f32_16x16x32_bf16 v[48:51], v[150:153], v[190:193], v[48:51]
	v_mfma_f32_16x16x32_bf16 v[44:47], v[138:141], v[198:201], v[44:47]
	v_mfma_f32_16x16x32_bf16 v[32:35], v[150:153], v[198:201], v[32:35]
	v_mfma_f32_16x16x32_bf16 v[28:31], v[138:141], v[206:209], v[28:31]
	v_mfma_f32_16x16x32_bf16 v[16:19], v[150:153], v[206:209], v[16:19]
	v_mfma_f32_16x16x32_bf16 v[12:15], v[138:141], v[214:217], v[12:15]
	v_mfma_f32_16x16x32_bf16 v[0:3], v[150:153], v[214:217], v[0:3]
	v_mfma_f32_16x16x32_bf16 v[60:63], v[142:145], v[194:197], v[60:63]
	v_mfma_f32_16x16x32_bf16 v[48:51], v[154:157], v[194:197], v[48:51]
	v_mfma_f32_16x16x32_bf16 v[44:47], v[142:145], v[202:205], v[44:47]
	v_mfma_f32_16x16x32_bf16 v[32:35], v[154:157], v[202:205], v[32:35]
	v_mfma_f32_16x16x32_bf16 v[28:31], v[142:145], v[210:213], v[28:31]
	v_mfma_f32_16x16x32_bf16 v[16:19], v[154:157], v[210:213], v[16:19]
	v_mfma_f32_16x16x32_bf16 v[12:15], v[142:145], v[238:241], v[12:15]
	v_mfma_f32_16x16x32_bf16 v[0:3], v[154:157], v[238:241], v[0:3]
	s_setprio 0
	s_setprio 1
	v_mfma_f32_16x16x32_bf16 v[56:59], v[174:177], v[190:193], v[56:59]
	v_mfma_f32_16x16x32_bf16 v[52:55], v[182:185], v[190:193], v[52:55]
	v_mfma_f32_16x16x32_bf16 v[40:43], v[174:177], v[198:201], v[40:43]
	v_mfma_f32_16x16x32_bf16 v[36:39], v[182:185], v[198:201], v[36:39]
	v_mfma_f32_16x16x32_bf16 v[24:27], v[174:177], v[206:209], v[24:27]
	v_mfma_f32_16x16x32_bf16 v[20:23], v[182:185], v[206:209], v[20:23]
	v_mfma_f32_16x16x32_bf16 v[8:11], v[174:177], v[214:217], v[8:11]
	v_mfma_f32_16x16x32_bf16 v[4:7], v[182:185], v[214:217], v[4:7]
	v_mfma_f32_16x16x32_bf16 v[56:59], v[178:181], v[194:197], v[56:59]
	v_mfma_f32_16x16x32_bf16 v[52:55], v[186:189], v[194:197], v[52:55]
	v_mfma_f32_16x16x32_bf16 v[40:43], v[178:181], v[202:205], v[40:43]
	v_mfma_f32_16x16x32_bf16 v[36:39], v[186:189], v[202:205], v[36:39]
	v_mfma_f32_16x16x32_bf16 v[24:27], v[178:181], v[210:213], v[24:27]
	v_mfma_f32_16x16x32_bf16 v[20:23], v[186:189], v[210:213], v[20:23]
	v_mfma_f32_16x16x32_bf16 v[8:11], v[178:181], v[238:241], v[8:11]
	v_mfma_f32_16x16x32_bf16 v[4:7], v[186:189], v[238:241], v[4:7]
	s_setprio 0
	s_barrier
	s_add_i32 s21, s21, 2
	s_add_u32 s92, s92, 0x100
	s_addc_u32 s93, s93, 0
	s_add_u32 s10, s10, 0x100
	s_addc_u32 s11, s11, 0
	s_cmp_gt_u32 s21, 13
	s_cbranch_scc0 .LBB0_474
	v_lshl_add_u32 v192, s8, 8, v146
	v_lshlrev_b32_e32 v192, 3, v192
	global_load_dwordx2 v[176:177], v192, s[4:5]
	global_load_dwordx2 v[178:179], v192, s[4:5] offset:128
	global_load_dwordx2 v[180:181], v192, s[4:5] offset:256
	global_load_dwordx2 v[182:183], v192, s[4:5] offset:384
	global_load_dwordx2 v[184:185], v192, s[4:5] offset:1024
	global_load_dwordx2 v[186:187], v192, s[4:5] offset:1152
	global_load_dwordx2 v[188:189], v192, s[4:5] offset:1280
	global_load_dwordx2 v[190:191], v192, s[4:5] offset:1408
	s_and_b64 vcc, exec, s[6:7]
	s_cbranch_vccz .LBB0_477
	s_barrier
